# load segments: s_nop 0 between m0 write and LDS-DMA replaced by one of the segment's own ds_read_b128 (on top of saddr-form DMA)
# speedup vs baseline: 1.0052x; 1.0052x over previous
; #define PG8_STAGE(bufoff, gbase, voff) do { _Pragma("unroll") for (int _i = 0; _i < 2; ++_i) \
;         __builtin_amdgcn_global_load_lds((const unsigned*)((const char*)(gbase) + (voff)[_i]), (PG8_LAS unsigned*)(lds + (bufoff) + ldsw + _i * 8192), 16, 0, 0); } while (0)
; #define PG8_LDA(dst, b, h) do { _Pragma("unroll") for (int m = 0; m < 4; ++m) _Pragma("unroll") for (int k = 0; k < 2; ++k) dst[m][k] = *(const PG8_LAS bf16x8*)(lds + PG8_SA(b, h) + aoff + m * 2048 + k * 1024); } while (0)
; #define PG8_LDB(dst, b, h) do { _Pragma("unroll") for (int n = 0; n < 2; ++n) _Pragma("unroll") for (int k = 0; k < 2; ++k) dst[n][k] = *(const PG8_LAS bf16x8*)(lds + PG8_SB(b, h) + boff + n * 2048 + k * 1024); } while (0)
; #define PG8_MMA(ai, bj, At, Bt) do { __builtin_amdgcn_s_setprio(1); _Pragma("unroll") for (int m = 0; m < 4; ++m) _Pragma("unroll") for (int n = 0; n < 2; ++n) _Pragma("unroll") for (int k = 0; k < 2; ++k) \
;         acc[ai][bj][m][n] = __builtin_amdgcn_mfma_f32_16x16x32_bf16(Bt[n][k], At[m][k], acc[ai][bj][m][n], 0, 0, 0); __builtin_amdgcn_s_setprio(0); } while (0)
; #define PG8_WAIT_V(n) asm volatile("s_waitcnt vmcnt(" #n ")" ::: "memory")
; #define PG8_WAIT_L(n) asm volatile("s_waitcnt lgkmcnt(" #n ")" ::: "memory")
; #define PG8_BAR __builtin_amdgcn_s_barrier()
; #define PG8_SCHED __builtin_amdgcn_sched_barrier(0)
; template <class Epi, class Sched, bool ALIGN_EPI = false, bool SP2 = false>
; __device__ __forceinline__ void gemm_phase(PG8_LAS unsigned char* lds, const Gemm g, const Sched& S, const Epi& E) {
;     ...
;             PG8_WAIT_V(8); PG8_WAIT_L(0); PG8_BAR; PG8_MMA(0, 0, At, B0); PG8_MMA(0, 1, At, B1); PG8_BAR; PG8_SCHED;
;             PG8_LDA(At, 0, 1); PG8_STAGE(PG8_SB(0, 0), b2, voffB); PG8_STAGE(PG8_SB(0, 1), b2 + hstep, voffB); PG8_STAGE(PG8_SA(0, 0), a2, voffA);
;             PG8_WAIT_V(8); PG8_WAIT_L(0); PG8_BAR; PG8_MMA(1, 0, At, B0); PG8_MMA(1, 1, At, B1); PG8_BAR; PG8_SCHED;
;             PG8_LDB(B0, 1, 0); PG8_LDB(B1, 1, 1); PG8_SCHED; PG8_LDA(At, 1, 0); PG8_STAGE(PG8_SA(0, 1), a2 + hstep, voffA);
.Lgr_p1_0:
	s_waitcnt lgkmcnt(0)
	s_barrier
	s_setprio 1
	s_waitcnt lgkmcnt(0)
	v_mfma_f32_16x16x32_bf16 v[116:119], v[152:155], v[184:187], v[116:119]
	v_mfma_f32_16x16x32_bf16 v[112:115], v[160:163], v[184:187], v[112:115]
	v_mfma_f32_16x16x32_bf16 v[108:111], v[152:155], v[192:195], v[108:111]
	v_mfma_f32_16x16x32_bf16 v[100:103], v[160:163], v[192:195], v[100:103]
	v_mfma_f32_16x16x32_bf16 v[92:95], v[152:155], v[200:203], v[92:95]
	v_mfma_f32_16x16x32_bf16 v[84:87], v[160:163], v[200:203], v[84:87]
	v_mfma_f32_16x16x32_bf16 v[76:79], v[152:155], v[210:213], v[76:79]
	v_mfma_f32_16x16x32_bf16 v[68:71], v[160:163], v[210:213], v[68:71]
	v_mfma_f32_16x16x32_bf16 v[116:119], v[156:159], v[188:191], v[116:119]
	v_mfma_f32_16x16x32_bf16 v[112:115], v[164:167], v[188:191], v[112:115]
	v_mfma_f32_16x16x32_bf16 v[108:111], v[156:159], v[196:199], v[108:111]
	v_mfma_f32_16x16x32_bf16 v[100:103], v[164:167], v[196:199], v[100:103]
	v_mfma_f32_16x16x32_bf16 v[92:95], v[156:159], v[206:209], v[92:95]
	v_mfma_f32_16x16x32_bf16 v[84:87], v[164:167], v[206:209], v[84:87]
	v_mfma_f32_16x16x32_bf16 v[76:79], v[156:159], v[214:217], v[76:79]
	v_mfma_f32_16x16x32_bf16 v[68:71], v[164:167], v[214:217], v[68:71]
	s_setprio 0
	s_setprio 1
	v_mfma_f32_16x16x32_bf16 v[124:127], v[168:171], v[184:187], v[124:127]
	v_mfma_f32_16x16x32_bf16 v[120:123], v[176:179], v[184:187], v[120:123]
	v_mfma_f32_16x16x32_bf16 v[104:107], v[168:171], v[192:195], v[104:107]
	v_mfma_f32_16x16x32_bf16 v[96:99], v[176:179], v[192:195], v[96:99]
	v_mfma_f32_16x16x32_bf16 v[88:91], v[168:171], v[200:203], v[88:91]
	v_mfma_f32_16x16x32_bf16 v[80:83], v[176:179], v[200:203], v[80:83]
	v_mfma_f32_16x16x32_bf16 v[72:75], v[168:171], v[210:213], v[72:75]
	v_mfma_f32_16x16x32_bf16 v[64:67], v[176:179], v[210:213], v[64:67]
	v_mfma_f32_16x16x32_bf16 v[124:127], v[172:175], v[188:191], v[124:127]
	v_mfma_f32_16x16x32_bf16 v[120:123], v[180:183], v[188:191], v[120:123]
	v_mfma_f32_16x16x32_bf16 v[104:107], v[172:175], v[196:199], v[104:107]
	v_mfma_f32_16x16x32_bf16 v[96:99], v[180:183], v[196:199], v[96:99]
	v_mfma_f32_16x16x32_bf16 v[88:91], v[172:175], v[206:209], v[88:91]
	v_mfma_f32_16x16x32_bf16 v[80:83], v[180:183], v[206:209], v[80:83]
	v_mfma_f32_16x16x32_bf16 v[72:75], v[172:175], v[214:217], v[72:75]
	v_mfma_f32_16x16x32_bf16 v[64:67], v[180:183], v[214:217], v[64:67]
	s_setprio 0
	s_barrier
	s_add_i32 s52, s43, s0
	s_add_u32 vcc_lo, s24, 0x80
	s_addc_u32 vcc_hi, s25, 0
	s_mov_b32 m0, s52
	ds_read_b128 v[184:187], v149 offset:16384
	ds_read_b128 v[188:191], v149 offset:17408
	ds_read_b128 v[192:195], v149 offset:18432
	ds_read_b128 v[196:199], v149 offset:19456
	global_load_lds_dwordx4 v132, s[24:25]
	s_add_i32 m0, s52, 0x2000
	s_add_u32 s52, s24, 0x80000
	s_addc_u32 s53, s25, 0
	s_add_i32 s54, s44, s0
	global_load_lds_dwordx4 v128, s[24:25]
	s_mov_b32 m0, s54
	ds_read_b128 v[214:217], v149 offset:23552
	global_load_lds_dwordx4 v132, s[52:53]
	s_add_i32 m0, s54, 0x2000
	ds_read_b128 v[210:213], v149 offset:22528
	global_load_lds_dwordx4 v128, s[52:53]
	s_add_u32 s98, s26, 0x80
	s_addc_u32 s99, s27, 0
	s_mov_b32 m0, s29
	ds_read_b128 v[206:209], v149 offset:21504
	global_load_lds_dwordx4 v134, s[26:27]
	s_mov_b32 m0, s30
	ds_read_b128 v[200:203], v149 offset:20480
	global_load_lds_dwordx4 v130, s[26:27]
	s_cmp_lg_u32 s100, 0
	s_cbranch_scc1 .Lgr_p1_1
	s_waitcnt vmcnt(8)
.Lgr_p1_1:
	s_waitcnt lgkmcnt(0)
	s_barrier
	s_setprio 1
	s_waitcnt lgkmcnt(0)
	v_mfma_f32_16x16x32_bf16 v[60:63], v[152:155], v[184:187], v[60:63]
	v_mfma_f32_16x16x32_bf16 v[52:55], v[160:163], v[184:187], v[52:55]
	v_mfma_f32_16x16x32_bf16 v[44:47], v[152:155], v[192:195], v[44:47]
	v_mfma_f32_16x16x32_bf16 v[36:39], v[160:163], v[192:195], v[36:39]
	v_mfma_f32_16x16x32_bf16 v[28:31], v[152:155], v[200:203], v[28:31]
	v_mfma_f32_16x16x32_bf16 v[20:23], v[160:163], v[200:203], v[20:23]
	v_mfma_f32_16x16x32_bf16 v[12:15], v[152:155], v[210:213], v[12:15]
	v_mfma_f32_16x16x32_bf16 v[4:7], v[160:163], v[210:213], v[4:7]
	v_mfma_f32_16x16x32_bf16 v[60:63], v[156:159], v[188:191], v[60:63]
	v_mfma_f32_16x16x32_bf16 v[52:55], v[164:167], v[188:191], v[52:55]
	v_mfma_f32_16x16x32_bf16 v[44:47], v[156:159], v[196:199], v[44:47]
	v_mfma_f32_16x16x32_bf16 v[36:39], v[164:167], v[196:199], v[36:39]
	v_mfma_f32_16x16x32_bf16 v[28:31], v[156:159], v[206:209], v[28:31]
	v_mfma_f32_16x16x32_bf16 v[20:23], v[164:167], v[206:209], v[20:23]
	v_mfma_f32_16x16x32_bf16 v[12:15], v[156:159], v[214:217], v[12:15]
	v_mfma_f32_16x16x32_bf16 v[4:7], v[164:167], v[214:217], v[4:7]
	s_setprio 0
	s_setprio 1
	v_mfma_f32_16x16x32_bf16 v[56:59], v[168:171], v[184:187], v[56:59]
	v_mfma_f32_16x16x32_bf16 v[48:51], v[176:179], v[184:187], v[48:51]
	v_mfma_f32_16x16x32_bf16 v[40:43], v[168:171], v[192:195], v[40:43]
	v_mfma_f32_16x16x32_bf16 v[32:35], v[176:179], v[192:195], v[32:35]
	v_mfma_f32_16x16x32_bf16 v[24:27], v[168:171], v[200:203], v[24:27]
	v_mfma_f32_16x16x32_bf16 v[16:19], v[176:179], v[200:203], v[16:19]
	v_mfma_f32_16x16x32_bf16 v[8:11], v[168:171], v[210:213], v[8:11]
	v_mfma_f32_16x16x32_bf16 v[0:3], v[176:179], v[210:213], v[0:3]
	v_mfma_f32_16x16x32_bf16 v[56:59], v[172:175], v[188:191], v[56:59]
	v_mfma_f32_16x16x32_bf16 v[48:51], v[180:183], v[188:191], v[48:51]
	v_mfma_f32_16x16x32_bf16 v[40:43], v[172:175], v[196:199], v[40:43]
	v_mfma_f32_16x16x32_bf16 v[32:35], v[180:183], v[196:199], v[32:35]
	v_mfma_f32_16x16x32_bf16 v[24:27], v[172:175], v[206:209], v[24:27]
	v_mfma_f32_16x16x32_bf16 v[16:19], v[180:183], v[206:209], v[16:19]
	v_mfma_f32_16x16x32_bf16 v[8:11], v[172:175], v[214:217], v[8:11]
	v_mfma_f32_16x16x32_bf16 v[0:3], v[180:183], v[214:217], v[0:3]
	s_setprio 0
	s_barrier
	s_add_i32 s52, 0, 0x18000
	v_add_u32_e32 v151, s52, v145
	s_add_i32 s53, 0, 0x1c000
	ds_read_b128 v[152:155], v151
	ds_read_b128 v[156:159], v151 offset:1024
	ds_read_b128 v[160:163], v151 offset:2048
	ds_read_b128 v[164:167], v151 offset:3072
	v_add_u32_e32 v151, s53, v145
	ds_read_b128 v[168:171], v151
	ds_read_b128 v[172:175], v151 offset:1024
	ds_read_b128 v[176:179], v151 offset:2048
	ds_read_b128 v[180:183], v151 offset:3072
	s_add_u32 s26, s26, 0x80000
	s_addc_u32 s27, s27, 0
	s_mov_b32 m0, s31
	ds_read_b128 v[184:187], v149 offset:32768
	ds_read_b128 v[188:191], v149 offset:33792
	ds_read_b128 v[192:195], v149 offset:34816
	ds_read_b128 v[196:199], v149 offset:35840
	ds_read_b128 v[200:203], v149 offset:36864
	ds_read_b128 v[206:209], v149 offset:37888
	ds_read_b128 v[210:213], v149 offset:38912
	global_load_lds_dwordx4 v134, s[26:27]
	s_mov_b32 m0, s33
	ds_read_b128 v[214:217], v149 offset:39936
	global_load_lds_dwordx4 v130, s[26:27]
	s_cmp_lg_u32 s100, 0
	s_cbranch_scc1 .Lgr_p1_2
	s_waitcnt vmcnt(8)
; #define PG8_STAGE(bufoff, gbase, voff) do { _Pragma("unroll") for (int _i = 0; _i < 2; ++_i) \
;         __builtin_amdgcn_global_load_lds((const unsigned*)((const char*)(gbase) + (voff)[_i]), (PG8_LAS unsigned*)(lds + (bufoff) + ldsw + _i * 8192), 16, 0, 0); } while (0)
; #define PG8_LDA(dst, b, h) do { _Pragma("unroll") for (int m = 0; m < 4; ++m) _Pragma("unroll") for (int k = 0; k < 2; ++k) dst[m][k] = *(const PG8_LAS bf16x8*)(lds + PG8_SA(b, h) + aoff + m * 2048 + k * 1024); } while (0)
; #define PG8_MMA(ai, bj, At, Bt) do { __builtin_amdgcn_s_setprio(1); _Pragma("unroll") for (int m = 0; m < 4; ++m) _Pragma("unroll") for (int n = 0; n < 2; ++n) _Pragma("unroll") for (int k = 0; k < 2; ++k) \
;         acc[ai][bj][m][n] = __builtin_amdgcn_mfma_f32_16x16x32_bf16(Bt[n][k], At[m][k], acc[ai][bj][m][n], 0, 0, 0); __builtin_amdgcn_s_setprio(0); } while (0)
; #define PG8_WAIT_V(n) asm volatile("s_waitcnt vmcnt(" #n ")" ::: "memory")
; #define PG8_WAIT_L(n) asm volatile("s_waitcnt lgkmcnt(" #n ")" ::: "memory")
; #define PG8_BAR __builtin_amdgcn_s_barrier()
; #define PG8_SCHED __builtin_amdgcn_sched_barrier(0)
; template <class Epi, class Sched, bool ALIGN_EPI = false, bool SP2 = false>
; __device__ __forceinline__ void gemm_phase(PG8_LAS unsigned char* lds, const Gemm g, const Sched& S, const Epi& E) {
;     ...
;             PG8_WAIT_V(8); PG8_WAIT_L(0); PG8_BAR; PG8_MMA(0, 0, At, B0); PG8_MMA(0, 1, At, B1); PG8_BAR; PG8_SCHED;
;             PG8_LDA(At, 1, 1); PG8_STAGE(PG8_SB(1, 0), b3, voffB); PG8_STAGE(PG8_SB(1, 1), b3 + hstep, voffB); PG8_STAGE(PG8_SA(1, 0), a3, voffA);
;             PG8_WAIT_V(8); PG8_WAIT_L(0); PG8_BAR; PG8_MMA(1, 0, At, B0); PG8_MMA(1, 1, At, B1); PG8_BAR; PG8_SCHED;
.Lgr_p1_2:
	s_waitcnt lgkmcnt(0)
	s_barrier
	s_setprio 1
	s_waitcnt lgkmcnt(0)
	v_mfma_f32_16x16x32_bf16 v[116:119], v[152:155], v[184:187], v[116:119]
	v_mfma_f32_16x16x32_bf16 v[112:115], v[160:163], v[184:187], v[112:115]
	v_mfma_f32_16x16x32_bf16 v[108:111], v[152:155], v[192:195], v[108:111]
	v_mfma_f32_16x16x32_bf16 v[100:103], v[160:163], v[192:195], v[100:103]
	v_mfma_f32_16x16x32_bf16 v[92:95], v[152:155], v[200:203], v[92:95]
	v_mfma_f32_16x16x32_bf16 v[84:87], v[160:163], v[200:203], v[84:87]
	v_mfma_f32_16x16x32_bf16 v[76:79], v[152:155], v[210:213], v[76:79]
	v_mfma_f32_16x16x32_bf16 v[68:71], v[160:163], v[210:213], v[68:71]
	v_mfma_f32_16x16x32_bf16 v[116:119], v[156:159], v[188:191], v[116:119]
	v_mfma_f32_16x16x32_bf16 v[112:115], v[164:167], v[188:191], v[112:115]
	v_mfma_f32_16x16x32_bf16 v[108:111], v[156:159], v[196:199], v[108:111]
	v_mfma_f32_16x16x32_bf16 v[100:103], v[164:167], v[196:199], v[100:103]
	v_mfma_f32_16x16x32_bf16 v[92:95], v[156:159], v[206:209], v[92:95]
	v_mfma_f32_16x16x32_bf16 v[84:87], v[164:167], v[206:209], v[84:87]
	v_mfma_f32_16x16x32_bf16 v[76:79], v[156:159], v[214:217], v[76:79]
	v_mfma_f32_16x16x32_bf16 v[68:71], v[164:167], v[214:217], v[68:71]
	s_setprio 0
	s_setprio 1
	v_mfma_f32_16x16x32_bf16 v[124:127], v[168:171], v[184:187], v[124:127]
	v_mfma_f32_16x16x32_bf16 v[120:123], v[176:179], v[184:187], v[120:123]
	v_mfma_f32_16x16x32_bf16 v[104:107], v[168:171], v[192:195], v[104:107]
	v_mfma_f32_16x16x32_bf16 v[96:99], v[176:179], v[192:195], v[96:99]
	v_mfma_f32_16x16x32_bf16 v[88:91], v[168:171], v[200:203], v[88:91]
	v_mfma_f32_16x16x32_bf16 v[80:83], v[176:179], v[200:203], v[80:83]
	v_mfma_f32_16x16x32_bf16 v[72:75], v[168:171], v[210:213], v[72:75]
	v_mfma_f32_16x16x32_bf16 v[64:67], v[176:179], v[210:213], v[64:67]
	v_mfma_f32_16x16x32_bf16 v[124:127], v[172:175], v[188:191], v[124:127]
	v_mfma_f32_16x16x32_bf16 v[120:123], v[180:183], v[188:191], v[120:123]
	v_mfma_f32_16x16x32_bf16 v[104:107], v[172:175], v[196:199], v[104:107]
	v_mfma_f32_16x16x32_bf16 v[96:99], v[180:183], v[196:199], v[96:99]
	v_mfma_f32_16x16x32_bf16 v[88:91], v[172:175], v[206:209], v[88:91]
	v_mfma_f32_16x16x32_bf16 v[80:83], v[180:183], v[206:209], v[80:83]
	v_mfma_f32_16x16x32_bf16 v[72:75], v[172:175], v[214:217], v[72:75]
	v_mfma_f32_16x16x32_bf16 v[64:67], v[180:183], v[214:217], v[64:67]
	s_setprio 0
	s_barrier
	s_add_i32 s26, s52, s0
	s_mov_b32 m0, s26
	ds_read_b128 v[184:187], v149 offset:49152
	ds_read_b128 v[188:191], v149 offset:50176
	ds_read_b128 v[192:195], v149 offset:51200
	ds_read_b128 v[196:199], v149 offset:52224
	global_load_lds_dwordx4 v132, vcc
	s_add_i32 m0, s26, 0x2000
	s_add_u32 s24, s24, 0x80080
	s_addc_u32 s25, s25, 0
	s_add_i32 s26, s53, s0
	global_load_lds_dwordx4 v128, vcc
	s_mov_b32 m0, s26
	ds_read_b128 v[214:217], v149 offset:56320
	global_load_lds_dwordx4 v132, s[24:25]
	s_add_i32 m0, s26, 0x2000
	ds_read_b128 v[210:213], v149 offset:55296
	global_load_lds_dwordx4 v128, s[24:25]
	s_mov_b32 m0, s35
	ds_read_b128 v[206:209], v149 offset:54272
	global_load_lds_dwordx4 v134, s[98:99]
	s_mov_b32 m0, s40
	ds_read_b128 v[200:203], v149 offset:53248
	global_load_lds_dwordx4 v130, s[98:99]
	s_waitcnt vmcnt(8)
	s_waitcnt lgkmcnt(0)
	s_barrier
	s_setprio 1
	s_waitcnt lgkmcnt(0)
	v_mfma_f32_16x16x32_bf16 v[60:63], v[152:155], v[184:187], v[60:63]
	v_mfma_f32_16x16x32_bf16 v[52:55], v[160:163], v[184:187], v[52:55]
	v_mfma_f32_16x16x32_bf16 v[44:47], v[152:155], v[192:195], v[44:47]
	v_mfma_f32_16x16x32_bf16 v[36:39], v[160:163], v[192:195], v[36:39]
	v_mfma_f32_16x16x32_bf16 v[28:31], v[152:155], v[200:203], v[28:31]
	v_mfma_f32_16x16x32_bf16 v[20:23], v[160:163], v[200:203], v[20:23]
	v_mfma_f32_16x16x32_bf16 v[12:15], v[152:155], v[210:213], v[12:15]
	v_mfma_f32_16x16x32_bf16 v[4:7], v[160:163], v[210:213], v[4:7]
	v_mfma_f32_16x16x32_bf16 v[60:63], v[156:159], v[188:191], v[60:63]
	v_mfma_f32_16x16x32_bf16 v[52:55], v[164:167], v[188:191], v[52:55]
	v_mfma_f32_16x16x32_bf16 v[44:47], v[156:159], v[196:199], v[44:47]
	v_mfma_f32_16x16x32_bf16 v[36:39], v[164:167], v[196:199], v[36:39]
	v_mfma_f32_16x16x32_bf16 v[28:31], v[156:159], v[206:209], v[28:31]
	v_mfma_f32_16x16x32_bf16 v[20:23], v[164:167], v[206:209], v[20:23]
	v_mfma_f32_16x16x32_bf16 v[12:15], v[156:159], v[214:217], v[12:15]
	v_mfma_f32_16x16x32_bf16 v[4:7], v[164:167], v[214:217], v[4:7]
	s_setprio 0
	s_setprio 1
	v_mfma_f32_16x16x32_bf16 v[56:59], v[168:171], v[184:187], v[56:59]
	v_mfma_f32_16x16x32_bf16 v[48:51], v[176:179], v[184:187], v[48:51]
	v_mfma_f32_16x16x32_bf16 v[40:43], v[168:171], v[192:195], v[40:43]
	v_mfma_f32_16x16x32_bf16 v[32:35], v[176:179], v[192:195], v[32:35]
	v_mfma_f32_16x16x32_bf16 v[24:27], v[168:171], v[200:203], v[24:27]
	v_mfma_f32_16x16x32_bf16 v[16:19], v[176:179], v[200:203], v[16:19]
	v_mfma_f32_16x16x32_bf16 v[8:11], v[168:171], v[210:213], v[8:11]
	v_mfma_f32_16x16x32_bf16 v[0:3], v[176:179], v[210:213], v[0:3]
	v_mfma_f32_16x16x32_bf16 v[56:59], v[172:175], v[188:191], v[56:59]
	v_mfma_f32_16x16x32_bf16 v[48:51], v[180:183], v[188:191], v[48:51]
	v_mfma_f32_16x16x32_bf16 v[40:43], v[172:175], v[196:199], v[40:43]
	v_mfma_f32_16x16x32_bf16 v[32:35], v[180:183], v[196:199], v[32:35]
	v_mfma_f32_16x16x32_bf16 v[24:27], v[172:175], v[206:209], v[24:27]
	v_mfma_f32_16x16x32_bf16 v[16:19], v[180:183], v[206:209], v[16:19]
	v_mfma_f32_16x16x32_bf16 v[8:11], v[172:175], v[214:217], v[8:11]
	v_mfma_f32_16x16x32_bf16 v[0:3], v[180:183], v[214:217], v[0:3]
	s_setprio 0
	s_barrier
	s_mov_b32 s100, 0
	s_add_i32 s51, s51, 2
	s_add_u32 s22, s22, 0x100
	s_addc_u32 s23, s23, 0
	s_add_u32 s49, s49, 0x100
	s_addc_u32 s50, s50, 0
	s_cmp_gt_u32 s51, 29
	s_cbranch_scc0 .LBB0_204
	s_and_b64 vcc, exec, s[12:13]
	s_cbranch_vccz .LBB0_207
	s_barrier

; #define PG8_STAGE(bufoff, gbase, voff) do { _Pragma("unroll") for (int _i = 0; _i < 2; ++_i) \
;         __builtin_amdgcn_global_load_lds((const unsigned*)((const char*)(gbase) + (voff)[_i]), (PG8_LAS unsigned*)(lds + (bufoff) + ldsw + _i * 8192), 16, 0, 0); } while (0)
; #define PG8_LDA(dst, b, h) do { _Pragma("unroll") for (int m = 0; m < 4; ++m) _Pragma("unroll") for (int k = 0; k < 2; ++k) dst[m][k] = *(const PG8_LAS bf16x8*)(lds + PG8_SA(b, h) + aoff + m * 2048 + k * 1024); } while (0)
; #define PG8_LDB(dst, b, h) do { _Pragma("unroll") for (int n = 0; n < 2; ++n) _Pragma("unroll") for (int k = 0; k < 2; ++k) dst[n][k] = *(const PG8_LAS bf16x8*)(lds + PG8_SB(b, h) + boff + n * 2048 + k * 1024); } while (0)
; #define PG8_MMA(ai, bj, At, Bt) do { __builtin_amdgcn_s_setprio(1); _Pragma("unroll") for (int m = 0; m < 4; ++m) _Pragma("unroll") for (int n = 0; n < 2; ++n) _Pragma("unroll") for (int k = 0; k < 2; ++k) \
;         acc[ai][bj][m][n] = __builtin_amdgcn_mfma_f32_16x16x32_bf16(Bt[n][k], At[m][k], acc[ai][bj][m][n], 0, 0, 0); __builtin_amdgcn_s_setprio(0); } while (0)
; #define PG8_WAIT_V(n) asm volatile("s_waitcnt vmcnt(" #n ")" ::: "memory")
; #define PG8_WAIT_L(n) asm volatile("s_waitcnt lgkmcnt(" #n ")" ::: "memory")
; template <class Epi, class Sched, bool ALIGN_EPI = false, bool SP2 = false>
; __device__ __forceinline__ void gemm_phase(PG8_LAS unsigned char* lds, const Gemm g, const Sched& S, const Epi& E) {
;     ...
;             const bool last = (t == nt - 2);
;             const char* a1 = cA + (size_t)(t + 1) * kstep;
;             const char* a2 = last ? nA : cA + (size_t)(t + 2) * kstep; const char* b2 = last ? nB : cB + (size_t)(t + 2) * kstep;
;             const char* a3 = a2 + kstep; const char* b3 = b2 + kstep;
;             if (last && has_next) S.a_ready(nxt);
;             if constexpr (SP2) {
;             PG8_LDB(B0, 0, 0); PG8_LDB(B1, 0, 1); PG8_SCHED; PG8_LDA(At, 0, 0); PG8_STAGE(PG8_SA(1, 1), a1 + hstep, voffA);
;             PG8_WAIT_V(8); PG8_WAIT_L(0); PG8_BAR; PG8_MMA(0, 0, At, B0); PG8_MMA(0, 1, At, B1); PG8_BAR; PG8_SCHED;
;             PG8_LDA(At, 0, 1); PG8_STAGE(PG8_SB(0, 0), b2, voffB); PG8_STAGE(PG8_SB(0, 1), b2 + hstep, voffB); PG8_STAGE(PG8_SA(0, 0), a2, voffA);
;             PG8_WAIT_V(8); PG8_WAIT_L(0); PG8_BAR; PG8_MMA(1, 0, At, B0); PG8_MMA(1, 1, At, B1); PG8_BAR; PG8_SCHED;
.LBB0_285:
	ds_read_b128 v[128:131], v208
	ds_read_b128 v[132:135], v208 offset:1024
	ds_read_b128 v[136:139], v208 offset:2048
	ds_read_b128 v[140:143], v208 offset:3072
	ds_read_b128 v[144:147], v209
	ds_read_b128 v[148:151], v209 offset:1024
	ds_read_b128 v[152:155], v209 offset:2048
	ds_read_b128 v[156:159], v209 offset:3072
	s_add_u32 s22, s20, 0xffea0080
	s_addc_u32 s23, s21, -1
	s_cmpk_eq_i32 s48, 0x54
	s_cselect_b32 s25, s7, s23
	s_cselect_b32 s24, s6, s22
	s_cselect_b32 s23, s19, s47
	s_cselect_b32 s22, s18, s46
	s_add_i32 m0, s1, 0xc000
	ds_read_b128 v[160:163], v210
	ds_read_b128 v[164:167], v210 offset:1024
	ds_read_b128 v[168:171], v210 offset:2048
	ds_read_b128 v[172:175], v210 offset:3072
	ds_read_b128 v[192:195], v210 offset:4096
	ds_read_b128 v[196:199], v210 offset:5120
	ds_read_b128 v[200:203], v210 offset:6144
	global_load_lds_dwordx4 v184, s[20:21]
	s_add_i32 m0, s1, 0xe000
	ds_read_b128 v[212:215], v210 offset:7168
	global_load_lds_dwordx4 v186, s[20:21]
	s_waitcnt vmcnt(8)
	s_waitcnt lgkmcnt(0)
	s_barrier
	s_setprio 1
	s_waitcnt lgkmcnt(0)
	v_mfma_f32_16x16x32_bf16 v[124:127], v[128:131], v[160:163], v[124:127]
	v_mfma_f32_16x16x32_bf16 v[120:123], v[136:139], v[160:163], v[120:123]
	v_mfma_f32_16x16x32_bf16 v[108:111], v[128:131], v[168:171], v[108:111]
	v_mfma_f32_16x16x32_bf16 v[104:107], v[136:139], v[168:171], v[104:107]
	v_mfma_f32_16x16x32_bf16 v[92:95], v[128:131], v[192:195], v[92:95]
	v_mfma_f32_16x16x32_bf16 v[88:91], v[136:139], v[192:195], v[88:91]
	v_mfma_f32_16x16x32_bf16 v[76:79], v[128:131], v[200:203], v[76:79]
	v_mfma_f32_16x16x32_bf16 v[72:75], v[136:139], v[200:203], v[72:75]
	v_mfma_f32_16x16x32_bf16 v[124:127], v[132:135], v[164:167], v[124:127]
	v_mfma_f32_16x16x32_bf16 v[120:123], v[140:143], v[164:167], v[120:123]
	v_mfma_f32_16x16x32_bf16 v[108:111], v[132:135], v[172:175], v[108:111]
	v_mfma_f32_16x16x32_bf16 v[104:107], v[140:143], v[172:175], v[104:107]
	v_mfma_f32_16x16x32_bf16 v[92:95], v[132:135], v[196:199], v[92:95]
	v_mfma_f32_16x16x32_bf16 v[88:91], v[140:143], v[196:199], v[88:91]
	v_mfma_f32_16x16x32_bf16 v[76:79], v[132:135], v[212:215], v[76:79]
	v_mfma_f32_16x16x32_bf16 v[72:75], v[140:143], v[212:215], v[72:75]
	s_setprio 0
	s_setprio 1
	v_mfma_f32_16x16x32_bf16 v[116:119], v[144:147], v[160:163], v[116:119]
	v_mfma_f32_16x16x32_bf16 v[112:115], v[152:155], v[160:163], v[112:115]
	v_mfma_f32_16x16x32_bf16 v[100:103], v[144:147], v[168:171], v[100:103]
	v_mfma_f32_16x16x32_bf16 v[96:99], v[152:155], v[168:171], v[96:99]
	v_mfma_f32_16x16x32_bf16 v[84:87], v[144:147], v[192:195], v[84:87]
	v_mfma_f32_16x16x32_bf16 v[80:83], v[152:155], v[192:195], v[80:83]
	v_mfma_f32_16x16x32_bf16 v[68:71], v[144:147], v[200:203], v[68:71]
	v_mfma_f32_16x16x32_bf16 v[64:67], v[152:155], v[200:203], v[64:67]
	v_mfma_f32_16x16x32_bf16 v[116:119], v[148:151], v[164:167], v[116:119]
	v_mfma_f32_16x16x32_bf16 v[112:115], v[156:159], v[164:167], v[112:115]
	v_mfma_f32_16x16x32_bf16 v[100:103], v[148:151], v[172:175], v[100:103]
	v_mfma_f32_16x16x32_bf16 v[96:99], v[156:159], v[172:175], v[96:99]
	v_mfma_f32_16x16x32_bf16 v[84:87], v[148:151], v[196:199], v[84:87]
	v_mfma_f32_16x16x32_bf16 v[80:83], v[156:159], v[196:199], v[80:83]
	v_mfma_f32_16x16x32_bf16 v[68:71], v[148:151], v[212:215], v[68:71]
	v_mfma_f32_16x16x32_bf16 v[64:67], v[156:159], v[212:215], v[64:67]
	s_setprio 0
	s_barrier
	s_add_i32 s49, s40, s0
	s_add_u32 vcc_lo, s22, 0x80
	s_addc_u32 vcc_hi, s23, 0
	s_mov_b32 m0, s49
	ds_read_b128 v[160:163], v210 offset:16384
	ds_read_b128 v[164:167], v210 offset:17408
	ds_read_b128 v[168:171], v210 offset:18432
	ds_read_b128 v[172:175], v210 offset:19456
	global_load_lds_dwordx4 v178, s[22:23]
	s_add_i32 m0, s49, 0x2000
	s_add_u32 s50, s22, 0x160000
	s_addc_u32 s51, s23, 0
	s_add_i32 s49, s41, s0
	global_load_lds_dwordx4 v182, s[22:23]
	s_mov_b32 m0, s49
	ds_read_b128 v[212:215], v210 offset:23552
	global_load_lds_dwordx4 v178, s[50:51]
	s_add_i32 m0, s49, 0x2000
	ds_read_b128 v[200:203], v210 offset:22528
	global_load_lds_dwordx4 v182, s[50:51]
	s_add_u32 s98, s24, 0x80
	s_addc_u32 s99, s25, 0
	s_mov_b32 m0, s1
	ds_read_b128 v[196:199], v210 offset:21504
	global_load_lds_dwordx4 v176, s[24:25]
	s_mov_b32 m0, s26
	ds_read_b128 v[192:195], v210 offset:20480
	global_load_lds_dwordx4 v180, s[24:25]
	s_waitcnt vmcnt(8)
	s_waitcnt lgkmcnt(0)
	s_barrier
	s_setprio 1
	s_waitcnt lgkmcnt(0)
	v_mfma_f32_16x16x32_bf16 v[60:63], v[128:131], v[160:163], v[60:63]
	v_mfma_f32_16x16x32_bf16 v[56:59], v[136:139], v[160:163], v[56:59]
	v_mfma_f32_16x16x32_bf16 v[44:47], v[128:131], v[168:171], v[44:47]
	v_mfma_f32_16x16x32_bf16 v[40:43], v[136:139], v[168:171], v[40:43]
	v_mfma_f32_16x16x32_bf16 v[28:31], v[128:131], v[192:195], v[28:31]
	v_mfma_f32_16x16x32_bf16 v[24:27], v[136:139], v[192:195], v[24:27]
	v_mfma_f32_16x16x32_bf16 v[12:15], v[128:131], v[200:203], v[12:15]
	v_mfma_f32_16x16x32_bf16 v[8:11], v[136:139], v[200:203], v[8:11]
	v_mfma_f32_16x16x32_bf16 v[60:63], v[132:135], v[164:167], v[60:63]
	v_mfma_f32_16x16x32_bf16 v[56:59], v[140:143], v[164:167], v[56:59]
	v_mfma_f32_16x16x32_bf16 v[44:47], v[132:135], v[172:175], v[44:47]
	v_mfma_f32_16x16x32_bf16 v[40:43], v[140:143], v[172:175], v[40:43]
	v_mfma_f32_16x16x32_bf16 v[28:31], v[132:135], v[196:199], v[28:31]
	v_mfma_f32_16x16x32_bf16 v[24:27], v[140:143], v[196:199], v[24:27]
	v_mfma_f32_16x16x32_bf16 v[12:15], v[132:135], v[212:215], v[12:15]
	v_mfma_f32_16x16x32_bf16 v[8:11], v[140:143], v[212:215], v[8:11]
	s_setprio 0
	s_setprio 1
	v_mfma_f32_16x16x32_bf16 v[52:55], v[144:147], v[160:163], v[52:55]
	v_mfma_f32_16x16x32_bf16 v[48:51], v[152:155], v[160:163], v[48:51]
	v_mfma_f32_16x16x32_bf16 v[36:39], v[144:147], v[168:171], v[36:39]
	v_mfma_f32_16x16x32_bf16 v[32:35], v[152:155], v[168:171], v[32:35]
	v_mfma_f32_16x16x32_bf16 v[20:23], v[144:147], v[192:195], v[20:23]
	v_mfma_f32_16x16x32_bf16 v[16:19], v[152:155], v[192:195], v[16:19]
	v_mfma_f32_16x16x32_bf16 v[4:7], v[144:147], v[200:203], v[4:7]
	v_mfma_f32_16x16x32_bf16 v[0:3], v[152:155], v[200:203], v[0:3]
	v_mfma_f32_16x16x32_bf16 v[52:55], v[148:151], v[164:167], v[52:55]
	v_mfma_f32_16x16x32_bf16 v[48:51], v[156:159], v[164:167], v[48:51]
	v_mfma_f32_16x16x32_bf16 v[36:39], v[148:151], v[172:175], v[36:39]
	v_mfma_f32_16x16x32_bf16 v[32:35], v[156:159], v[172:175], v[32:35]
	v_mfma_f32_16x16x32_bf16 v[20:23], v[148:151], v[196:199], v[20:23]
	v_mfma_f32_16x16x32_bf16 v[16:19], v[156:159], v[196:199], v[16:19]
	v_mfma_f32_16x16x32_bf16 v[4:7], v[148:151], v[212:215], v[4:7]
	v_mfma_f32_16x16x32_bf16 v[0:3], v[156:159], v[212:215], v[0:3]
	s_setprio 0
	s_barrier
; #define PG8_STAGE(bufoff, gbase, voff) do { _Pragma("unroll") for (int _i = 0; _i < 2; ++_i) \
;         __builtin_amdgcn_global_load_lds((const unsigned*)((const char*)(gbase) + (voff)[_i]), (PG8_LAS unsigned*)(lds + (bufoff) + ldsw + _i * 8192), 16, 0, 0); } while (0)
; #define PG8_LDA(dst, b, h) do { _Pragma("unroll") for (int m = 0; m < 4; ++m) _Pragma("unroll") for (int k = 0; k < 2; ++k) dst[m][k] = *(const PG8_LAS bf16x8*)(lds + PG8_SA(b, h) + aoff + m * 2048 + k * 1024); } while (0)
; #define PG8_LDB(dst, b, h) do { _Pragma("unroll") for (int n = 0; n < 2; ++n) _Pragma("unroll") for (int k = 0; k < 2; ++k) dst[n][k] = *(const PG8_LAS bf16x8*)(lds + PG8_SB(b, h) + boff + n * 2048 + k * 1024); } while (0)
; #define PG8_MMA(ai, bj, At, Bt) do { __builtin_amdgcn_s_setprio(1); _Pragma("unroll") for (int m = 0; m < 4; ++m) _Pragma("unroll") for (int n = 0; n < 2; ++n) _Pragma("unroll") for (int k = 0; k < 2; ++k) \
;         acc[ai][bj][m][n] = __builtin_amdgcn_mfma_f32_16x16x32_bf16(Bt[n][k], At[m][k], acc[ai][bj][m][n], 0, 0, 0); __builtin_amdgcn_s_setprio(0); } while (0)
; #define PG8_WAIT_V(n) asm volatile("s_waitcnt vmcnt(" #n ")" ::: "memory")
; #define PG8_WAIT_L(n) asm volatile("s_waitcnt lgkmcnt(" #n ")" ::: "memory")
; #define PG8_BAR __builtin_amdgcn_s_barrier()
; #define PG8_SCHED __builtin_amdgcn_sched_barrier(0)
; template <class Epi, class Sched, bool ALIGN_EPI = false, bool SP2 = false>
; __device__ __forceinline__ void gemm_phase(PG8_LAS unsigned char* lds, const Gemm g, const Sched& S, const Epi& E) {
;     ...
;             PG8_LDB(B0, 1, 0); PG8_LDB(B1, 1, 1); PG8_SCHED; PG8_LDA(At, 1, 0); PG8_STAGE(PG8_SA(0, 1), a2 + hstep, voffA);
;             PG8_WAIT_V(8); PG8_WAIT_L(0); PG8_BAR; PG8_MMA(0, 0, At, B0); PG8_MMA(0, 1, At, B1); PG8_BAR; PG8_SCHED;
;             PG8_LDA(At, 1, 1); PG8_STAGE(PG8_SB(1, 0), b3, voffB); PG8_STAGE(PG8_SB(1, 1), b3 + hstep, voffB); PG8_STAGE(PG8_SA(1, 0), a3, voffA);
;             PG8_WAIT_V(8); PG8_WAIT_L(0); PG8_BAR; PG8_MMA(1, 0, At, B0); PG8_MMA(1, 1, At, B1); PG8_BAR; PG8_SCHED;
	s_add_i32 s49, 0, 0x18000
	s_add_i32 s50, 0, 0x1c000
	v_add_u32_e32 v140, s49, v206
	v_add_u32_e32 v156, s50, v206
	ds_read_b128 v[128:131], v140
	ds_read_b128 v[132:135], v140 offset:1024
	ds_read_b128 v[136:139], v140 offset:2048
	ds_read_b128 v[140:143], v140 offset:3072
	ds_read_b128 v[144:147], v156
	ds_read_b128 v[148:151], v156 offset:1024
	ds_read_b128 v[152:155], v156 offset:2048
	ds_read_b128 v[156:159], v156 offset:3072
	s_add_u32 s24, s24, 0x160000
	s_addc_u32 s25, s25, 0
	s_mov_b32 m0, s27
	ds_read_b128 v[160:163], v210 offset:32768
	ds_read_b128 v[164:167], v210 offset:33792
	ds_read_b128 v[168:171], v210 offset:34816
	ds_read_b128 v[172:175], v210 offset:35840
	ds_read_b128 v[192:195], v210 offset:36864
	ds_read_b128 v[196:199], v210 offset:37888
	ds_read_b128 v[200:203], v210 offset:38912
	global_load_lds_dwordx4 v176, s[24:25]
	s_mov_b32 m0, s28
	ds_read_b128 v[212:215], v210 offset:39936
	global_load_lds_dwordx4 v180, s[24:25]
	s_waitcnt vmcnt(8)
	s_waitcnt lgkmcnt(0)
	s_barrier
	s_setprio 1
	s_waitcnt lgkmcnt(0)
	v_mfma_f32_16x16x32_bf16 v[124:127], v[128:131], v[160:163], v[124:127]
	v_mfma_f32_16x16x32_bf16 v[120:123], v[136:139], v[160:163], v[120:123]
	v_mfma_f32_16x16x32_bf16 v[108:111], v[128:131], v[168:171], v[108:111]
	v_mfma_f32_16x16x32_bf16 v[104:107], v[136:139], v[168:171], v[104:107]
	v_mfma_f32_16x16x32_bf16 v[92:95], v[128:131], v[192:195], v[92:95]
	v_mfma_f32_16x16x32_bf16 v[88:91], v[136:139], v[192:195], v[88:91]
	v_mfma_f32_16x16x32_bf16 v[76:79], v[128:131], v[200:203], v[76:79]
	v_mfma_f32_16x16x32_bf16 v[72:75], v[136:139], v[200:203], v[72:75]
	v_mfma_f32_16x16x32_bf16 v[124:127], v[132:135], v[164:167], v[124:127]
	v_mfma_f32_16x16x32_bf16 v[120:123], v[140:143], v[164:167], v[120:123]
	v_mfma_f32_16x16x32_bf16 v[108:111], v[132:135], v[172:175], v[108:111]
	v_mfma_f32_16x16x32_bf16 v[104:107], v[140:143], v[172:175], v[104:107]
	v_mfma_f32_16x16x32_bf16 v[92:95], v[132:135], v[196:199], v[92:95]
	v_mfma_f32_16x16x32_bf16 v[88:91], v[140:143], v[196:199], v[88:91]
	v_mfma_f32_16x16x32_bf16 v[76:79], v[132:135], v[212:215], v[76:79]
	v_mfma_f32_16x16x32_bf16 v[72:75], v[140:143], v[212:215], v[72:75]
	s_setprio 0
	s_setprio 1
	v_mfma_f32_16x16x32_bf16 v[116:119], v[144:147], v[160:163], v[116:119]
	v_mfma_f32_16x16x32_bf16 v[112:115], v[152:155], v[160:163], v[112:115]
	v_mfma_f32_16x16x32_bf16 v[100:103], v[144:147], v[168:171], v[100:103]
	v_mfma_f32_16x16x32_bf16 v[96:99], v[152:155], v[168:171], v[96:99]
	v_mfma_f32_16x16x32_bf16 v[84:87], v[144:147], v[192:195], v[84:87]
	v_mfma_f32_16x16x32_bf16 v[80:83], v[152:155], v[192:195], v[80:83]
	v_mfma_f32_16x16x32_bf16 v[68:71], v[144:147], v[200:203], v[68:71]
	v_mfma_f32_16x16x32_bf16 v[64:67], v[152:155], v[200:203], v[64:67]
	v_mfma_f32_16x16x32_bf16 v[116:119], v[148:151], v[164:167], v[116:119]
	v_mfma_f32_16x16x32_bf16 v[112:115], v[156:159], v[164:167], v[112:115]
	v_mfma_f32_16x16x32_bf16 v[100:103], v[148:151], v[172:175], v[100:103]
	v_mfma_f32_16x16x32_bf16 v[96:99], v[156:159], v[172:175], v[96:99]
	v_mfma_f32_16x16x32_bf16 v[84:87], v[148:151], v[196:199], v[84:87]
	v_mfma_f32_16x16x32_bf16 v[80:83], v[156:159], v[196:199], v[80:83]
	v_mfma_f32_16x16x32_bf16 v[68:71], v[148:151], v[212:215], v[68:71]
	v_mfma_f32_16x16x32_bf16 v[64:67], v[156:159], v[212:215], v[64:67]
	s_setprio 0
	s_barrier
	s_add_i32 s24, s49, s0
	s_mov_b32 m0, s24
	ds_read_b128 v[160:163], v210 offset:49152
	ds_read_b128 v[164:167], v210 offset:50176
	ds_read_b128 v[168:171], v210 offset:51200
	ds_read_b128 v[172:175], v210 offset:52224
	global_load_lds_dwordx4 v178, vcc
	s_add_i32 m0, s24, 0x2000
	s_add_u32 s22, s22, 0x160080
	s_addc_u32 s23, s23, 0
	s_add_i32 s24, s50, s0
	global_load_lds_dwordx4 v182, vcc
	s_mov_b32 m0, s24
	ds_read_b128 v[212:215], v210 offset:56320
	global_load_lds_dwordx4 v178, s[22:23]
	s_add_i32 m0, s24, 0x2000
	ds_read_b128 v[200:203], v210 offset:55296
	global_load_lds_dwordx4 v182, s[22:23]
	s_mov_b32 m0, s30
	ds_read_b128 v[196:199], v210 offset:54272
	global_load_lds_dwordx4 v176, s[98:99]
	s_mov_b32 m0, s31
	ds_read_b128 v[192:195], v210 offset:53248
	global_load_lds_dwordx4 v180, s[98:99]
	s_waitcnt vmcnt(8)
	s_waitcnt lgkmcnt(0)
	s_barrier
	s_setprio 1
	s_waitcnt lgkmcnt(0)
	v_mfma_f32_16x16x32_bf16 v[60:63], v[128:131], v[160:163], v[60:63]
	v_mfma_f32_16x16x32_bf16 v[56:59], v[136:139], v[160:163], v[56:59]
	v_mfma_f32_16x16x32_bf16 v[44:47], v[128:131], v[168:171], v[44:47]
	v_mfma_f32_16x16x32_bf16 v[40:43], v[136:139], v[168:171], v[40:43]
	v_mfma_f32_16x16x32_bf16 v[28:31], v[128:131], v[192:195], v[28:31]
	v_mfma_f32_16x16x32_bf16 v[24:27], v[136:139], v[192:195], v[24:27]
	v_mfma_f32_16x16x32_bf16 v[12:15], v[128:131], v[200:203], v[12:15]
	v_mfma_f32_16x16x32_bf16 v[8:11], v[136:139], v[200:203], v[8:11]
	v_mfma_f32_16x16x32_bf16 v[60:63], v[132:135], v[164:167], v[60:63]
	v_mfma_f32_16x16x32_bf16 v[56:59], v[140:143], v[164:167], v[56:59]
	v_mfma_f32_16x16x32_bf16 v[44:47], v[132:135], v[172:175], v[44:47]
	v_mfma_f32_16x16x32_bf16 v[40:43], v[140:143], v[172:175], v[40:43]
	v_mfma_f32_16x16x32_bf16 v[28:31], v[132:135], v[196:199], v[28:31]
	v_mfma_f32_16x16x32_bf16 v[24:27], v[140:143], v[196:199], v[24:27]
	v_mfma_f32_16x16x32_bf16 v[12:15], v[132:135], v[212:215], v[12:15]
	v_mfma_f32_16x16x32_bf16 v[8:11], v[140:143], v[212:215], v[8:11]
	s_setprio 0
	s_setprio 1
	v_mfma_f32_16x16x32_bf16 v[52:55], v[144:147], v[160:163], v[52:55]
	v_mfma_f32_16x16x32_bf16 v[48:51], v[152:155], v[160:163], v[48:51]
	v_mfma_f32_16x16x32_bf16 v[36:39], v[144:147], v[168:171], v[36:39]
	v_mfma_f32_16x16x32_bf16 v[32:35], v[152:155], v[168:171], v[32:35]
	v_mfma_f32_16x16x32_bf16 v[20:23], v[144:147], v[192:195], v[20:23]
	v_mfma_f32_16x16x32_bf16 v[16:19], v[152:155], v[192:195], v[16:19]
	v_mfma_f32_16x16x32_bf16 v[4:7], v[144:147], v[200:203], v[4:7]
	v_mfma_f32_16x16x32_bf16 v[0:3], v[152:155], v[200:203], v[0:3]
	v_mfma_f32_16x16x32_bf16 v[52:55], v[148:151], v[164:167], v[52:55]
	v_mfma_f32_16x16x32_bf16 v[48:51], v[156:159], v[164:167], v[48:51]
	v_mfma_f32_16x16x32_bf16 v[36:39], v[148:151], v[172:175], v[36:39]
	v_mfma_f32_16x16x32_bf16 v[32:35], v[156:159], v[172:175], v[32:35]
	v_mfma_f32_16x16x32_bf16 v[20:23], v[148:151], v[196:199], v[20:23]
	v_mfma_f32_16x16x32_bf16 v[16:19], v[156:159], v[196:199], v[16:19]
	v_mfma_f32_16x16x32_bf16 v[4:7], v[148:151], v[212:215], v[4:7]
	v_mfma_f32_16x16x32_bf16 v[0:3], v[156:159], v[212:215], v[0:3]
	s_setprio 0
	s_barrier
	s_add_i32 s48, s48, 2
	s_add_u32 s20, s20, 0x100
	s_addc_u32 s21, s21, 0
	s_add_u32 s46, s46, 0x100
	s_addc_u32 s47, s47, 0
	s_cmpk_gt_u32 s48, 0x55
	s_cbranch_scc0 .LBB0_285
	s_and_b64 vcc, exec, s[16:17]
	s_cbranch_vccz .LBB0_288
	s_barrier

; #define PG8_STAGE(bufoff, gbase, voff) do { _Pragma("unroll") for (int _i = 0; _i < 2; ++_i) \
;         __builtin_amdgcn_global_load_lds((const unsigned*)((const char*)(gbase) + (voff)[_i]), (PG8_LAS unsigned*)(lds + (bufoff) + ldsw + _i * 8192), 16, 0, 0); } while (0)
; #define PG8_LDA(dst, b, h) do { _Pragma("unroll") for (int m = 0; m < 4; ++m) _Pragma("unroll") for (int k = 0; k < 2; ++k) dst[m][k] = *(const PG8_LAS bf16x8*)(lds + PG8_SA(b, h) + aoff + m * 2048 + k * 1024); } while (0)
; #define PG8_LDB(dst, b, h) do { _Pragma("unroll") for (int n = 0; n < 2; ++n) _Pragma("unroll") for (int k = 0; k < 2; ++k) dst[n][k] = *(const PG8_LAS bf16x8*)(lds + PG8_SB(b, h) + boff + n * 2048 + k * 1024); } while (0)
; #define PG8_MMA(ai, bj, At, Bt) do { __builtin_amdgcn_s_setprio(1); _Pragma("unroll") for (int m = 0; m < 4; ++m) _Pragma("unroll") for (int n = 0; n < 2; ++n) _Pragma("unroll") for (int k = 0; k < 2; ++k) \
;         acc[ai][bj][m][n] = __builtin_amdgcn_mfma_f32_16x16x32_bf16(Bt[n][k], At[m][k], acc[ai][bj][m][n], 0, 0, 0); __builtin_amdgcn_s_setprio(0); } while (0)
; #define PG8_WAIT_V(n) asm volatile("s_waitcnt vmcnt(" #n ")" ::: "memory")
; #define PG8_WAIT_L(n) asm volatile("s_waitcnt lgkmcnt(" #n ")" ::: "memory")
; #define PG8_BAR __builtin_amdgcn_s_barrier()
; #define PG8_SCHED __builtin_amdgcn_sched_barrier(0)
; template <class Epi, class Sched, bool ALIGN_EPI = false, bool SP2 = false>
; __device__ __forceinline__ void gemm_phase(PG8_LAS unsigned char* lds, const Gemm g, const Sched& S, const Epi& E) {
;     ...
;             PG8_WAIT_V(8); PG8_WAIT_L(0); PG8_BAR; PG8_MMA(0, 0, At, B0); PG8_MMA(0, 1, At, B1); PG8_BAR; PG8_SCHED;
;             PG8_LDA(At, 0, 1); PG8_STAGE(PG8_SB(0, 0), b2, voffB); PG8_STAGE(PG8_SB(0, 1), b2 + hstep, voffB); PG8_STAGE(PG8_SA(0, 0), a2, voffA);
;             PG8_WAIT_V(8); PG8_WAIT_L(0); PG8_BAR; PG8_MMA(1, 0, At, B0); PG8_MMA(1, 1, At, B1); PG8_BAR; PG8_SCHED;
;             PG8_LDB(B0, 1, 0); PG8_LDB(B1, 1, 1); PG8_SCHED; PG8_LDA(At, 1, 0); PG8_STAGE(PG8_SA(0, 1), a2 + hstep, voffA);
.Lgr_p3_0:
	s_waitcnt lgkmcnt(0)
	s_barrier
	s_setprio 1
	s_waitcnt lgkmcnt(0)
	v_mfma_f32_16x16x32_bf16 v[124:127], v[128:131], v[190:193], v[124:127]
	v_mfma_f32_16x16x32_bf16 v[120:123], v[156:159], v[190:193], v[120:123]
	v_mfma_f32_16x16x32_bf16 v[108:111], v[128:131], v[198:201], v[108:111]
	v_mfma_f32_16x16x32_bf16 v[104:107], v[156:159], v[198:201], v[104:107]
	v_mfma_f32_16x16x32_bf16 v[92:95], v[128:131], v[210:213], v[92:95]
	v_mfma_f32_16x16x32_bf16 v[88:91], v[156:159], v[210:213], v[88:91]
	v_mfma_f32_16x16x32_bf16 v[76:79], v[128:131], v[222:225], v[76:79]
	v_mfma_f32_16x16x32_bf16 v[72:75], v[156:159], v[222:225], v[72:75]
	v_mfma_f32_16x16x32_bf16 v[124:127], v[132:135], v[194:197], v[124:127]
	v_mfma_f32_16x16x32_bf16 v[120:123], v[160:163], v[194:197], v[120:123]
	v_mfma_f32_16x16x32_bf16 v[108:111], v[132:135], v[206:209], v[108:111]
	v_mfma_f32_16x16x32_bf16 v[104:107], v[160:163], v[206:209], v[104:107]
	v_mfma_f32_16x16x32_bf16 v[92:95], v[132:135], v[214:217], v[92:95]
	v_mfma_f32_16x16x32_bf16 v[88:91], v[160:163], v[214:217], v[88:91]
	v_mfma_f32_16x16x32_bf16 v[76:79], v[132:135], v[226:229], v[76:79]
	v_mfma_f32_16x16x32_bf16 v[72:75], v[160:163], v[226:229], v[72:75]
	s_setprio 0
	s_setprio 1
	v_mfma_f32_16x16x32_bf16 v[116:119], v[164:167], v[190:193], v[116:119]
	v_mfma_f32_16x16x32_bf16 v[112:115], v[182:185], v[190:193], v[112:115]
	v_mfma_f32_16x16x32_bf16 v[100:103], v[164:167], v[198:201], v[100:103]
	v_mfma_f32_16x16x32_bf16 v[96:99], v[182:185], v[198:201], v[96:99]
	v_mfma_f32_16x16x32_bf16 v[84:87], v[164:167], v[210:213], v[84:87]
	v_mfma_f32_16x16x32_bf16 v[80:83], v[182:185], v[210:213], v[80:83]
	v_mfma_f32_16x16x32_bf16 v[68:71], v[164:167], v[222:225], v[68:71]
	v_mfma_f32_16x16x32_bf16 v[64:67], v[182:185], v[222:225], v[64:67]
	v_mfma_f32_16x16x32_bf16 v[116:119], v[178:181], v[194:197], v[116:119]
	v_mfma_f32_16x16x32_bf16 v[112:115], v[186:189], v[194:197], v[112:115]
	v_mfma_f32_16x16x32_bf16 v[100:103], v[178:181], v[206:209], v[100:103]
	v_mfma_f32_16x16x32_bf16 v[96:99], v[186:189], v[206:209], v[96:99]
	v_mfma_f32_16x16x32_bf16 v[84:87], v[178:181], v[214:217], v[84:87]
	v_mfma_f32_16x16x32_bf16 v[80:83], v[186:189], v[214:217], v[80:83]
	v_mfma_f32_16x16x32_bf16 v[68:71], v[178:181], v[226:229], v[68:71]
	v_mfma_f32_16x16x32_bf16 v[64:67], v[186:189], v[226:229], v[64:67]
	s_setprio 0
	s_barrier
	s_add_i32 s69, s53, s0
	s_add_u32 vcc_lo, s6, 0x80
	s_addc_u32 vcc_hi, s7, 0
	s_mov_b32 m0, s69
	ds_read_b128 v[190:193], v175 offset:16384
	ds_read_b128 v[194:197], v175 offset:17408
	ds_read_b128 v[198:201], v175 offset:18432
	ds_read_b128 v[206:209], v175 offset:19456
	global_load_lds_dwordx4 v138, s[6:7]
	s_add_i32 m0, s69, 0x2000
	s_add_u32 s70, s6, 0x80000
	s_addc_u32 s71, s7, 0
	s_add_i32 s69, s54, s0
	global_load_lds_dwordx4 v142, s[6:7]
	s_mov_b32 m0, s69
	ds_read_b128 v[226:229], v175 offset:23552
	global_load_lds_dwordx4 v138, s[70:71]
	s_add_i32 m0, s69, 0x2000
	ds_read_b128 v[222:225], v175 offset:22528
	global_load_lds_dwordx4 v142, s[70:71]
	s_add_u32 s98, s42, 0x80
	s_addc_u32 s99, s43, 0
	s_mov_b32 m0, s1
	ds_read_b128 v[214:217], v175 offset:21504
	global_load_lds_dwordx4 v136, s[42:43]
	s_mov_b32 m0, s33
	ds_read_b128 v[210:213], v175 offset:20480
	global_load_lds_dwordx4 v140, s[42:43]
	s_cmp_lg_u32 s100, 0
	s_cbranch_scc1 .Lgr_p3_1
	s_waitcnt vmcnt(8)
.Lgr_p3_1:
	s_waitcnt lgkmcnt(0)
	s_barrier
	s_setprio 1
	s_waitcnt lgkmcnt(0)
	v_mfma_f32_16x16x32_bf16 v[60:63], v[128:131], v[190:193], v[60:63]
	v_mfma_f32_16x16x32_bf16 v[56:59], v[156:159], v[190:193], v[56:59]
	v_mfma_f32_16x16x32_bf16 v[44:47], v[128:131], v[198:201], v[44:47]
	v_mfma_f32_16x16x32_bf16 v[40:43], v[156:159], v[198:201], v[40:43]
	v_mfma_f32_16x16x32_bf16 v[28:31], v[128:131], v[210:213], v[28:31]
	v_mfma_f32_16x16x32_bf16 v[24:27], v[156:159], v[210:213], v[24:27]
	v_mfma_f32_16x16x32_bf16 v[12:15], v[128:131], v[222:225], v[12:15]
	v_mfma_f32_16x16x32_bf16 v[8:11], v[156:159], v[222:225], v[8:11]
	v_mfma_f32_16x16x32_bf16 v[60:63], v[132:135], v[194:197], v[60:63]
	v_mfma_f32_16x16x32_bf16 v[56:59], v[160:163], v[194:197], v[56:59]
	v_mfma_f32_16x16x32_bf16 v[44:47], v[132:135], v[206:209], v[44:47]
	v_mfma_f32_16x16x32_bf16 v[40:43], v[160:163], v[206:209], v[40:43]
	v_mfma_f32_16x16x32_bf16 v[28:31], v[132:135], v[214:217], v[28:31]
	v_mfma_f32_16x16x32_bf16 v[24:27], v[160:163], v[214:217], v[24:27]
	v_mfma_f32_16x16x32_bf16 v[12:15], v[132:135], v[226:229], v[12:15]
	v_mfma_f32_16x16x32_bf16 v[8:11], v[160:163], v[226:229], v[8:11]
	s_setprio 0
	s_setprio 1
	v_mfma_f32_16x16x32_bf16 v[52:55], v[164:167], v[190:193], v[52:55]
	v_mfma_f32_16x16x32_bf16 v[48:51], v[182:185], v[190:193], v[48:51]
	v_mfma_f32_16x16x32_bf16 v[36:39], v[164:167], v[198:201], v[36:39]
	v_mfma_f32_16x16x32_bf16 v[32:35], v[182:185], v[198:201], v[32:35]
	v_mfma_f32_16x16x32_bf16 v[20:23], v[164:167], v[210:213], v[20:23]
	v_mfma_f32_16x16x32_bf16 v[16:19], v[182:185], v[210:213], v[16:19]
	v_mfma_f32_16x16x32_bf16 v[4:7], v[164:167], v[222:225], v[4:7]
	v_mfma_f32_16x16x32_bf16 v[0:3], v[182:185], v[222:225], v[0:3]
	v_mfma_f32_16x16x32_bf16 v[52:55], v[178:181], v[194:197], v[52:55]
	v_mfma_f32_16x16x32_bf16 v[48:51], v[186:189], v[194:197], v[48:51]
	v_mfma_f32_16x16x32_bf16 v[36:39], v[178:181], v[206:209], v[36:39]
	v_mfma_f32_16x16x32_bf16 v[32:35], v[186:189], v[206:209], v[32:35]
	v_mfma_f32_16x16x32_bf16 v[20:23], v[178:181], v[214:217], v[20:23]
	v_mfma_f32_16x16x32_bf16 v[16:19], v[186:189], v[214:217], v[16:19]
	v_mfma_f32_16x16x32_bf16 v[4:7], v[178:181], v[226:229], v[4:7]
	v_mfma_f32_16x16x32_bf16 v[0:3], v[186:189], v[226:229], v[0:3]
	s_setprio 0
	s_barrier
	s_add_i32 s69, 0, 0x18000
	v_add_u32_e32 v144, s69, v171
	s_add_i32 s70, 0, 0x1c000
	ds_read_b128 v[128:131], v144
	ds_read_b128 v[132:135], v144 offset:1024
	ds_read_b128 v[156:159], v144 offset:2048
	ds_read_b128 v[160:163], v144 offset:3072
	v_add_u32_e32 v144, s70, v171
	ds_read_b128 v[164:167], v144
	ds_read_b128 v[178:181], v144 offset:1024
	ds_read_b128 v[182:185], v144 offset:2048
	ds_read_b128 v[186:189], v144 offset:3072
	s_add_u32 s42, s42, 0x80000
	s_addc_u32 s43, s43, 0
	s_mov_b32 m0, s37
	ds_read_b128 v[190:193], v175 offset:32768
	ds_read_b128 v[194:197], v175 offset:33792
	ds_read_b128 v[198:201], v175 offset:34816
	ds_read_b128 v[206:209], v175 offset:35840
	ds_read_b128 v[210:213], v175 offset:36864
	ds_read_b128 v[214:217], v175 offset:37888
	ds_read_b128 v[222:225], v175 offset:38912
	global_load_lds_dwordx4 v136, s[42:43]
	s_mov_b32 m0, s41
	ds_read_b128 v[226:229], v175 offset:39936
	global_load_lds_dwordx4 v140, s[42:43]
	s_cmp_lg_u32 s100, 0
	s_cbranch_scc1 .Lgr_p3_2
	s_waitcnt vmcnt(8)
; #define PG8_STAGE(bufoff, gbase, voff) do { _Pragma("unroll") for (int _i = 0; _i < 2; ++_i) \
;         __builtin_amdgcn_global_load_lds((const unsigned*)((const char*)(gbase) + (voff)[_i]), (PG8_LAS unsigned*)(lds + (bufoff) + ldsw + _i * 8192), 16, 0, 0); } while (0)
; #define PG8_LDA(dst, b, h) do { _Pragma("unroll") for (int m = 0; m < 4; ++m) _Pragma("unroll") for (int k = 0; k < 2; ++k) dst[m][k] = *(const PG8_LAS bf16x8*)(lds + PG8_SA(b, h) + aoff + m * 2048 + k * 1024); } while (0)
; #define PG8_MMA(ai, bj, At, Bt) do { __builtin_amdgcn_s_setprio(1); _Pragma("unroll") for (int m = 0; m < 4; ++m) _Pragma("unroll") for (int n = 0; n < 2; ++n) _Pragma("unroll") for (int k = 0; k < 2; ++k) \
;         acc[ai][bj][m][n] = __builtin_amdgcn_mfma_f32_16x16x32_bf16(Bt[n][k], At[m][k], acc[ai][bj][m][n], 0, 0, 0); __builtin_amdgcn_s_setprio(0); } while (0)
; #define PG8_WAIT_V(n) asm volatile("s_waitcnt vmcnt(" #n ")" ::: "memory")
; #define PG8_WAIT_L(n) asm volatile("s_waitcnt lgkmcnt(" #n ")" ::: "memory")
; #define PG8_BAR __builtin_amdgcn_s_barrier()
; #define PG8_SCHED __builtin_amdgcn_sched_barrier(0)
; template <class Epi, class Sched, bool ALIGN_EPI = false, bool SP2 = false>
; __device__ __forceinline__ void gemm_phase(PG8_LAS unsigned char* lds, const Gemm g, const Sched& S, const Epi& E) {
;     ...
;             PG8_WAIT_V(8); PG8_WAIT_L(0); PG8_BAR; PG8_MMA(0, 0, At, B0); PG8_MMA(0, 1, At, B1); PG8_BAR; PG8_SCHED;
;             PG8_LDA(At, 1, 1); PG8_STAGE(PG8_SB(1, 0), b3, voffB); PG8_STAGE(PG8_SB(1, 1), b3 + hstep, voffB); PG8_STAGE(PG8_SA(1, 0), a3, voffA);
;             PG8_WAIT_V(8); PG8_WAIT_L(0); PG8_BAR; PG8_MMA(1, 0, At, B0); PG8_MMA(1, 1, At, B1); PG8_BAR; PG8_SCHED;
.Lgr_p3_2:
	s_waitcnt lgkmcnt(0)
	s_barrier
	s_setprio 1
	s_waitcnt lgkmcnt(0)
	v_mfma_f32_16x16x32_bf16 v[124:127], v[128:131], v[190:193], v[124:127]
	v_mfma_f32_16x16x32_bf16 v[120:123], v[156:159], v[190:193], v[120:123]
	v_mfma_f32_16x16x32_bf16 v[108:111], v[128:131], v[198:201], v[108:111]
	v_mfma_f32_16x16x32_bf16 v[104:107], v[156:159], v[198:201], v[104:107]
	v_mfma_f32_16x16x32_bf16 v[92:95], v[128:131], v[210:213], v[92:95]
	v_mfma_f32_16x16x32_bf16 v[88:91], v[156:159], v[210:213], v[88:91]
	v_mfma_f32_16x16x32_bf16 v[76:79], v[128:131], v[222:225], v[76:79]
	v_mfma_f32_16x16x32_bf16 v[72:75], v[156:159], v[222:225], v[72:75]
	v_mfma_f32_16x16x32_bf16 v[124:127], v[132:135], v[194:197], v[124:127]
	v_mfma_f32_16x16x32_bf16 v[120:123], v[160:163], v[194:197], v[120:123]
	v_mfma_f32_16x16x32_bf16 v[108:111], v[132:135], v[206:209], v[108:111]
	v_mfma_f32_16x16x32_bf16 v[104:107], v[160:163], v[206:209], v[104:107]
	v_mfma_f32_16x16x32_bf16 v[92:95], v[132:135], v[214:217], v[92:95]
	v_mfma_f32_16x16x32_bf16 v[88:91], v[160:163], v[214:217], v[88:91]
	v_mfma_f32_16x16x32_bf16 v[76:79], v[132:135], v[226:229], v[76:79]
	v_mfma_f32_16x16x32_bf16 v[72:75], v[160:163], v[226:229], v[72:75]
	s_setprio 0
	s_setprio 1
	v_mfma_f32_16x16x32_bf16 v[116:119], v[164:167], v[190:193], v[116:119]
	v_mfma_f32_16x16x32_bf16 v[112:115], v[182:185], v[190:193], v[112:115]
	v_mfma_f32_16x16x32_bf16 v[100:103], v[164:167], v[198:201], v[100:103]
	v_mfma_f32_16x16x32_bf16 v[96:99], v[182:185], v[198:201], v[96:99]
	v_mfma_f32_16x16x32_bf16 v[84:87], v[164:167], v[210:213], v[84:87]
	v_mfma_f32_16x16x32_bf16 v[80:83], v[182:185], v[210:213], v[80:83]
	v_mfma_f32_16x16x32_bf16 v[68:71], v[164:167], v[222:225], v[68:71]
	v_mfma_f32_16x16x32_bf16 v[64:67], v[182:185], v[222:225], v[64:67]
	v_mfma_f32_16x16x32_bf16 v[116:119], v[178:181], v[194:197], v[116:119]
	v_mfma_f32_16x16x32_bf16 v[112:115], v[186:189], v[194:197], v[112:115]
	v_mfma_f32_16x16x32_bf16 v[100:103], v[178:181], v[206:209], v[100:103]
	v_mfma_f32_16x16x32_bf16 v[96:99], v[186:189], v[206:209], v[96:99]
	v_mfma_f32_16x16x32_bf16 v[84:87], v[178:181], v[214:217], v[84:87]
	v_mfma_f32_16x16x32_bf16 v[80:83], v[186:189], v[214:217], v[80:83]
	v_mfma_f32_16x16x32_bf16 v[68:71], v[178:181], v[226:229], v[68:71]
	v_mfma_f32_16x16x32_bf16 v[64:67], v[186:189], v[226:229], v[64:67]
	s_setprio 0
	s_barrier
	s_add_i32 s42, s69, s0
	s_mov_b32 m0, s42
	ds_read_b128 v[190:193], v175 offset:49152
	ds_read_b128 v[194:197], v175 offset:50176
	ds_read_b128 v[198:201], v175 offset:51200
	ds_read_b128 v[206:209], v175 offset:52224
	global_load_lds_dwordx4 v138, vcc
	s_add_i32 m0, s42, 0x2000
	s_add_u32 s6, s6, 0x80080
	s_addc_u32 s7, s7, 0
	s_add_i32 s42, s70, s0
	global_load_lds_dwordx4 v142, vcc
	s_mov_b32 m0, s42
	ds_read_b128 v[226:229], v175 offset:56320
	global_load_lds_dwordx4 v138, s[6:7]
	s_add_i32 m0, s42, 0x2000
	ds_read_b128 v[222:225], v175 offset:55296
	global_load_lds_dwordx4 v142, s[6:7]
	s_mov_b32 m0, s48
	ds_read_b128 v[214:217], v175 offset:54272
	global_load_lds_dwordx4 v136, s[98:99]
	s_mov_b32 m0, s49
	ds_read_b128 v[210:213], v175 offset:53248
	global_load_lds_dwordx4 v140, s[98:99]
	s_waitcnt vmcnt(8)
	s_waitcnt lgkmcnt(0)
	s_barrier
	s_setprio 1
	s_waitcnt lgkmcnt(0)
	v_mfma_f32_16x16x32_bf16 v[60:63], v[128:131], v[190:193], v[60:63]
	v_mfma_f32_16x16x32_bf16 v[56:59], v[156:159], v[190:193], v[56:59]
	v_mfma_f32_16x16x32_bf16 v[44:47], v[128:131], v[198:201], v[44:47]
	v_mfma_f32_16x16x32_bf16 v[40:43], v[156:159], v[198:201], v[40:43]
	v_mfma_f32_16x16x32_bf16 v[28:31], v[128:131], v[210:213], v[28:31]
	v_mfma_f32_16x16x32_bf16 v[24:27], v[156:159], v[210:213], v[24:27]
	v_mfma_f32_16x16x32_bf16 v[12:15], v[128:131], v[222:225], v[12:15]
	v_mfma_f32_16x16x32_bf16 v[8:11], v[156:159], v[222:225], v[8:11]
	v_mfma_f32_16x16x32_bf16 v[60:63], v[132:135], v[194:197], v[60:63]
	v_mfma_f32_16x16x32_bf16 v[56:59], v[160:163], v[194:197], v[56:59]
	v_mfma_f32_16x16x32_bf16 v[44:47], v[132:135], v[206:209], v[44:47]
	v_mfma_f32_16x16x32_bf16 v[40:43], v[160:163], v[206:209], v[40:43]
	v_mfma_f32_16x16x32_bf16 v[28:31], v[132:135], v[214:217], v[28:31]
	v_mfma_f32_16x16x32_bf16 v[24:27], v[160:163], v[214:217], v[24:27]
	v_mfma_f32_16x16x32_bf16 v[12:15], v[132:135], v[226:229], v[12:15]
	v_mfma_f32_16x16x32_bf16 v[8:11], v[160:163], v[226:229], v[8:11]
	s_setprio 0
	s_setprio 1
	v_mfma_f32_16x16x32_bf16 v[52:55], v[164:167], v[190:193], v[52:55]
	v_mfma_f32_16x16x32_bf16 v[48:51], v[182:185], v[190:193], v[48:51]
	v_mfma_f32_16x16x32_bf16 v[36:39], v[164:167], v[198:201], v[36:39]
	v_mfma_f32_16x16x32_bf16 v[32:35], v[182:185], v[198:201], v[32:35]
	v_mfma_f32_16x16x32_bf16 v[20:23], v[164:167], v[210:213], v[20:23]
	v_mfma_f32_16x16x32_bf16 v[16:19], v[182:185], v[210:213], v[16:19]
	v_mfma_f32_16x16x32_bf16 v[4:7], v[164:167], v[222:225], v[4:7]
	v_mfma_f32_16x16x32_bf16 v[0:3], v[182:185], v[222:225], v[0:3]
	v_mfma_f32_16x16x32_bf16 v[52:55], v[178:181], v[194:197], v[52:55]
	v_mfma_f32_16x16x32_bf16 v[48:51], v[186:189], v[194:197], v[48:51]
	v_mfma_f32_16x16x32_bf16 v[36:39], v[178:181], v[206:209], v[36:39]
	v_mfma_f32_16x16x32_bf16 v[32:35], v[186:189], v[206:209], v[32:35]
	v_mfma_f32_16x16x32_bf16 v[20:23], v[178:181], v[214:217], v[20:23]
	v_mfma_f32_16x16x32_bf16 v[16:19], v[186:189], v[214:217], v[16:19]
	v_mfma_f32_16x16x32_bf16 v[4:7], v[178:181], v[226:229], v[4:7]
	v_mfma_f32_16x16x32_bf16 v[0:3], v[186:189], v[226:229], v[0:3]
	s_setprio 0
	s_barrier
	s_mov_b32 s100, 0
	s_add_i32 s47, s47, 2
	s_add_u32 s4, s4, 0x100
	s_addc_u32 s5, s5, 0
	s_add_u32 s45, s45, 0x100
	s_addc_u32 s46, s46, 0
	s_cmp_gt_u32 s47, 29
	s_cbranch_scc0 .LBB0_370
	s_and_b64 vcc, exec, s[18:19]
	s_cbranch_vccnz .LBB0_375
	s_add_u32 s98, s29, 0x80080
	s_addc_u32 s99, s10, 0
	v_lshl_add_u64 v[252:253], s[98:99], 0, v[146:147]
	s_add_i32 m0, s1, 0xc000
	s_nop 0
	global_load_lds_dwordx4 v[252:253], off
	v_lshl_add_u64 v[252:253], s[98:99], 0, v[148:149]
	s_add_i32 m0, s1, 0xe000
	s_nop 0
	global_load_lds_dwordx4 v[252:253], off
	s_mov_b32 s100, 1
	s_cmp_gt_i32 s36, 7
	s_mov_b64 s[4:5], -1
	s_cbranch_scc1 .LBB0_376

; #define PG8_STAGE(bufoff, gbase, voff) do { _Pragma("unroll") for (int _i = 0; _i < 2; ++_i) \
;         __builtin_amdgcn_global_load_lds((const unsigned*)((const char*)(gbase) + (voff)[_i]), (PG8_LAS unsigned*)(lds + (bufoff) + ldsw + _i * 8192), 16, 0, 0); } while (0)
; #define PG8_LDA(dst, b, h) do { _Pragma("unroll") for (int m = 0; m < 4; ++m) _Pragma("unroll") for (int k = 0; k < 2; ++k) dst[m][k] = *(const PG8_LAS bf16x8*)(lds + PG8_SA(b, h) + aoff + m * 2048 + k * 1024); } while (0)
; #define PG8_LDB(dst, b, h) do { _Pragma("unroll") for (int n = 0; n < 2; ++n) _Pragma("unroll") for (int k = 0; k < 2; ++k) dst[n][k] = *(const PG8_LAS bf16x8*)(lds + PG8_SB(b, h) + boff + n * 2048 + k * 1024); } while (0)
; #define PG8_MMA(ai, bj, At, Bt) do { __builtin_amdgcn_s_setprio(1); _Pragma("unroll") for (int m = 0; m < 4; ++m) _Pragma("unroll") for (int n = 0; n < 2; ++n) _Pragma("unroll") for (int k = 0; k < 2; ++k) \
;         acc[ai][bj][m][n] = __builtin_amdgcn_mfma_f32_16x16x32_bf16(Bt[n][k], At[m][k], acc[ai][bj][m][n], 0, 0, 0); __builtin_amdgcn_s_setprio(0); } while (0)
; #define PG8_WAIT_V(n) asm volatile("s_waitcnt vmcnt(" #n ")" ::: "memory")
; #define PG8_WAIT_L(n) asm volatile("s_waitcnt lgkmcnt(" #n ")" ::: "memory")
; #define PG8_BAR __builtin_amdgcn_s_barrier()
; #define PG8_SCHED __builtin_amdgcn_sched_barrier(0)
; template <class Epi, class Sched, bool ALIGN_EPI = false, bool SP2 = false>
; __device__ __forceinline__ void gemm_phase(PG8_LAS unsigned char* lds, const Gemm g, const Sched& S, const Epi& E) {
;     ...
;             PG8_WAIT_V(8); PG8_WAIT_L(0); PG8_BAR; PG8_MMA(0, 0, At, B0); PG8_MMA(0, 1, At, B1); PG8_BAR; PG8_SCHED;
;             PG8_LDA(At, 0, 1); PG8_STAGE(PG8_SB(0, 0), b2, voffB); PG8_STAGE(PG8_SB(0, 1), b2 + hstep, voffB); PG8_STAGE(PG8_SA(0, 0), a2, voffA);
;             PG8_WAIT_V(8); PG8_WAIT_L(0); PG8_BAR; PG8_MMA(1, 0, At, B0); PG8_MMA(1, 1, At, B1); PG8_BAR; PG8_SCHED;
;             PG8_LDB(B0, 1, 0); PG8_LDB(B1, 1, 1); PG8_SCHED; PG8_LDA(At, 1, 0); PG8_STAGE(PG8_SA(0, 1), a2 + hstep, voffA);
.Lgr_p5_0:
	s_waitcnt lgkmcnt(0)
	s_barrier
	s_setprio 1
	s_waitcnt lgkmcnt(0)
	v_mfma_f32_16x16x32_bf16 v[124:127], v[128:131], v[160:163], v[124:127]
	v_mfma_f32_16x16x32_bf16 v[120:123], v[136:139], v[160:163], v[120:123]
	v_mfma_f32_16x16x32_bf16 v[108:111], v[128:131], v[168:171], v[108:111]
	v_mfma_f32_16x16x32_bf16 v[104:107], v[136:139], v[168:171], v[104:107]
	v_mfma_f32_16x16x32_bf16 v[92:95], v[128:131], v[176:179], v[92:95]
	v_mfma_f32_16x16x32_bf16 v[88:91], v[136:139], v[176:179], v[88:91]
	v_mfma_f32_16x16x32_bf16 v[76:79], v[128:131], v[184:187], v[76:79]
	v_mfma_f32_16x16x32_bf16 v[72:75], v[136:139], v[184:187], v[72:75]
	v_mfma_f32_16x16x32_bf16 v[124:127], v[132:135], v[164:167], v[124:127]
	v_mfma_f32_16x16x32_bf16 v[120:123], v[140:143], v[164:167], v[120:123]
	v_mfma_f32_16x16x32_bf16 v[108:111], v[132:135], v[172:175], v[108:111]
	v_mfma_f32_16x16x32_bf16 v[104:107], v[140:143], v[172:175], v[104:107]
	v_mfma_f32_16x16x32_bf16 v[92:95], v[132:135], v[180:183], v[92:95]
	v_mfma_f32_16x16x32_bf16 v[88:91], v[140:143], v[180:183], v[88:91]
	v_mfma_f32_16x16x32_bf16 v[76:79], v[132:135], v[188:191], v[76:79]
	v_mfma_f32_16x16x32_bf16 v[72:75], v[140:143], v[188:191], v[72:75]
	s_setprio 0
	s_setprio 1
	v_mfma_f32_16x16x32_bf16 v[116:119], v[144:147], v[160:163], v[116:119]
	v_mfma_f32_16x16x32_bf16 v[112:115], v[152:155], v[160:163], v[112:115]
	v_mfma_f32_16x16x32_bf16 v[100:103], v[144:147], v[168:171], v[100:103]
	v_mfma_f32_16x16x32_bf16 v[96:99], v[152:155], v[168:171], v[96:99]
	v_mfma_f32_16x16x32_bf16 v[84:87], v[144:147], v[176:179], v[84:87]
	v_mfma_f32_16x16x32_bf16 v[80:83], v[152:155], v[176:179], v[80:83]
	v_mfma_f32_16x16x32_bf16 v[68:71], v[144:147], v[184:187], v[68:71]
	v_mfma_f32_16x16x32_bf16 v[64:67], v[152:155], v[184:187], v[64:67]
	v_mfma_f32_16x16x32_bf16 v[116:119], v[148:151], v[164:167], v[116:119]
	v_mfma_f32_16x16x32_bf16 v[112:115], v[156:159], v[164:167], v[112:115]
	v_mfma_f32_16x16x32_bf16 v[100:103], v[148:151], v[172:175], v[100:103]
	v_mfma_f32_16x16x32_bf16 v[96:99], v[156:159], v[172:175], v[96:99]
	v_mfma_f32_16x16x32_bf16 v[84:87], v[148:151], v[180:183], v[84:87]
	v_mfma_f32_16x16x32_bf16 v[80:83], v[156:159], v[180:183], v[80:83]
	v_mfma_f32_16x16x32_bf16 v[68:71], v[148:151], v[188:191], v[68:71]
	v_mfma_f32_16x16x32_bf16 v[64:67], v[156:159], v[188:191], v[64:67]
	s_setprio 0
	s_barrier
	s_add_i32 s47, s41, s29
	s_add_u32 vcc_lo, s24, 0x80
	s_addc_u32 vcc_hi, s25, 0
	s_mov_b32 m0, s47
	ds_read_b128 v[160:163], v226 offset:16384
	ds_read_b128 v[164:167], v226 offset:17408
	ds_read_b128 v[168:171], v226 offset:18432
	ds_read_b128 v[172:175], v226 offset:19456
	global_load_lds_dwordx4 v194, s[24:25]
	s_add_i32 m0, s47, 0x2000
	s_add_u32 s48, s24, 0x40000
	s_addc_u32 s49, s25, 0
	s_add_i32 s47, s42, s29
	global_load_lds_dwordx4 v198, s[24:25]
	s_mov_b32 m0, s47
	ds_read_b128 v[188:191], v226 offset:23552
	global_load_lds_dwordx4 v194, s[48:49]
	s_add_i32 m0, s47, 0x2000
	ds_read_b128 v[184:187], v226 offset:22528
	global_load_lds_dwordx4 v198, s[48:49]
	s_add_u32 s98, s26, 0x80
	s_addc_u32 s99, s27, 0
	s_mov_b32 m0, s21
	ds_read_b128 v[180:183], v226 offset:21504
	global_load_lds_dwordx4 v192, s[26:27]
	s_mov_b32 m0, s30
	ds_read_b128 v[176:179], v226 offset:20480
	global_load_lds_dwordx4 v196, s[26:27]
	s_cmp_lg_u32 s100, 0
	s_cbranch_scc1 .Lgr_p5_1
	s_waitcnt vmcnt(8)
.Lgr_p5_1:
	s_waitcnt lgkmcnt(0)
	s_barrier
	s_setprio 1
	s_waitcnt lgkmcnt(0)
	v_mfma_f32_16x16x32_bf16 v[60:63], v[128:131], v[160:163], v[60:63]
	v_mfma_f32_16x16x32_bf16 v[56:59], v[136:139], v[160:163], v[56:59]
	v_mfma_f32_16x16x32_bf16 v[44:47], v[128:131], v[168:171], v[44:47]
	v_mfma_f32_16x16x32_bf16 v[40:43], v[136:139], v[168:171], v[40:43]
	v_mfma_f32_16x16x32_bf16 v[28:31], v[128:131], v[176:179], v[28:31]
	v_mfma_f32_16x16x32_bf16 v[24:27], v[136:139], v[176:179], v[24:27]
	v_mfma_f32_16x16x32_bf16 v[12:15], v[128:131], v[184:187], v[12:15]
	v_mfma_f32_16x16x32_bf16 v[8:11], v[136:139], v[184:187], v[8:11]
	v_mfma_f32_16x16x32_bf16 v[60:63], v[132:135], v[164:167], v[60:63]
	v_mfma_f32_16x16x32_bf16 v[56:59], v[140:143], v[164:167], v[56:59]
	v_mfma_f32_16x16x32_bf16 v[44:47], v[132:135], v[172:175], v[44:47]
	v_mfma_f32_16x16x32_bf16 v[40:43], v[140:143], v[172:175], v[40:43]
	v_mfma_f32_16x16x32_bf16 v[28:31], v[132:135], v[180:183], v[28:31]
	v_mfma_f32_16x16x32_bf16 v[24:27], v[140:143], v[180:183], v[24:27]
	v_mfma_f32_16x16x32_bf16 v[12:15], v[132:135], v[188:191], v[12:15]
	v_mfma_f32_16x16x32_bf16 v[8:11], v[140:143], v[188:191], v[8:11]
	s_setprio 0
	s_setprio 1
	v_mfma_f32_16x16x32_bf16 v[52:55], v[144:147], v[160:163], v[52:55]
	v_mfma_f32_16x16x32_bf16 v[48:51], v[152:155], v[160:163], v[48:51]
	v_mfma_f32_16x16x32_bf16 v[36:39], v[144:147], v[168:171], v[36:39]
	v_mfma_f32_16x16x32_bf16 v[32:35], v[152:155], v[168:171], v[32:35]
	v_mfma_f32_16x16x32_bf16 v[20:23], v[144:147], v[176:179], v[20:23]
	v_mfma_f32_16x16x32_bf16 v[16:19], v[152:155], v[176:179], v[16:19]
	v_mfma_f32_16x16x32_bf16 v[4:7], v[144:147], v[184:187], v[4:7]
	v_mfma_f32_16x16x32_bf16 v[0:3], v[152:155], v[184:187], v[0:3]
	v_mfma_f32_16x16x32_bf16 v[52:55], v[148:151], v[164:167], v[52:55]
	v_mfma_f32_16x16x32_bf16 v[48:51], v[156:159], v[164:167], v[48:51]
	v_mfma_f32_16x16x32_bf16 v[36:39], v[148:151], v[172:175], v[36:39]
	v_mfma_f32_16x16x32_bf16 v[32:35], v[156:159], v[172:175], v[32:35]
	v_mfma_f32_16x16x32_bf16 v[20:23], v[148:151], v[180:183], v[20:23]
	v_mfma_f32_16x16x32_bf16 v[16:19], v[156:159], v[180:183], v[16:19]
	v_mfma_f32_16x16x32_bf16 v[4:7], v[148:151], v[188:191], v[4:7]
	v_mfma_f32_16x16x32_bf16 v[0:3], v[156:159], v[188:191], v[0:3]
	s_setprio 0
	s_barrier
	s_add_i32 s47, 0, 0x18000
	s_add_i32 s48, 0, 0x1c000
	v_add_u32_e32 v140, s47, v222
	v_add_u32_e32 v156, s48, v222
	ds_read_b128 v[128:131], v140
	ds_read_b128 v[132:135], v140 offset:1024
	ds_read_b128 v[136:139], v140 offset:2048
	ds_read_b128 v[140:143], v140 offset:3072
	ds_read_b128 v[144:147], v156
	ds_read_b128 v[148:151], v156 offset:1024
	ds_read_b128 v[152:155], v156 offset:2048
	ds_read_b128 v[156:159], v156 offset:3072
	s_add_u32 s26, s26, 0x40000
	s_addc_u32 s27, s27, 0
	s_mov_b32 m0, s31
	ds_read_b128 v[160:163], v226 offset:32768
	ds_read_b128 v[164:167], v226 offset:33792
	ds_read_b128 v[168:171], v226 offset:34816
	ds_read_b128 v[172:175], v226 offset:35840
	ds_read_b128 v[176:179], v226 offset:36864
	ds_read_b128 v[180:183], v226 offset:37888
	ds_read_b128 v[184:187], v226 offset:38912
	global_load_lds_dwordx4 v192, s[26:27]
	s_mov_b32 m0, s33
	ds_read_b128 v[188:191], v226 offset:39936
	global_load_lds_dwordx4 v196, s[26:27]
	s_cmp_lg_u32 s100, 0
	s_cbranch_scc1 .Lgr_p5_2
	s_waitcnt vmcnt(8)
; #define PG8_STAGE(bufoff, gbase, voff) do { _Pragma("unroll") for (int _i = 0; _i < 2; ++_i) \
;         __builtin_amdgcn_global_load_lds((const unsigned*)((const char*)(gbase) + (voff)[_i]), (PG8_LAS unsigned*)(lds + (bufoff) + ldsw + _i * 8192), 16, 0, 0); } while (0)
; #define PG8_LDA(dst, b, h) do { _Pragma("unroll") for (int m = 0; m < 4; ++m) _Pragma("unroll") for (int k = 0; k < 2; ++k) dst[m][k] = *(const PG8_LAS bf16x8*)(lds + PG8_SA(b, h) + aoff + m * 2048 + k * 1024); } while (0)
; #define PG8_MMA(ai, bj, At, Bt) do { __builtin_amdgcn_s_setprio(1); _Pragma("unroll") for (int m = 0; m < 4; ++m) _Pragma("unroll") for (int n = 0; n < 2; ++n) _Pragma("unroll") for (int k = 0; k < 2; ++k) \
;         acc[ai][bj][m][n] = __builtin_amdgcn_mfma_f32_16x16x32_bf16(Bt[n][k], At[m][k], acc[ai][bj][m][n], 0, 0, 0); __builtin_amdgcn_s_setprio(0); } while (0)
; #define PG8_WAIT_V(n) asm volatile("s_waitcnt vmcnt(" #n ")" ::: "memory")
; #define PG8_WAIT_L(n) asm volatile("s_waitcnt lgkmcnt(" #n ")" ::: "memory")
; #define PG8_BAR __builtin_amdgcn_s_barrier()
; #define PG8_SCHED __builtin_amdgcn_sched_barrier(0)
; template <class Epi, class Sched, bool ALIGN_EPI = false, bool SP2 = false>
; __device__ __forceinline__ void gemm_phase(PG8_LAS unsigned char* lds, const Gemm g, const Sched& S, const Epi& E) {
;     ...
;             PG8_WAIT_V(8); PG8_WAIT_L(0); PG8_BAR; PG8_MMA(0, 0, At, B0); PG8_MMA(0, 1, At, B1); PG8_BAR; PG8_SCHED;
;             PG8_LDA(At, 1, 1); PG8_STAGE(PG8_SB(1, 0), b3, voffB); PG8_STAGE(PG8_SB(1, 1), b3 + hstep, voffB); PG8_STAGE(PG8_SA(1, 0), a3, voffA);
;             PG8_WAIT_V(8); PG8_WAIT_L(0); PG8_BAR; PG8_MMA(1, 0, At, B0); PG8_MMA(1, 1, At, B1); PG8_BAR; PG8_SCHED;
.Lgr_p5_2:
	s_waitcnt lgkmcnt(0)
	s_barrier
	s_setprio 1
	s_waitcnt lgkmcnt(0)
	v_mfma_f32_16x16x32_bf16 v[124:127], v[128:131], v[160:163], v[124:127]
	v_mfma_f32_16x16x32_bf16 v[120:123], v[136:139], v[160:163], v[120:123]
	v_mfma_f32_16x16x32_bf16 v[108:111], v[128:131], v[168:171], v[108:111]
	v_mfma_f32_16x16x32_bf16 v[104:107], v[136:139], v[168:171], v[104:107]
	v_mfma_f32_16x16x32_bf16 v[92:95], v[128:131], v[176:179], v[92:95]
	v_mfma_f32_16x16x32_bf16 v[88:91], v[136:139], v[176:179], v[88:91]
	v_mfma_f32_16x16x32_bf16 v[76:79], v[128:131], v[184:187], v[76:79]
	v_mfma_f32_16x16x32_bf16 v[72:75], v[136:139], v[184:187], v[72:75]
	v_mfma_f32_16x16x32_bf16 v[124:127], v[132:135], v[164:167], v[124:127]
	v_mfma_f32_16x16x32_bf16 v[120:123], v[140:143], v[164:167], v[120:123]
	v_mfma_f32_16x16x32_bf16 v[108:111], v[132:135], v[172:175], v[108:111]
	v_mfma_f32_16x16x32_bf16 v[104:107], v[140:143], v[172:175], v[104:107]
	v_mfma_f32_16x16x32_bf16 v[92:95], v[132:135], v[180:183], v[92:95]
	v_mfma_f32_16x16x32_bf16 v[88:91], v[140:143], v[180:183], v[88:91]
	v_mfma_f32_16x16x32_bf16 v[76:79], v[132:135], v[188:191], v[76:79]
	v_mfma_f32_16x16x32_bf16 v[72:75], v[140:143], v[188:191], v[72:75]
	s_setprio 0
	s_setprio 1
	v_mfma_f32_16x16x32_bf16 v[116:119], v[144:147], v[160:163], v[116:119]
	v_mfma_f32_16x16x32_bf16 v[112:115], v[152:155], v[160:163], v[112:115]
	v_mfma_f32_16x16x32_bf16 v[100:103], v[144:147], v[168:171], v[100:103]
	v_mfma_f32_16x16x32_bf16 v[96:99], v[152:155], v[168:171], v[96:99]
	v_mfma_f32_16x16x32_bf16 v[84:87], v[144:147], v[176:179], v[84:87]
	v_mfma_f32_16x16x32_bf16 v[80:83], v[152:155], v[176:179], v[80:83]
	v_mfma_f32_16x16x32_bf16 v[68:71], v[144:147], v[184:187], v[68:71]
	v_mfma_f32_16x16x32_bf16 v[64:67], v[152:155], v[184:187], v[64:67]
	v_mfma_f32_16x16x32_bf16 v[116:119], v[148:151], v[164:167], v[116:119]
	v_mfma_f32_16x16x32_bf16 v[112:115], v[156:159], v[164:167], v[112:115]
	v_mfma_f32_16x16x32_bf16 v[100:103], v[148:151], v[172:175], v[100:103]
	v_mfma_f32_16x16x32_bf16 v[96:99], v[156:159], v[172:175], v[96:99]
	v_mfma_f32_16x16x32_bf16 v[84:87], v[148:151], v[180:183], v[84:87]
	v_mfma_f32_16x16x32_bf16 v[80:83], v[156:159], v[180:183], v[80:83]
	v_mfma_f32_16x16x32_bf16 v[68:71], v[148:151], v[188:191], v[68:71]
	v_mfma_f32_16x16x32_bf16 v[64:67], v[156:159], v[188:191], v[64:67]
	s_setprio 0
	s_barrier
	s_add_i32 s26, s47, s29
	s_mov_b32 m0, s26
	ds_read_b128 v[160:163], v226 offset:49152
	ds_read_b128 v[164:167], v226 offset:50176
	ds_read_b128 v[168:171], v226 offset:51200
	ds_read_b128 v[172:175], v226 offset:52224
	global_load_lds_dwordx4 v194, vcc
	s_add_i32 m0, s26, 0x2000
	s_add_u32 s24, s24, 0x40080
	s_addc_u32 s25, s25, 0
	s_add_i32 s26, s48, s29
	global_load_lds_dwordx4 v198, vcc
	s_mov_b32 m0, s26
	ds_read_b128 v[188:191], v226 offset:56320
	global_load_lds_dwordx4 v194, s[24:25]
	s_add_i32 m0, s26, 0x2000
	ds_read_b128 v[184:187], v226 offset:55296
	global_load_lds_dwordx4 v198, s[24:25]
	s_mov_b32 m0, s37
	ds_read_b128 v[180:183], v226 offset:54272
	global_load_lds_dwordx4 v192, s[98:99]
	s_mov_b32 m0, s38
	ds_read_b128 v[176:179], v226 offset:53248
	global_load_lds_dwordx4 v196, s[98:99]
	s_waitcnt vmcnt(8)
	s_waitcnt lgkmcnt(0)
	s_barrier
	s_setprio 1
	s_waitcnt lgkmcnt(0)
	v_mfma_f32_16x16x32_bf16 v[60:63], v[128:131], v[160:163], v[60:63]
	v_mfma_f32_16x16x32_bf16 v[56:59], v[136:139], v[160:163], v[56:59]
	v_mfma_f32_16x16x32_bf16 v[44:47], v[128:131], v[168:171], v[44:47]
	v_mfma_f32_16x16x32_bf16 v[40:43], v[136:139], v[168:171], v[40:43]
	v_mfma_f32_16x16x32_bf16 v[28:31], v[128:131], v[176:179], v[28:31]
	v_mfma_f32_16x16x32_bf16 v[24:27], v[136:139], v[176:179], v[24:27]
	v_mfma_f32_16x16x32_bf16 v[12:15], v[128:131], v[184:187], v[12:15]
	v_mfma_f32_16x16x32_bf16 v[8:11], v[136:139], v[184:187], v[8:11]
	v_mfma_f32_16x16x32_bf16 v[60:63], v[132:135], v[164:167], v[60:63]
	v_mfma_f32_16x16x32_bf16 v[56:59], v[140:143], v[164:167], v[56:59]
	v_mfma_f32_16x16x32_bf16 v[44:47], v[132:135], v[172:175], v[44:47]
	v_mfma_f32_16x16x32_bf16 v[40:43], v[140:143], v[172:175], v[40:43]
	v_mfma_f32_16x16x32_bf16 v[28:31], v[132:135], v[180:183], v[28:31]
	v_mfma_f32_16x16x32_bf16 v[24:27], v[140:143], v[180:183], v[24:27]
	v_mfma_f32_16x16x32_bf16 v[12:15], v[132:135], v[188:191], v[12:15]
	v_mfma_f32_16x16x32_bf16 v[8:11], v[140:143], v[188:191], v[8:11]
	s_setprio 0
	s_setprio 1
	v_mfma_f32_16x16x32_bf16 v[52:55], v[144:147], v[160:163], v[52:55]
	v_mfma_f32_16x16x32_bf16 v[48:51], v[152:155], v[160:163], v[48:51]
	v_mfma_f32_16x16x32_bf16 v[36:39], v[144:147], v[168:171], v[36:39]
	v_mfma_f32_16x16x32_bf16 v[32:35], v[152:155], v[168:171], v[32:35]
	v_mfma_f32_16x16x32_bf16 v[20:23], v[144:147], v[176:179], v[20:23]
	v_mfma_f32_16x16x32_bf16 v[16:19], v[152:155], v[176:179], v[16:19]
	v_mfma_f32_16x16x32_bf16 v[4:7], v[144:147], v[184:187], v[4:7]
	v_mfma_f32_16x16x32_bf16 v[0:3], v[152:155], v[184:187], v[0:3]
	v_mfma_f32_16x16x32_bf16 v[52:55], v[148:151], v[164:167], v[52:55]
	v_mfma_f32_16x16x32_bf16 v[48:51], v[156:159], v[164:167], v[48:51]
	v_mfma_f32_16x16x32_bf16 v[36:39], v[148:151], v[172:175], v[36:39]
	v_mfma_f32_16x16x32_bf16 v[32:35], v[156:159], v[172:175], v[32:35]
	v_mfma_f32_16x16x32_bf16 v[20:23], v[148:151], v[180:183], v[20:23]
	v_mfma_f32_16x16x32_bf16 v[16:19], v[156:159], v[180:183], v[16:19]
	v_mfma_f32_16x16x32_bf16 v[4:7], v[148:151], v[188:191], v[4:7]
	v_mfma_f32_16x16x32_bf16 v[0:3], v[156:159], v[188:191], v[0:3]
	s_setprio 0
	s_barrier
	s_mov_b32 s100, 0
	s_add_i32 s46, s46, 2
	s_add_u32 s0, s0, 0x100
	s_addc_u32 s1, s1, 0
	s_add_u32 s44, s44, 0x100
	s_addc_u32 s45, s45, 0
	s_cmp_gt_u32 s46, 13
	s_cbranch_scc0 .LBB0_884
	s_and_b64 vcc, exec, s[8:9]
	s_cbranch_vccz .LBB0_887
	s_barrier

; #define PG8_STAGE(bufoff, gbase, voff) do { _Pragma("unroll") for (int _i = 0; _i < 2; ++_i) \
;         __builtin_amdgcn_global_load_lds((const unsigned*)((const char*)(gbase) + (voff)[_i]), (PG8_LAS unsigned*)(lds + (bufoff) + ldsw + _i * 8192), 16, 0, 0); } while (0)
; #define PG8_LDA(dst, b, h) do { _Pragma("unroll") for (int m = 0; m < 4; ++m) _Pragma("unroll") for (int k = 0; k < 2; ++k) dst[m][k] = *(const PG8_LAS bf16x8*)(lds + PG8_SA(b, h) + aoff + m * 2048 + k * 1024); } while (0)
; #define PG8_LDB(dst, b, h) do { _Pragma("unroll") for (int n = 0; n < 2; ++n) _Pragma("unroll") for (int k = 0; k < 2; ++k) dst[n][k] = *(const PG8_LAS bf16x8*)(lds + PG8_SB(b, h) + boff + n * 2048 + k * 1024); } while (0)
; #define PG8_MMA(ai, bj, At, Bt) do { __builtin_amdgcn_s_setprio(1); _Pragma("unroll") for (int m = 0; m < 4; ++m) _Pragma("unroll") for (int n = 0; n < 2; ++n) _Pragma("unroll") for (int k = 0; k < 2; ++k) \
;         acc[ai][bj][m][n] = __builtin_amdgcn_mfma_f32_16x16x32_bf16(Bt[n][k], At[m][k], acc[ai][bj][m][n], 0, 0, 0); __builtin_amdgcn_s_setprio(0); } while (0)
; #define PG8_WAIT_V(n) asm volatile("s_waitcnt vmcnt(" #n ")" ::: "memory")
; #define PG8_WAIT_L(n) asm volatile("s_waitcnt lgkmcnt(" #n ")" ::: "memory")
; template <class Epi, class Sched, bool ALIGN_EPI = false, bool SP2 = false>
; __device__ __forceinline__ void gemm_phase(PG8_LAS unsigned char* lds, const Gemm g, const Sched& S, const Epi& E) {
;     ...
;             const bool last = (t == nt - 2);
;             const char* a1 = cA + (size_t)(t + 1) * kstep;
;             const char* a2 = last ? nA : cA + (size_t)(t + 2) * kstep; const char* b2 = last ? nB : cB + (size_t)(t + 2) * kstep;
;             const char* a3 = a2 + kstep; const char* b3 = b2 + kstep;
;             if (last && has_next) S.a_ready(nxt);
;             if constexpr (SP2) {
;             PG8_LDB(B0, 0, 0); PG8_LDB(B1, 0, 1); PG8_SCHED; PG8_LDA(At, 0, 0); PG8_STAGE(PG8_SA(1, 1), a1 + hstep, voffA);
;             PG8_WAIT_V(8); PG8_WAIT_L(0); PG8_BAR; PG8_MMA(0, 0, At, B0); PG8_MMA(0, 1, At, B1); PG8_BAR; PG8_SCHED;
;             PG8_LDA(At, 0, 1); PG8_STAGE(PG8_SB(0, 0), b2, voffB); PG8_STAGE(PG8_SB(0, 1), b2 + hstep, voffB); PG8_STAGE(PG8_SA(0, 0), a2, voffA);
;             PG8_WAIT_V(8); PG8_WAIT_L(0); PG8_BAR; PG8_MMA(1, 0, At, B0); PG8_MMA(1, 1, At, B1); PG8_BAR; PG8_SCHED;
.LBB0_993:
	ds_read_b128 v[128:131], v213
	ds_read_b128 v[132:135], v213 offset:1024
	ds_read_b128 v[136:139], v213 offset:2048
	ds_read_b128 v[140:143], v213 offset:3072
	ds_read_b128 v[144:147], v214
	ds_read_b128 v[148:151], v214 offset:1024
	ds_read_b128 v[152:155], v214 offset:2048
	ds_read_b128 v[156:159], v214 offset:3072
	s_add_u32 s28, s26, 0xfff80080
	s_addc_u32 s29, s27, -1
	s_cmp_eq_u32 s48, 28
	s_cselect_b32 s31, s17, s29
	s_cselect_b32 s30, s23, s28
	s_cselect_b32 s29, s15, s47
	s_cselect_b32 s28, s45, s46
	s_add_i32 m0, s25, 0xc000
	ds_read_b128 v[160:163], v215
	ds_read_b128 v[164:167], v215 offset:1024
	ds_read_b128 v[168:171], v215 offset:2048
	ds_read_b128 v[172:175], v215 offset:3072
	ds_read_b128 v[192:195], v215 offset:4096
	ds_read_b128 v[196:199], v215 offset:5120
	ds_read_b128 v[200:203], v215 offset:6144
	global_load_lds_dwordx4 v184, s[26:27]
	s_add_i32 m0, s25, 0xe000
	ds_read_b128 v[204:207], v215 offset:7168
	global_load_lds_dwordx4 v186, s[26:27]
	s_waitcnt vmcnt(8)
	s_waitcnt lgkmcnt(0)
	s_barrier
	s_setprio 1
	s_waitcnt lgkmcnt(0)
	v_mfma_f32_16x16x32_bf16 v[124:127], v[128:131], v[160:163], v[124:127]
	v_mfma_f32_16x16x32_bf16 v[120:123], v[136:139], v[160:163], v[120:123]
	v_mfma_f32_16x16x32_bf16 v[108:111], v[128:131], v[168:171], v[108:111]
	v_mfma_f32_16x16x32_bf16 v[104:107], v[136:139], v[168:171], v[104:107]
	v_mfma_f32_16x16x32_bf16 v[92:95], v[128:131], v[192:195], v[92:95]
	v_mfma_f32_16x16x32_bf16 v[88:91], v[136:139], v[192:195], v[88:91]
	v_mfma_f32_16x16x32_bf16 v[76:79], v[128:131], v[200:203], v[76:79]
	v_mfma_f32_16x16x32_bf16 v[72:75], v[136:139], v[200:203], v[72:75]
	v_mfma_f32_16x16x32_bf16 v[124:127], v[132:135], v[164:167], v[124:127]
	v_mfma_f32_16x16x32_bf16 v[120:123], v[140:143], v[164:167], v[120:123]
	v_mfma_f32_16x16x32_bf16 v[108:111], v[132:135], v[172:175], v[108:111]
	v_mfma_f32_16x16x32_bf16 v[104:107], v[140:143], v[172:175], v[104:107]
	v_mfma_f32_16x16x32_bf16 v[92:95], v[132:135], v[196:199], v[92:95]
	v_mfma_f32_16x16x32_bf16 v[88:91], v[140:143], v[196:199], v[88:91]
	v_mfma_f32_16x16x32_bf16 v[76:79], v[132:135], v[204:207], v[76:79]
	v_mfma_f32_16x16x32_bf16 v[72:75], v[140:143], v[204:207], v[72:75]
	s_setprio 0
	s_setprio 1
	v_mfma_f32_16x16x32_bf16 v[116:119], v[144:147], v[160:163], v[116:119]
	v_mfma_f32_16x16x32_bf16 v[112:115], v[152:155], v[160:163], v[112:115]
	v_mfma_f32_16x16x32_bf16 v[100:103], v[144:147], v[168:171], v[100:103]
	v_mfma_f32_16x16x32_bf16 v[96:99], v[152:155], v[168:171], v[96:99]
	v_mfma_f32_16x16x32_bf16 v[84:87], v[144:147], v[192:195], v[84:87]
	v_mfma_f32_16x16x32_bf16 v[80:83], v[152:155], v[192:195], v[80:83]
	v_mfma_f32_16x16x32_bf16 v[68:71], v[144:147], v[200:203], v[68:71]
	v_mfma_f32_16x16x32_bf16 v[64:67], v[152:155], v[200:203], v[64:67]
	v_mfma_f32_16x16x32_bf16 v[116:119], v[148:151], v[164:167], v[116:119]
	v_mfma_f32_16x16x32_bf16 v[112:115], v[156:159], v[164:167], v[112:115]
	v_mfma_f32_16x16x32_bf16 v[100:103], v[148:151], v[172:175], v[100:103]
	v_mfma_f32_16x16x32_bf16 v[96:99], v[156:159], v[172:175], v[96:99]
	v_mfma_f32_16x16x32_bf16 v[84:87], v[148:151], v[196:199], v[84:87]
	v_mfma_f32_16x16x32_bf16 v[80:83], v[156:159], v[196:199], v[80:83]
	v_mfma_f32_16x16x32_bf16 v[68:71], v[148:151], v[204:207], v[68:71]
	v_mfma_f32_16x16x32_bf16 v[64:67], v[156:159], v[204:207], v[64:67]
	s_setprio 0
	s_barrier
	s_add_i32 s49, s43, s33
	s_add_u32 vcc_lo, s28, 0x80
	s_addc_u32 vcc_hi, s29, 0
	s_mov_b32 m0, s49
	ds_read_b128 v[160:163], v215 offset:16384
	ds_read_b128 v[164:167], v215 offset:17408
	ds_read_b128 v[168:171], v215 offset:18432
	ds_read_b128 v[172:175], v215 offset:19456
	global_load_lds_dwordx4 v178, s[28:29]
	s_add_i32 m0, s49, 0x2000
	s_add_u32 s50, s28, 0x80000
	s_addc_u32 s51, s29, 0
	s_add_i32 s49, s44, s33
	global_load_lds_dwordx4 v182, s[28:29]
	s_mov_b32 m0, s49
	ds_read_b128 v[204:207], v215 offset:23552
	global_load_lds_dwordx4 v178, s[50:51]
	s_add_i32 m0, s49, 0x2000
	ds_read_b128 v[200:203], v215 offset:22528
	global_load_lds_dwordx4 v182, s[50:51]
	s_add_u32 s98, s30, 0x80
	s_addc_u32 s99, s31, 0
	s_mov_b32 m0, s25
	ds_read_b128 v[196:199], v215 offset:21504
	global_load_lds_dwordx4 v176, s[30:31]
	s_mov_b32 m0, s34
	ds_read_b128 v[192:195], v215 offset:20480
	global_load_lds_dwordx4 v180, s[30:31]
	s_waitcnt vmcnt(8)
	s_waitcnt lgkmcnt(0)
	s_barrier
	s_setprio 1
	s_waitcnt lgkmcnt(0)
	v_mfma_f32_16x16x32_bf16 v[60:63], v[128:131], v[160:163], v[60:63]
	v_mfma_f32_16x16x32_bf16 v[56:59], v[136:139], v[160:163], v[56:59]
	v_mfma_f32_16x16x32_bf16 v[44:47], v[128:131], v[168:171], v[44:47]
	v_mfma_f32_16x16x32_bf16 v[40:43], v[136:139], v[168:171], v[40:43]
	v_mfma_f32_16x16x32_bf16 v[28:31], v[128:131], v[192:195], v[28:31]
	v_mfma_f32_16x16x32_bf16 v[24:27], v[136:139], v[192:195], v[24:27]
	v_mfma_f32_16x16x32_bf16 v[12:15], v[128:131], v[200:203], v[12:15]
	v_mfma_f32_16x16x32_bf16 v[8:11], v[136:139], v[200:203], v[8:11]
	v_mfma_f32_16x16x32_bf16 v[60:63], v[132:135], v[164:167], v[60:63]
	v_mfma_f32_16x16x32_bf16 v[56:59], v[140:143], v[164:167], v[56:59]
	v_mfma_f32_16x16x32_bf16 v[44:47], v[132:135], v[172:175], v[44:47]
	v_mfma_f32_16x16x32_bf16 v[40:43], v[140:143], v[172:175], v[40:43]
	v_mfma_f32_16x16x32_bf16 v[28:31], v[132:135], v[196:199], v[28:31]
	v_mfma_f32_16x16x32_bf16 v[24:27], v[140:143], v[196:199], v[24:27]
	v_mfma_f32_16x16x32_bf16 v[12:15], v[132:135], v[204:207], v[12:15]
	v_mfma_f32_16x16x32_bf16 v[8:11], v[140:143], v[204:207], v[8:11]
	s_setprio 0
	s_setprio 1
	v_mfma_f32_16x16x32_bf16 v[52:55], v[144:147], v[160:163], v[52:55]
	v_mfma_f32_16x16x32_bf16 v[48:51], v[152:155], v[160:163], v[48:51]
	v_mfma_f32_16x16x32_bf16 v[36:39], v[144:147], v[168:171], v[36:39]
	v_mfma_f32_16x16x32_bf16 v[32:35], v[152:155], v[168:171], v[32:35]
	v_mfma_f32_16x16x32_bf16 v[20:23], v[144:147], v[192:195], v[20:23]
	v_mfma_f32_16x16x32_bf16 v[16:19], v[152:155], v[192:195], v[16:19]
	v_mfma_f32_16x16x32_bf16 v[4:7], v[144:147], v[200:203], v[4:7]
	v_mfma_f32_16x16x32_bf16 v[0:3], v[152:155], v[200:203], v[0:3]
	v_mfma_f32_16x16x32_bf16 v[52:55], v[148:151], v[164:167], v[52:55]
	v_mfma_f32_16x16x32_bf16 v[48:51], v[156:159], v[164:167], v[48:51]
	v_mfma_f32_16x16x32_bf16 v[36:39], v[148:151], v[172:175], v[36:39]
	v_mfma_f32_16x16x32_bf16 v[32:35], v[156:159], v[172:175], v[32:35]
	v_mfma_f32_16x16x32_bf16 v[20:23], v[148:151], v[196:199], v[20:23]
	v_mfma_f32_16x16x32_bf16 v[16:19], v[156:159], v[196:199], v[16:19]
	v_mfma_f32_16x16x32_bf16 v[4:7], v[148:151], v[204:207], v[4:7]
	v_mfma_f32_16x16x32_bf16 v[0:3], v[156:159], v[204:207], v[0:3]
	s_setprio 0
	s_barrier
; #define PG8_STAGE(bufoff, gbase, voff) do { _Pragma("unroll") for (int _i = 0; _i < 2; ++_i) \
;         __builtin_amdgcn_global_load_lds((const unsigned*)((const char*)(gbase) + (voff)[_i]), (PG8_LAS unsigned*)(lds + (bufoff) + ldsw + _i * 8192), 16, 0, 0); } while (0)
; #define PG8_LDA(dst, b, h) do { _Pragma("unroll") for (int m = 0; m < 4; ++m) _Pragma("unroll") for (int k = 0; k < 2; ++k) dst[m][k] = *(const PG8_LAS bf16x8*)(lds + PG8_SA(b, h) + aoff + m * 2048 + k * 1024); } while (0)
; #define PG8_LDB(dst, b, h) do { _Pragma("unroll") for (int n = 0; n < 2; ++n) _Pragma("unroll") for (int k = 0; k < 2; ++k) dst[n][k] = *(const PG8_LAS bf16x8*)(lds + PG8_SB(b, h) + boff + n * 2048 + k * 1024); } while (0)
; #define PG8_MMA(ai, bj, At, Bt) do { __builtin_amdgcn_s_setprio(1); _Pragma("unroll") for (int m = 0; m < 4; ++m) _Pragma("unroll") for (int n = 0; n < 2; ++n) _Pragma("unroll") for (int k = 0; k < 2; ++k) \
;         acc[ai][bj][m][n] = __builtin_amdgcn_mfma_f32_16x16x32_bf16(Bt[n][k], At[m][k], acc[ai][bj][m][n], 0, 0, 0); __builtin_amdgcn_s_setprio(0); } while (0)
; #define PG8_WAIT_V(n) asm volatile("s_waitcnt vmcnt(" #n ")" ::: "memory")
; #define PG8_WAIT_L(n) asm volatile("s_waitcnt lgkmcnt(" #n ")" ::: "memory")
; #define PG8_BAR __builtin_amdgcn_s_barrier()
; #define PG8_SCHED __builtin_amdgcn_sched_barrier(0)
; template <class Epi, class Sched, bool ALIGN_EPI = false, bool SP2 = false>
; __device__ __forceinline__ void gemm_phase(PG8_LAS unsigned char* lds, const Gemm g, const Sched& S, const Epi& E) {
;     ...
;             PG8_LDB(B0, 1, 0); PG8_LDB(B1, 1, 1); PG8_SCHED; PG8_LDA(At, 1, 0); PG8_STAGE(PG8_SA(0, 1), a2 + hstep, voffA);
;             PG8_WAIT_V(8); PG8_WAIT_L(0); PG8_BAR; PG8_MMA(0, 0, At, B0); PG8_MMA(0, 1, At, B1); PG8_BAR; PG8_SCHED;
;             PG8_LDA(At, 1, 1); PG8_STAGE(PG8_SB(1, 0), b3, voffB); PG8_STAGE(PG8_SB(1, 1), b3 + hstep, voffB); PG8_STAGE(PG8_SA(1, 0), a3, voffA);
;             PG8_WAIT_V(8); PG8_WAIT_L(0); PG8_BAR; PG8_MMA(1, 0, At, B0); PG8_MMA(1, 1, At, B1); PG8_BAR; PG8_SCHED;
	s_add_i32 s49, 0, 0x18000
	s_add_i32 s50, 0, 0x1c000
	v_add_u32_e32 v140, s49, v211
	v_add_u32_e32 v156, s50, v211
	ds_read_b128 v[128:131], v140
	ds_read_b128 v[132:135], v140 offset:1024
	ds_read_b128 v[136:139], v140 offset:2048
	ds_read_b128 v[140:143], v140 offset:3072
	ds_read_b128 v[144:147], v156
	ds_read_b128 v[148:151], v156 offset:1024
	ds_read_b128 v[152:155], v156 offset:2048
	ds_read_b128 v[156:159], v156 offset:3072
	s_add_u32 s30, s30, 0x80000
	s_addc_u32 s31, s31, 0
	s_mov_b32 m0, s35
	ds_read_b128 v[160:163], v215 offset:32768
	ds_read_b128 v[164:167], v215 offset:33792
	ds_read_b128 v[168:171], v215 offset:34816
	ds_read_b128 v[172:175], v215 offset:35840
	ds_read_b128 v[192:195], v215 offset:36864
	ds_read_b128 v[196:199], v215 offset:37888
	ds_read_b128 v[200:203], v215 offset:38912
	global_load_lds_dwordx4 v176, s[30:31]
	s_mov_b32 m0, s36
	ds_read_b128 v[204:207], v215 offset:39936
	global_load_lds_dwordx4 v180, s[30:31]
	s_waitcnt vmcnt(8)
	s_waitcnt lgkmcnt(0)
	s_barrier
	s_setprio 1
	s_waitcnt lgkmcnt(0)
	v_mfma_f32_16x16x32_bf16 v[124:127], v[128:131], v[160:163], v[124:127]
	v_mfma_f32_16x16x32_bf16 v[120:123], v[136:139], v[160:163], v[120:123]
	v_mfma_f32_16x16x32_bf16 v[108:111], v[128:131], v[168:171], v[108:111]
	v_mfma_f32_16x16x32_bf16 v[104:107], v[136:139], v[168:171], v[104:107]
	v_mfma_f32_16x16x32_bf16 v[92:95], v[128:131], v[192:195], v[92:95]
	v_mfma_f32_16x16x32_bf16 v[88:91], v[136:139], v[192:195], v[88:91]
	v_mfma_f32_16x16x32_bf16 v[76:79], v[128:131], v[200:203], v[76:79]
	v_mfma_f32_16x16x32_bf16 v[72:75], v[136:139], v[200:203], v[72:75]
	v_mfma_f32_16x16x32_bf16 v[124:127], v[132:135], v[164:167], v[124:127]
	v_mfma_f32_16x16x32_bf16 v[120:123], v[140:143], v[164:167], v[120:123]
	v_mfma_f32_16x16x32_bf16 v[108:111], v[132:135], v[172:175], v[108:111]
	v_mfma_f32_16x16x32_bf16 v[104:107], v[140:143], v[172:175], v[104:107]
	v_mfma_f32_16x16x32_bf16 v[92:95], v[132:135], v[196:199], v[92:95]
	v_mfma_f32_16x16x32_bf16 v[88:91], v[140:143], v[196:199], v[88:91]
	v_mfma_f32_16x16x32_bf16 v[76:79], v[132:135], v[204:207], v[76:79]
	v_mfma_f32_16x16x32_bf16 v[72:75], v[140:143], v[204:207], v[72:75]
	s_setprio 0
	s_setprio 1
	v_mfma_f32_16x16x32_bf16 v[116:119], v[144:147], v[160:163], v[116:119]
	v_mfma_f32_16x16x32_bf16 v[112:115], v[152:155], v[160:163], v[112:115]
	v_mfma_f32_16x16x32_bf16 v[100:103], v[144:147], v[168:171], v[100:103]
	v_mfma_f32_16x16x32_bf16 v[96:99], v[152:155], v[168:171], v[96:99]
	v_mfma_f32_16x16x32_bf16 v[84:87], v[144:147], v[192:195], v[84:87]
	v_mfma_f32_16x16x32_bf16 v[80:83], v[152:155], v[192:195], v[80:83]
	v_mfma_f32_16x16x32_bf16 v[68:71], v[144:147], v[200:203], v[68:71]
	v_mfma_f32_16x16x32_bf16 v[64:67], v[152:155], v[200:203], v[64:67]
	v_mfma_f32_16x16x32_bf16 v[116:119], v[148:151], v[164:167], v[116:119]
	v_mfma_f32_16x16x32_bf16 v[112:115], v[156:159], v[164:167], v[112:115]
	v_mfma_f32_16x16x32_bf16 v[100:103], v[148:151], v[172:175], v[100:103]
	v_mfma_f32_16x16x32_bf16 v[96:99], v[156:159], v[172:175], v[96:99]
	v_mfma_f32_16x16x32_bf16 v[84:87], v[148:151], v[196:199], v[84:87]
	v_mfma_f32_16x16x32_bf16 v[80:83], v[156:159], v[196:199], v[80:83]
	v_mfma_f32_16x16x32_bf16 v[68:71], v[148:151], v[204:207], v[68:71]
	v_mfma_f32_16x16x32_bf16 v[64:67], v[156:159], v[204:207], v[64:67]
	s_setprio 0
	s_barrier
	s_add_i32 s30, s49, s33
	s_mov_b32 m0, s30
	ds_read_b128 v[160:163], v215 offset:49152
	ds_read_b128 v[164:167], v215 offset:50176
	ds_read_b128 v[168:171], v215 offset:51200
	ds_read_b128 v[172:175], v215 offset:52224
	global_load_lds_dwordx4 v178, vcc
	s_add_i32 m0, s30, 0x2000
	s_add_u32 s28, s28, 0x80080
	s_addc_u32 s29, s29, 0
	s_add_i32 s30, s50, s33
	global_load_lds_dwordx4 v182, vcc
	s_mov_b32 m0, s30
	ds_read_b128 v[204:207], v215 offset:56320
	global_load_lds_dwordx4 v178, s[28:29]
	s_add_i32 m0, s30, 0x2000
	ds_read_b128 v[200:203], v215 offset:55296
	global_load_lds_dwordx4 v182, s[28:29]
	s_mov_b32 m0, s38
	ds_read_b128 v[196:199], v215 offset:54272
	global_load_lds_dwordx4 v176, s[98:99]
	s_mov_b32 m0, s39
	ds_read_b128 v[192:195], v215 offset:53248
	global_load_lds_dwordx4 v180, s[98:99]
	s_waitcnt vmcnt(8)
	s_waitcnt lgkmcnt(0)
	s_barrier
	s_setprio 1
	s_waitcnt lgkmcnt(0)
	v_mfma_f32_16x16x32_bf16 v[60:63], v[128:131], v[160:163], v[60:63]
	v_mfma_f32_16x16x32_bf16 v[56:59], v[136:139], v[160:163], v[56:59]
	v_mfma_f32_16x16x32_bf16 v[44:47], v[128:131], v[168:171], v[44:47]
	v_mfma_f32_16x16x32_bf16 v[40:43], v[136:139], v[168:171], v[40:43]
	v_mfma_f32_16x16x32_bf16 v[28:31], v[128:131], v[192:195], v[28:31]
	v_mfma_f32_16x16x32_bf16 v[24:27], v[136:139], v[192:195], v[24:27]
	v_mfma_f32_16x16x32_bf16 v[12:15], v[128:131], v[200:203], v[12:15]
	v_mfma_f32_16x16x32_bf16 v[8:11], v[136:139], v[200:203], v[8:11]
	v_mfma_f32_16x16x32_bf16 v[60:63], v[132:135], v[164:167], v[60:63]
	v_mfma_f32_16x16x32_bf16 v[56:59], v[140:143], v[164:167], v[56:59]
	v_mfma_f32_16x16x32_bf16 v[44:47], v[132:135], v[172:175], v[44:47]
	v_mfma_f32_16x16x32_bf16 v[40:43], v[140:143], v[172:175], v[40:43]
	v_mfma_f32_16x16x32_bf16 v[28:31], v[132:135], v[196:199], v[28:31]
	v_mfma_f32_16x16x32_bf16 v[24:27], v[140:143], v[196:199], v[24:27]
	v_mfma_f32_16x16x32_bf16 v[12:15], v[132:135], v[204:207], v[12:15]
	v_mfma_f32_16x16x32_bf16 v[8:11], v[140:143], v[204:207], v[8:11]
	s_setprio 0
	s_setprio 1
	v_mfma_f32_16x16x32_bf16 v[52:55], v[144:147], v[160:163], v[52:55]
	v_mfma_f32_16x16x32_bf16 v[48:51], v[152:155], v[160:163], v[48:51]
	v_mfma_f32_16x16x32_bf16 v[36:39], v[144:147], v[168:171], v[36:39]
	v_mfma_f32_16x16x32_bf16 v[32:35], v[152:155], v[168:171], v[32:35]
	v_mfma_f32_16x16x32_bf16 v[20:23], v[144:147], v[192:195], v[20:23]
	v_mfma_f32_16x16x32_bf16 v[16:19], v[152:155], v[192:195], v[16:19]
	v_mfma_f32_16x16x32_bf16 v[4:7], v[144:147], v[200:203], v[4:7]
	v_mfma_f32_16x16x32_bf16 v[0:3], v[152:155], v[200:203], v[0:3]
	v_mfma_f32_16x16x32_bf16 v[52:55], v[148:151], v[164:167], v[52:55]
	v_mfma_f32_16x16x32_bf16 v[48:51], v[156:159], v[164:167], v[48:51]
	v_mfma_f32_16x16x32_bf16 v[36:39], v[148:151], v[172:175], v[36:39]
	v_mfma_f32_16x16x32_bf16 v[32:35], v[156:159], v[172:175], v[32:35]
	v_mfma_f32_16x16x32_bf16 v[20:23], v[148:151], v[196:199], v[20:23]
	v_mfma_f32_16x16x32_bf16 v[16:19], v[156:159], v[196:199], v[16:19]
	v_mfma_f32_16x16x32_bf16 v[4:7], v[148:151], v[204:207], v[4:7]
	v_mfma_f32_16x16x32_bf16 v[0:3], v[156:159], v[204:207], v[0:3]
	s_setprio 0
	s_barrier
	s_add_i32 s48, s48, 2
	s_add_u32 s26, s26, 0x100
	s_addc_u32 s27, s27, 0
	s_add_u32 s46, s46, 0x100
	s_addc_u32 s47, s47, 0
	s_cmp_gt_u32 s48, 29
	s_cbranch_scc0 .LBB0_993
	s_and_b64 vcc, exec, s[12:13]
	s_cbranch_vccz .LBB0_996
	s_barrier

; #define PG8_STAGE(bufoff, gbase, voff) do { _Pragma("unroll") for (int _i = 0; _i < 2; ++_i) \
;         __builtin_amdgcn_global_load_lds((const unsigned*)((const char*)(gbase) + (voff)[_i]), (PG8_LAS unsigned*)(lds + (bufoff) + ldsw + _i * 8192), 16, 0, 0); } while (0)
; #define PG8_LDA(dst, b, h) do { _Pragma("unroll") for (int m = 0; m < 4; ++m) _Pragma("unroll") for (int k = 0; k < 2; ++k) dst[m][k] = *(const PG8_LAS bf16x8*)(lds + PG8_SA(b, h) + aoff + m * 2048 + k * 1024); } while (0)
; #define PG8_LDB(dst, b, h) do { _Pragma("unroll") for (int n = 0; n < 2; ++n) _Pragma("unroll") for (int k = 0; k < 2; ++k) dst[n][k] = *(const PG8_LAS bf16x8*)(lds + PG8_SB(b, h) + boff + n * 2048 + k * 1024); } while (0)
; #define PG8_MMA(ai, bj, At, Bt) do { __builtin_amdgcn_s_setprio(1); _Pragma("unroll") for (int m = 0; m < 4; ++m) _Pragma("unroll") for (int n = 0; n < 2; ++n) _Pragma("unroll") for (int k = 0; k < 2; ++k) \
;         acc[ai][bj][m][n] = __builtin_amdgcn_mfma_f32_16x16x32_bf16(Bt[n][k], At[m][k], acc[ai][bj][m][n], 0, 0, 0); __builtin_amdgcn_s_setprio(0); } while (0)
; #define PG8_WAIT_V(n) asm volatile("s_waitcnt vmcnt(" #n ")" ::: "memory")
; #define PG8_WAIT_L(n) asm volatile("s_waitcnt lgkmcnt(" #n ")" ::: "memory")
; #define PG8_BAR __builtin_amdgcn_s_barrier()
; #define PG8_SCHED __builtin_amdgcn_sched_barrier(0)
; template <class Epi, class Sched, bool ALIGN_EPI = false, bool SP2 = false>
; __device__ __forceinline__ void gemm_phase(PG8_LAS unsigned char* lds, const Gemm g, const Sched& S, const Epi& E) {
;     ...
;             PG8_WAIT_V(8); PG8_WAIT_L(0); PG8_BAR; PG8_MMA(0, 0, At, B0); PG8_MMA(0, 1, At, B1); PG8_BAR; PG8_SCHED;
;             PG8_LDA(At, 0, 1); PG8_STAGE(PG8_SB(0, 0), b2, voffB); PG8_STAGE(PG8_SB(0, 1), b2 + hstep, voffB); PG8_STAGE(PG8_SA(0, 0), a2, voffA);
;             PG8_WAIT_V(8); PG8_WAIT_L(0); PG8_BAR; PG8_MMA(1, 0, At, B0); PG8_MMA(1, 1, At, B1); PG8_BAR; PG8_SCHED;
;             PG8_LDB(B0, 1, 0); PG8_LDB(B1, 1, 1); PG8_SCHED; PG8_LDA(At, 1, 0); PG8_STAGE(PG8_SA(0, 1), a2 + hstep, voffA);
.Lgr_p7_0:
	s_waitcnt lgkmcnt(0)
	s_barrier
	s_setprio 1
	s_waitcnt lgkmcnt(0)
	v_mfma_f32_16x16x32_bf16 v[116:119], v[166:169], v[198:201], v[116:119]
	v_mfma_f32_16x16x32_bf16 v[112:115], v[174:177], v[198:201], v[112:115]
	v_mfma_f32_16x16x32_bf16 v[108:111], v[166:169], v[206:209], v[108:111]
	v_mfma_f32_16x16x32_bf16 v[100:103], v[174:177], v[206:209], v[100:103]
	v_mfma_f32_16x16x32_bf16 v[92:95], v[166:169], v[214:217], v[92:95]
	v_mfma_f32_16x16x32_bf16 v[84:87], v[174:177], v[214:217], v[84:87]
	v_mfma_f32_16x16x32_bf16 v[76:79], v[166:169], v[226:229], v[76:79]
	v_mfma_f32_16x16x32_bf16 v[68:71], v[174:177], v[226:229], v[68:71]
	v_mfma_f32_16x16x32_bf16 v[116:119], v[170:173], v[202:205], v[116:119]
	v_mfma_f32_16x16x32_bf16 v[112:115], v[178:181], v[202:205], v[112:115]
	v_mfma_f32_16x16x32_bf16 v[108:111], v[170:173], v[210:213], v[108:111]
	v_mfma_f32_16x16x32_bf16 v[100:103], v[178:181], v[210:213], v[100:103]
	v_mfma_f32_16x16x32_bf16 v[92:95], v[170:173], v[222:225], v[92:95]
	v_mfma_f32_16x16x32_bf16 v[84:87], v[178:181], v[222:225], v[84:87]
	v_mfma_f32_16x16x32_bf16 v[76:79], v[170:173], v[230:233], v[76:79]
	v_mfma_f32_16x16x32_bf16 v[68:71], v[178:181], v[230:233], v[68:71]
	s_setprio 0
	s_setprio 1
	v_mfma_f32_16x16x32_bf16 v[124:127], v[182:185], v[198:201], v[124:127]
	v_mfma_f32_16x16x32_bf16 v[120:123], v[190:193], v[198:201], v[120:123]
	v_mfma_f32_16x16x32_bf16 v[104:107], v[182:185], v[206:209], v[104:107]
	v_mfma_f32_16x16x32_bf16 v[96:99], v[190:193], v[206:209], v[96:99]
	v_mfma_f32_16x16x32_bf16 v[88:91], v[182:185], v[214:217], v[88:91]
	v_mfma_f32_16x16x32_bf16 v[80:83], v[190:193], v[214:217], v[80:83]
	v_mfma_f32_16x16x32_bf16 v[72:75], v[182:185], v[226:229], v[72:75]
	v_mfma_f32_16x16x32_bf16 v[64:67], v[190:193], v[226:229], v[64:67]
	v_mfma_f32_16x16x32_bf16 v[124:127], v[186:189], v[202:205], v[124:127]
	v_mfma_f32_16x16x32_bf16 v[120:123], v[194:197], v[202:205], v[120:123]
	v_mfma_f32_16x16x32_bf16 v[104:107], v[186:189], v[210:213], v[104:107]
	v_mfma_f32_16x16x32_bf16 v[96:99], v[194:197], v[210:213], v[96:99]
	v_mfma_f32_16x16x32_bf16 v[88:91], v[186:189], v[222:225], v[88:91]
	v_mfma_f32_16x16x32_bf16 v[80:83], v[194:197], v[222:225], v[80:83]
	v_mfma_f32_16x16x32_bf16 v[72:75], v[186:189], v[230:233], v[72:75]
	v_mfma_f32_16x16x32_bf16 v[64:67], v[194:197], v[230:233], v[64:67]
	s_setprio 0
	s_barrier
	s_add_i32 s52, s43, s30
	s_add_u32 vcc_lo, s26, 0x80
	s_addc_u32 vcc_hi, s27, 0
	s_mov_b32 m0, s52
	ds_read_b128 v[198:201], v164 offset:16384
	ds_read_b128 v[202:205], v164 offset:17408
	ds_read_b128 v[206:209], v164 offset:18432
	ds_read_b128 v[210:213], v164 offset:19456
	global_load_lds_dwordx4 v132, s[26:27]
	s_add_i32 m0, s52, 0x2000
	s_add_u32 s52, s26, 0x80000
	s_addc_u32 s53, s27, 0
	s_add_i32 s54, s44, s30
	global_load_lds_dwordx4 v128, s[26:27]
	s_mov_b32 m0, s54
	ds_read_b128 v[230:233], v164 offset:23552
	global_load_lds_dwordx4 v132, s[52:53]
	s_add_i32 m0, s54, 0x2000
	ds_read_b128 v[226:229], v164 offset:22528
	global_load_lds_dwordx4 v128, s[52:53]
	s_add_u32 s98, s28, 0x80
	s_addc_u32 s99, s29, 0
	s_mov_b32 m0, s34
	ds_read_b128 v[222:225], v164 offset:21504
	global_load_lds_dwordx4 v134, s[28:29]
	s_mov_b32 m0, s35
	ds_read_b128 v[214:217], v164 offset:20480
	global_load_lds_dwordx4 v130, s[28:29]
	s_cmp_lg_u32 s100, 0
	s_cbranch_scc1 .Lgr_p7_1
	s_waitcnt vmcnt(8)
.Lgr_p7_1:
	s_waitcnt lgkmcnt(0)
	s_barrier
	s_setprio 1
	s_waitcnt lgkmcnt(0)
	v_mfma_f32_16x16x32_bf16 v[60:63], v[166:169], v[198:201], v[60:63]
	v_mfma_f32_16x16x32_bf16 v[52:55], v[174:177], v[198:201], v[52:55]
	v_mfma_f32_16x16x32_bf16 v[44:47], v[166:169], v[206:209], v[44:47]
	v_mfma_f32_16x16x32_bf16 v[36:39], v[174:177], v[206:209], v[36:39]
	v_mfma_f32_16x16x32_bf16 v[28:31], v[166:169], v[214:217], v[28:31]
	v_mfma_f32_16x16x32_bf16 v[20:23], v[174:177], v[214:217], v[20:23]
	v_mfma_f32_16x16x32_bf16 v[12:15], v[166:169], v[226:229], v[12:15]
	v_mfma_f32_16x16x32_bf16 v[4:7], v[174:177], v[226:229], v[4:7]
	v_mfma_f32_16x16x32_bf16 v[60:63], v[170:173], v[202:205], v[60:63]
	v_mfma_f32_16x16x32_bf16 v[52:55], v[178:181], v[202:205], v[52:55]
	v_mfma_f32_16x16x32_bf16 v[44:47], v[170:173], v[210:213], v[44:47]
	v_mfma_f32_16x16x32_bf16 v[36:39], v[178:181], v[210:213], v[36:39]
	v_mfma_f32_16x16x32_bf16 v[28:31], v[170:173], v[222:225], v[28:31]
	v_mfma_f32_16x16x32_bf16 v[20:23], v[178:181], v[222:225], v[20:23]
	v_mfma_f32_16x16x32_bf16 v[12:15], v[170:173], v[230:233], v[12:15]
	v_mfma_f32_16x16x32_bf16 v[4:7], v[178:181], v[230:233], v[4:7]
	s_setprio 0
	s_setprio 1
	v_mfma_f32_16x16x32_bf16 v[56:59], v[182:185], v[198:201], v[56:59]
	v_mfma_f32_16x16x32_bf16 v[48:51], v[190:193], v[198:201], v[48:51]
	v_mfma_f32_16x16x32_bf16 v[40:43], v[182:185], v[206:209], v[40:43]
	v_mfma_f32_16x16x32_bf16 v[32:35], v[190:193], v[206:209], v[32:35]
	v_mfma_f32_16x16x32_bf16 v[24:27], v[182:185], v[214:217], v[24:27]
	v_mfma_f32_16x16x32_bf16 v[16:19], v[190:193], v[214:217], v[16:19]
	v_mfma_f32_16x16x32_bf16 v[8:11], v[182:185], v[226:229], v[8:11]
	v_mfma_f32_16x16x32_bf16 v[0:3], v[190:193], v[226:229], v[0:3]
	v_mfma_f32_16x16x32_bf16 v[56:59], v[186:189], v[202:205], v[56:59]
	v_mfma_f32_16x16x32_bf16 v[48:51], v[194:197], v[202:205], v[48:51]
	v_mfma_f32_16x16x32_bf16 v[40:43], v[186:189], v[210:213], v[40:43]
	v_mfma_f32_16x16x32_bf16 v[32:35], v[194:197], v[210:213], v[32:35]
	v_mfma_f32_16x16x32_bf16 v[24:27], v[186:189], v[222:225], v[24:27]
	v_mfma_f32_16x16x32_bf16 v[16:19], v[194:197], v[222:225], v[16:19]
	v_mfma_f32_16x16x32_bf16 v[8:11], v[186:189], v[230:233], v[8:11]
	v_mfma_f32_16x16x32_bf16 v[0:3], v[194:197], v[230:233], v[0:3]
	s_setprio 0
	s_barrier
	s_add_i32 s52, 0, 0x18000
	s_add_i32 s53, 0, 0x1c000
	v_add_u32_e32 v178, s52, v160
	v_add_u32_e32 v194, s53, v160
	ds_read_b128 v[166:169], v178
	ds_read_b128 v[170:173], v178 offset:1024
	ds_read_b128 v[174:177], v178 offset:2048
	ds_read_b128 v[178:181], v178 offset:3072
	ds_read_b128 v[182:185], v194
	ds_read_b128 v[186:189], v194 offset:1024
	ds_read_b128 v[190:193], v194 offset:2048
	ds_read_b128 v[194:197], v194 offset:3072
	s_add_u32 s28, s28, 0x80000
	s_addc_u32 s29, s29, 0
	s_mov_b32 m0, s36
	ds_read_b128 v[198:201], v164 offset:32768
	ds_read_b128 v[202:205], v164 offset:33792
	ds_read_b128 v[206:209], v164 offset:34816
	ds_read_b128 v[210:213], v164 offset:35840
	ds_read_b128 v[214:217], v164 offset:36864
	ds_read_b128 v[222:225], v164 offset:37888
	ds_read_b128 v[226:229], v164 offset:38912
	global_load_lds_dwordx4 v134, s[28:29]
	s_mov_b32 m0, s37
	ds_read_b128 v[230:233], v164 offset:39936
	global_load_lds_dwordx4 v130, s[28:29]
	s_cmp_lg_u32 s100, 0
	s_cbranch_scc1 .Lgr_p7_2
	s_waitcnt vmcnt(8)
; #define PG8_STAGE(bufoff, gbase, voff) do { _Pragma("unroll") for (int _i = 0; _i < 2; ++_i) \
;         __builtin_amdgcn_global_load_lds((const unsigned*)((const char*)(gbase) + (voff)[_i]), (PG8_LAS unsigned*)(lds + (bufoff) + ldsw + _i * 8192), 16, 0, 0); } while (0)
; #define PG8_LDA(dst, b, h) do { _Pragma("unroll") for (int m = 0; m < 4; ++m) _Pragma("unroll") for (int k = 0; k < 2; ++k) dst[m][k] = *(const PG8_LAS bf16x8*)(lds + PG8_SA(b, h) + aoff + m * 2048 + k * 1024); } while (0)
; #define PG8_MMA(ai, bj, At, Bt) do { __builtin_amdgcn_s_setprio(1); _Pragma("unroll") for (int m = 0; m < 4; ++m) _Pragma("unroll") for (int n = 0; n < 2; ++n) _Pragma("unroll") for (int k = 0; k < 2; ++k) \
;         acc[ai][bj][m][n] = __builtin_amdgcn_mfma_f32_16x16x32_bf16(Bt[n][k], At[m][k], acc[ai][bj][m][n], 0, 0, 0); __builtin_amdgcn_s_setprio(0); } while (0)
; #define PG8_WAIT_V(n) asm volatile("s_waitcnt vmcnt(" #n ")" ::: "memory")
; #define PG8_WAIT_L(n) asm volatile("s_waitcnt lgkmcnt(" #n ")" ::: "memory")
; #define PG8_BAR __builtin_amdgcn_s_barrier()
; #define PG8_SCHED __builtin_amdgcn_sched_barrier(0)
; template <class Epi, class Sched, bool ALIGN_EPI = false, bool SP2 = false>
; __device__ __forceinline__ void gemm_phase(PG8_LAS unsigned char* lds, const Gemm g, const Sched& S, const Epi& E) {
;     ...
;         for (int t = 0; t < nt; t += 2) {
;     ...
;             PG8_WAIT_V(8); PG8_WAIT_L(0); PG8_BAR; PG8_MMA(0, 0, At, B0); PG8_MMA(0, 1, At, B1); PG8_BAR; PG8_SCHED;
;             PG8_LDA(At, 1, 1); PG8_STAGE(PG8_SB(1, 0), b3, voffB); PG8_STAGE(PG8_SB(1, 1), b3 + hstep, voffB); PG8_STAGE(PG8_SA(1, 0), a3, voffA);
;             PG8_WAIT_V(8); PG8_WAIT_L(0); PG8_BAR; PG8_MMA(1, 0, At, B0); PG8_MMA(1, 1, At, B1); PG8_BAR; PG8_SCHED;
.Lgr_p7_2:
	s_waitcnt lgkmcnt(0)
	s_barrier
	s_setprio 1
	s_waitcnt lgkmcnt(0)
	v_mfma_f32_16x16x32_bf16 v[116:119], v[166:169], v[198:201], v[116:119]
	v_mfma_f32_16x16x32_bf16 v[112:115], v[174:177], v[198:201], v[112:115]
	v_mfma_f32_16x16x32_bf16 v[108:111], v[166:169], v[206:209], v[108:111]
	v_mfma_f32_16x16x32_bf16 v[100:103], v[174:177], v[206:209], v[100:103]
	v_mfma_f32_16x16x32_bf16 v[92:95], v[166:169], v[214:217], v[92:95]
	v_mfma_f32_16x16x32_bf16 v[84:87], v[174:177], v[214:217], v[84:87]
	v_mfma_f32_16x16x32_bf16 v[76:79], v[166:169], v[226:229], v[76:79]
	v_mfma_f32_16x16x32_bf16 v[68:71], v[174:177], v[226:229], v[68:71]
	v_mfma_f32_16x16x32_bf16 v[116:119], v[170:173], v[202:205], v[116:119]
	v_mfma_f32_16x16x32_bf16 v[112:115], v[178:181], v[202:205], v[112:115]
	v_mfma_f32_16x16x32_bf16 v[108:111], v[170:173], v[210:213], v[108:111]
	v_mfma_f32_16x16x32_bf16 v[100:103], v[178:181], v[210:213], v[100:103]
	v_mfma_f32_16x16x32_bf16 v[92:95], v[170:173], v[222:225], v[92:95]
	v_mfma_f32_16x16x32_bf16 v[84:87], v[178:181], v[222:225], v[84:87]
	v_mfma_f32_16x16x32_bf16 v[76:79], v[170:173], v[230:233], v[76:79]
	v_mfma_f32_16x16x32_bf16 v[68:71], v[178:181], v[230:233], v[68:71]
	s_setprio 0
	s_setprio 1
	v_mfma_f32_16x16x32_bf16 v[124:127], v[182:185], v[198:201], v[124:127]
	v_mfma_f32_16x16x32_bf16 v[120:123], v[190:193], v[198:201], v[120:123]
	v_mfma_f32_16x16x32_bf16 v[104:107], v[182:185], v[206:209], v[104:107]
	v_mfma_f32_16x16x32_bf16 v[96:99], v[190:193], v[206:209], v[96:99]
	v_mfma_f32_16x16x32_bf16 v[88:91], v[182:185], v[214:217], v[88:91]
	v_mfma_f32_16x16x32_bf16 v[80:83], v[190:193], v[214:217], v[80:83]
	v_mfma_f32_16x16x32_bf16 v[72:75], v[182:185], v[226:229], v[72:75]
	v_mfma_f32_16x16x32_bf16 v[64:67], v[190:193], v[226:229], v[64:67]
	v_mfma_f32_16x16x32_bf16 v[124:127], v[186:189], v[202:205], v[124:127]
	v_mfma_f32_16x16x32_bf16 v[120:123], v[194:197], v[202:205], v[120:123]
	v_mfma_f32_16x16x32_bf16 v[104:107], v[186:189], v[210:213], v[104:107]
	v_mfma_f32_16x16x32_bf16 v[96:99], v[194:197], v[210:213], v[96:99]
	v_mfma_f32_16x16x32_bf16 v[88:91], v[186:189], v[222:225], v[88:91]
	v_mfma_f32_16x16x32_bf16 v[80:83], v[194:197], v[222:225], v[80:83]
	v_mfma_f32_16x16x32_bf16 v[72:75], v[186:189], v[230:233], v[72:75]
	v_mfma_f32_16x16x32_bf16 v[64:67], v[194:197], v[230:233], v[64:67]
	s_setprio 0
	s_barrier
	s_add_i32 s28, s52, s30
	s_mov_b32 m0, s28
	ds_read_b128 v[198:201], v164 offset:49152
	ds_read_b128 v[202:205], v164 offset:50176
	ds_read_b128 v[206:209], v164 offset:51200
	ds_read_b128 v[210:213], v164 offset:52224
	global_load_lds_dwordx4 v132, vcc
	s_add_i32 m0, s28, 0x2000
	s_add_u32 s26, s26, 0x80080
	s_addc_u32 s27, s27, 0
	s_add_i32 s28, s53, s30
	global_load_lds_dwordx4 v128, vcc
	s_mov_b32 m0, s28
	ds_read_b128 v[230:233], v164 offset:56320
	global_load_lds_dwordx4 v132, s[26:27]
	s_add_i32 m0, s28, 0x2000
	ds_read_b128 v[226:229], v164 offset:55296
	global_load_lds_dwordx4 v128, s[26:27]
	s_mov_b32 m0, s39
	ds_read_b128 v[222:225], v164 offset:54272
	global_load_lds_dwordx4 v134, s[98:99]
	s_mov_b32 m0, s40
	ds_read_b128 v[214:217], v164 offset:53248
	global_load_lds_dwordx4 v130, s[98:99]
	s_waitcnt vmcnt(8)
	s_waitcnt lgkmcnt(0)
	s_barrier
	s_setprio 1
	s_waitcnt lgkmcnt(0)
	v_mfma_f32_16x16x32_bf16 v[60:63], v[166:169], v[198:201], v[60:63]
	v_mfma_f32_16x16x32_bf16 v[52:55], v[174:177], v[198:201], v[52:55]
	v_mfma_f32_16x16x32_bf16 v[44:47], v[166:169], v[206:209], v[44:47]
	v_mfma_f32_16x16x32_bf16 v[36:39], v[174:177], v[206:209], v[36:39]
	v_mfma_f32_16x16x32_bf16 v[28:31], v[166:169], v[214:217], v[28:31]
	v_mfma_f32_16x16x32_bf16 v[20:23], v[174:177], v[214:217], v[20:23]
	v_mfma_f32_16x16x32_bf16 v[12:15], v[166:169], v[226:229], v[12:15]
	v_mfma_f32_16x16x32_bf16 v[4:7], v[174:177], v[226:229], v[4:7]
	v_mfma_f32_16x16x32_bf16 v[60:63], v[170:173], v[202:205], v[60:63]
	v_mfma_f32_16x16x32_bf16 v[52:55], v[178:181], v[202:205], v[52:55]
	v_mfma_f32_16x16x32_bf16 v[44:47], v[170:173], v[210:213], v[44:47]
	v_mfma_f32_16x16x32_bf16 v[36:39], v[178:181], v[210:213], v[36:39]
	v_mfma_f32_16x16x32_bf16 v[28:31], v[170:173], v[222:225], v[28:31]
	v_mfma_f32_16x16x32_bf16 v[20:23], v[178:181], v[222:225], v[20:23]
	v_mfma_f32_16x16x32_bf16 v[12:15], v[170:173], v[230:233], v[12:15]
	v_mfma_f32_16x16x32_bf16 v[4:7], v[178:181], v[230:233], v[4:7]
	s_setprio 0
	s_setprio 1
	v_mfma_f32_16x16x32_bf16 v[56:59], v[182:185], v[198:201], v[56:59]
	v_mfma_f32_16x16x32_bf16 v[48:51], v[190:193], v[198:201], v[48:51]
	v_mfma_f32_16x16x32_bf16 v[40:43], v[182:185], v[206:209], v[40:43]
	v_mfma_f32_16x16x32_bf16 v[32:35], v[190:193], v[206:209], v[32:35]
	v_mfma_f32_16x16x32_bf16 v[24:27], v[182:185], v[214:217], v[24:27]
	v_mfma_f32_16x16x32_bf16 v[16:19], v[190:193], v[214:217], v[16:19]
	v_mfma_f32_16x16x32_bf16 v[8:11], v[182:185], v[226:229], v[8:11]
	v_mfma_f32_16x16x32_bf16 v[0:3], v[190:193], v[226:229], v[0:3]
	v_mfma_f32_16x16x32_bf16 v[56:59], v[186:189], v[202:205], v[56:59]
	v_mfma_f32_16x16x32_bf16 v[48:51], v[194:197], v[202:205], v[48:51]
	v_mfma_f32_16x16x32_bf16 v[40:43], v[186:189], v[210:213], v[40:43]
	v_mfma_f32_16x16x32_bf16 v[32:35], v[194:197], v[210:213], v[32:35]
	v_mfma_f32_16x16x32_bf16 v[24:27], v[186:189], v[222:225], v[24:27]
	v_mfma_f32_16x16x32_bf16 v[16:19], v[194:197], v[222:225], v[16:19]
	v_mfma_f32_16x16x32_bf16 v[8:11], v[186:189], v[230:233], v[8:11]
	v_mfma_f32_16x16x32_bf16 v[0:3], v[194:197], v[230:233], v[0:3]
	s_setprio 0
	s_barrier
	s_mov_b32 s100, 0
	s_add_i32 s51, s51, 2
	s_add_u32 s24, s24, 0x100
	s_addc_u32 s25, s25, 0
	s_add_u32 s49, s49, 0x100
	s_addc_u32 s50, s50, 0
	s_cmp_gt_u32 s51, 29
	s_cbranch_scc0 .LBB0_1076
	s_and_b64 vcc, exec, s[14:15]
	s_cbranch_vccz .LBB0_1079
	s_barrier

; #define PG8_STAGE(bufoff, gbase, voff) do { _Pragma("unroll") for (int _i = 0; _i < 2; ++_i) \
;         __builtin_amdgcn_global_load_lds((const unsigned*)((const char*)(gbase) + (voff)[_i]), (PG8_LAS unsigned*)(lds + (bufoff) + ldsw + _i * 8192), 16, 0, 0); } while (0)
; #define PG8_LDA(dst, b, h) do { _Pragma("unroll") for (int m = 0; m < 4; ++m) _Pragma("unroll") for (int k = 0; k < 2; ++k) dst[m][k] = *(const PG8_LAS bf16x8*)(lds + PG8_SA(b, h) + aoff + m * 2048 + k * 1024); } while (0)
; #define PG8_LDB(dst, b, h) do { _Pragma("unroll") for (int n = 0; n < 2; ++n) _Pragma("unroll") for (int k = 0; k < 2; ++k) dst[n][k] = *(const PG8_LAS bf16x8*)(lds + PG8_SB(b, h) + boff + n * 2048 + k * 1024); } while (0)
; #define PG8_MMA(ai, bj, At, Bt) do { __builtin_amdgcn_s_setprio(1); _Pragma("unroll") for (int m = 0; m < 4; ++m) _Pragma("unroll") for (int n = 0; n < 2; ++n) _Pragma("unroll") for (int k = 0; k < 2; ++k) \
;         acc[ai][bj][m][n] = __builtin_amdgcn_mfma_f32_16x16x32_bf16(Bt[n][k], At[m][k], acc[ai][bj][m][n], 0, 0, 0); __builtin_amdgcn_s_setprio(0); } while (0)
; #define PG8_WAIT_V(n) asm volatile("s_waitcnt vmcnt(" #n ")" ::: "memory")
; #define PG8_WAIT_L(n) asm volatile("s_waitcnt lgkmcnt(" #n ")" ::: "memory")
; template <class Epi, class Sched, bool ALIGN_EPI = false, bool SP2 = false>
; __device__ __forceinline__ void gemm_phase(PG8_LAS unsigned char* lds, const Gemm g, const Sched& S, const Epi& E) {
;     ...
;             const bool last = (t == nt - 2);
;             const char* a1 = cA + (size_t)(t + 1) * kstep;
;             const char* a2 = last ? nA : cA + (size_t)(t + 2) * kstep; const char* b2 = last ? nB : cB + (size_t)(t + 2) * kstep;
;             const char* a3 = a2 + kstep; const char* b3 = b2 + kstep;
;             if (last && has_next) S.a_ready(nxt);
;             if constexpr (SP2) {
;             PG8_LDB(B0, 0, 0); PG8_LDB(B1, 0, 1); PG8_SCHED; PG8_LDA(At, 0, 0); PG8_STAGE(PG8_SA(1, 1), a1 + hstep, voffA);
;             PG8_WAIT_V(8); PG8_WAIT_L(0); PG8_BAR; PG8_MMA(0, 0, At, B0); PG8_MMA(0, 1, At, B1); PG8_BAR; PG8_SCHED;
;             PG8_LDA(At, 0, 1); PG8_STAGE(PG8_SB(0, 0), b2, voffB); PG8_STAGE(PG8_SB(0, 1), b2 + hstep, voffB); PG8_STAGE(PG8_SA(0, 0), a2, voffA);
;             PG8_WAIT_V(8); PG8_WAIT_L(0); PG8_BAR; PG8_MMA(1, 0, At, B0); PG8_MMA(1, 1, At, B1); PG8_BAR; PG8_SCHED;
.LBB0_1204:
	ds_read_b128 v[128:131], v213
	ds_read_b128 v[132:135], v213 offset:1024
	ds_read_b128 v[136:139], v213 offset:2048
	ds_read_b128 v[140:143], v213 offset:3072
	ds_read_b128 v[144:147], v214
	ds_read_b128 v[148:151], v214 offset:1024
	ds_read_b128 v[152:155], v214 offset:2048
	ds_read_b128 v[156:159], v214 offset:3072
	s_add_u32 s22, s20, 0xffea0080
	s_addc_u32 s23, s21, -1
	s_cmpk_eq_i32 s46, 0x54
	s_cselect_b32 s25, s5, s23
	s_cselect_b32 s24, s4, s22
	s_cselect_b32 s23, s19, s45
	s_cselect_b32 s22, s18, s44
	s_add_i32 m0, s27, 0xc000
	ds_read_b128 v[160:163], v215
	ds_read_b128 v[164:167], v215 offset:1024
	ds_read_b128 v[168:171], v215 offset:2048
	ds_read_b128 v[172:175], v215 offset:3072
	ds_read_b128 v[192:195], v215 offset:4096
	ds_read_b128 v[196:199], v215 offset:5120
	ds_read_b128 v[200:203], v215 offset:6144
	global_load_lds_dwordx4 v184, s[20:21]
	s_add_i32 m0, s27, 0xe000
	ds_read_b128 v[204:207], v215 offset:7168
	global_load_lds_dwordx4 v186, s[20:21]
	s_waitcnt vmcnt(8)
	s_waitcnt lgkmcnt(0)
	s_barrier
	s_setprio 1
	s_waitcnt lgkmcnt(0)
	v_mfma_f32_16x16x32_bf16 v[124:127], v[128:131], v[160:163], v[124:127]
	v_mfma_f32_16x16x32_bf16 v[120:123], v[136:139], v[160:163], v[120:123]
	v_mfma_f32_16x16x32_bf16 v[108:111], v[128:131], v[168:171], v[108:111]
	v_mfma_f32_16x16x32_bf16 v[104:107], v[136:139], v[168:171], v[104:107]
	v_mfma_f32_16x16x32_bf16 v[92:95], v[128:131], v[192:195], v[92:95]
	v_mfma_f32_16x16x32_bf16 v[88:91], v[136:139], v[192:195], v[88:91]
	v_mfma_f32_16x16x32_bf16 v[76:79], v[128:131], v[200:203], v[76:79]
	v_mfma_f32_16x16x32_bf16 v[72:75], v[136:139], v[200:203], v[72:75]
	v_mfma_f32_16x16x32_bf16 v[124:127], v[132:135], v[164:167], v[124:127]
	v_mfma_f32_16x16x32_bf16 v[120:123], v[140:143], v[164:167], v[120:123]
	v_mfma_f32_16x16x32_bf16 v[108:111], v[132:135], v[172:175], v[108:111]
	v_mfma_f32_16x16x32_bf16 v[104:107], v[140:143], v[172:175], v[104:107]
	v_mfma_f32_16x16x32_bf16 v[92:95], v[132:135], v[196:199], v[92:95]
	v_mfma_f32_16x16x32_bf16 v[88:91], v[140:143], v[196:199], v[88:91]
	v_mfma_f32_16x16x32_bf16 v[76:79], v[132:135], v[204:207], v[76:79]
	v_mfma_f32_16x16x32_bf16 v[72:75], v[140:143], v[204:207], v[72:75]
	s_setprio 0
	s_setprio 1
	v_mfma_f32_16x16x32_bf16 v[116:119], v[144:147], v[160:163], v[116:119]
	v_mfma_f32_16x16x32_bf16 v[112:115], v[152:155], v[160:163], v[112:115]
	v_mfma_f32_16x16x32_bf16 v[100:103], v[144:147], v[168:171], v[100:103]
	v_mfma_f32_16x16x32_bf16 v[96:99], v[152:155], v[168:171], v[96:99]
	v_mfma_f32_16x16x32_bf16 v[84:87], v[144:147], v[192:195], v[84:87]
	v_mfma_f32_16x16x32_bf16 v[80:83], v[152:155], v[192:195], v[80:83]
	v_mfma_f32_16x16x32_bf16 v[68:71], v[144:147], v[200:203], v[68:71]
	v_mfma_f32_16x16x32_bf16 v[64:67], v[152:155], v[200:203], v[64:67]
	v_mfma_f32_16x16x32_bf16 v[116:119], v[148:151], v[164:167], v[116:119]
	v_mfma_f32_16x16x32_bf16 v[112:115], v[156:159], v[164:167], v[112:115]
	v_mfma_f32_16x16x32_bf16 v[100:103], v[148:151], v[172:175], v[100:103]
	v_mfma_f32_16x16x32_bf16 v[96:99], v[156:159], v[172:175], v[96:99]
	v_mfma_f32_16x16x32_bf16 v[84:87], v[148:151], v[196:199], v[84:87]
	v_mfma_f32_16x16x32_bf16 v[80:83], v[156:159], v[196:199], v[80:83]
	v_mfma_f32_16x16x32_bf16 v[68:71], v[148:151], v[204:207], v[68:71]
	v_mfma_f32_16x16x32_bf16 v[64:67], v[156:159], v[204:207], v[64:67]
	s_setprio 0
	s_barrier
	s_add_i32 s47, s38, s26
	s_add_u32 vcc_lo, s22, 0x80
	s_addc_u32 vcc_hi, s23, 0
	s_mov_b32 m0, s47
	ds_read_b128 v[160:163], v215 offset:16384
	ds_read_b128 v[164:167], v215 offset:17408
	ds_read_b128 v[168:171], v215 offset:18432
	ds_read_b128 v[172:175], v215 offset:19456
	global_load_lds_dwordx4 v178, s[22:23]
	s_add_i32 m0, s47, 0x2000
	s_add_u32 s48, s22, 0x160000
	s_addc_u32 s49, s23, 0
	s_add_i32 s47, s39, s26
	global_load_lds_dwordx4 v182, s[22:23]
	s_mov_b32 m0, s47
	ds_read_b128 v[204:207], v215 offset:23552
	global_load_lds_dwordx4 v178, s[48:49]
	s_add_i32 m0, s47, 0x2000
	ds_read_b128 v[200:203], v215 offset:22528
	global_load_lds_dwordx4 v182, s[48:49]
	s_add_u32 s98, s24, 0x80
	s_addc_u32 s99, s25, 0
	s_mov_b32 m0, s27
	ds_read_b128 v[196:199], v215 offset:21504
	global_load_lds_dwordx4 v176, s[24:25]
	s_mov_b32 m0, s28
	ds_read_b128 v[192:195], v215 offset:20480
	global_load_lds_dwordx4 v180, s[24:25]
	s_waitcnt vmcnt(8)
	s_waitcnt lgkmcnt(0)
	s_barrier
	s_setprio 1
	s_waitcnt lgkmcnt(0)
	v_mfma_f32_16x16x32_bf16 v[60:63], v[128:131], v[160:163], v[60:63]
	v_mfma_f32_16x16x32_bf16 v[56:59], v[136:139], v[160:163], v[56:59]
	v_mfma_f32_16x16x32_bf16 v[44:47], v[128:131], v[168:171], v[44:47]
	v_mfma_f32_16x16x32_bf16 v[40:43], v[136:139], v[168:171], v[40:43]
	v_mfma_f32_16x16x32_bf16 v[28:31], v[128:131], v[192:195], v[28:31]
	v_mfma_f32_16x16x32_bf16 v[24:27], v[136:139], v[192:195], v[24:27]
	v_mfma_f32_16x16x32_bf16 v[12:15], v[128:131], v[200:203], v[12:15]
	v_mfma_f32_16x16x32_bf16 v[8:11], v[136:139], v[200:203], v[8:11]
	v_mfma_f32_16x16x32_bf16 v[60:63], v[132:135], v[164:167], v[60:63]
	v_mfma_f32_16x16x32_bf16 v[56:59], v[140:143], v[164:167], v[56:59]
	v_mfma_f32_16x16x32_bf16 v[44:47], v[132:135], v[172:175], v[44:47]
	v_mfma_f32_16x16x32_bf16 v[40:43], v[140:143], v[172:175], v[40:43]
	v_mfma_f32_16x16x32_bf16 v[28:31], v[132:135], v[196:199], v[28:31]
	v_mfma_f32_16x16x32_bf16 v[24:27], v[140:143], v[196:199], v[24:27]
	v_mfma_f32_16x16x32_bf16 v[12:15], v[132:135], v[204:207], v[12:15]
	v_mfma_f32_16x16x32_bf16 v[8:11], v[140:143], v[204:207], v[8:11]
	s_setprio 0
	s_setprio 1
	v_mfma_f32_16x16x32_bf16 v[52:55], v[144:147], v[160:163], v[52:55]
	v_mfma_f32_16x16x32_bf16 v[48:51], v[152:155], v[160:163], v[48:51]
	v_mfma_f32_16x16x32_bf16 v[36:39], v[144:147], v[168:171], v[36:39]
	v_mfma_f32_16x16x32_bf16 v[32:35], v[152:155], v[168:171], v[32:35]
	v_mfma_f32_16x16x32_bf16 v[20:23], v[144:147], v[192:195], v[20:23]
	v_mfma_f32_16x16x32_bf16 v[16:19], v[152:155], v[192:195], v[16:19]
	v_mfma_f32_16x16x32_bf16 v[4:7], v[144:147], v[200:203], v[4:7]
	v_mfma_f32_16x16x32_bf16 v[0:3], v[152:155], v[200:203], v[0:3]
	v_mfma_f32_16x16x32_bf16 v[52:55], v[148:151], v[164:167], v[52:55]
	v_mfma_f32_16x16x32_bf16 v[48:51], v[156:159], v[164:167], v[48:51]
	v_mfma_f32_16x16x32_bf16 v[36:39], v[148:151], v[172:175], v[36:39]
	v_mfma_f32_16x16x32_bf16 v[32:35], v[156:159], v[172:175], v[32:35]
	v_mfma_f32_16x16x32_bf16 v[20:23], v[148:151], v[196:199], v[20:23]
	v_mfma_f32_16x16x32_bf16 v[16:19], v[156:159], v[196:199], v[16:19]
	v_mfma_f32_16x16x32_bf16 v[4:7], v[148:151], v[204:207], v[4:7]
	v_mfma_f32_16x16x32_bf16 v[0:3], v[156:159], v[204:207], v[0:3]
	s_setprio 0
	s_barrier
; #define PG8_STAGE(bufoff, gbase, voff) do { _Pragma("unroll") for (int _i = 0; _i < 2; ++_i) \
;         __builtin_amdgcn_global_load_lds((const unsigned*)((const char*)(gbase) + (voff)[_i]), (PG8_LAS unsigned*)(lds + (bufoff) + ldsw + _i * 8192), 16, 0, 0); } while (0)
; #define PG8_LDA(dst, b, h) do { _Pragma("unroll") for (int m = 0; m < 4; ++m) _Pragma("unroll") for (int k = 0; k < 2; ++k) dst[m][k] = *(const PG8_LAS bf16x8*)(lds + PG8_SA(b, h) + aoff + m * 2048 + k * 1024); } while (0)
; #define PG8_LDB(dst, b, h) do { _Pragma("unroll") for (int n = 0; n < 2; ++n) _Pragma("unroll") for (int k = 0; k < 2; ++k) dst[n][k] = *(const PG8_LAS bf16x8*)(lds + PG8_SB(b, h) + boff + n * 2048 + k * 1024); } while (0)
; #define PG8_MMA(ai, bj, At, Bt) do { __builtin_amdgcn_s_setprio(1); _Pragma("unroll") for (int m = 0; m < 4; ++m) _Pragma("unroll") for (int n = 0; n < 2; ++n) _Pragma("unroll") for (int k = 0; k < 2; ++k) \
;         acc[ai][bj][m][n] = __builtin_amdgcn_mfma_f32_16x16x32_bf16(Bt[n][k], At[m][k], acc[ai][bj][m][n], 0, 0, 0); __builtin_amdgcn_s_setprio(0); } while (0)
; #define PG8_WAIT_V(n) asm volatile("s_waitcnt vmcnt(" #n ")" ::: "memory")
; #define PG8_WAIT_L(n) asm volatile("s_waitcnt lgkmcnt(" #n ")" ::: "memory")
; #define PG8_BAR __builtin_amdgcn_s_barrier()
; #define PG8_SCHED __builtin_amdgcn_sched_barrier(0)
; template <class Epi, class Sched, bool ALIGN_EPI = false, bool SP2 = false>
; __device__ __forceinline__ void gemm_phase(PG8_LAS unsigned char* lds, const Gemm g, const Sched& S, const Epi& E) {
;     ...
;         for (int t = 0; t < nt; t += 2) {
;     ...
;             PG8_LDB(B0, 1, 0); PG8_LDB(B1, 1, 1); PG8_SCHED; PG8_LDA(At, 1, 0); PG8_STAGE(PG8_SA(0, 1), a2 + hstep, voffA);
;             PG8_WAIT_V(8); PG8_WAIT_L(0); PG8_BAR; PG8_MMA(0, 0, At, B0); PG8_MMA(0, 1, At, B1); PG8_BAR; PG8_SCHED;
;             PG8_LDA(At, 1, 1); PG8_STAGE(PG8_SB(1, 0), b3, voffB); PG8_STAGE(PG8_SB(1, 1), b3 + hstep, voffB); PG8_STAGE(PG8_SA(1, 0), a3, voffA);
;             PG8_WAIT_V(8); PG8_WAIT_L(0); PG8_BAR; PG8_MMA(1, 0, At, B0); PG8_MMA(1, 1, At, B1); PG8_BAR; PG8_SCHED;
	s_add_i32 s47, 0, 0x18000
	s_add_i32 s48, 0, 0x1c000
	v_add_u32_e32 v140, s47, v211
	v_add_u32_e32 v156, s48, v211
	ds_read_b128 v[128:131], v140
	ds_read_b128 v[132:135], v140 offset:1024
	ds_read_b128 v[136:139], v140 offset:2048
	ds_read_b128 v[140:143], v140 offset:3072
	ds_read_b128 v[144:147], v156
	ds_read_b128 v[148:151], v156 offset:1024
	ds_read_b128 v[152:155], v156 offset:2048
	ds_read_b128 v[156:159], v156 offset:3072
	s_add_u32 s24, s24, 0x160000
	s_addc_u32 s25, s25, 0
	s_mov_b32 m0, s29
	ds_read_b128 v[160:163], v215 offset:32768
	ds_read_b128 v[164:167], v215 offset:33792
	ds_read_b128 v[168:171], v215 offset:34816
	ds_read_b128 v[172:175], v215 offset:35840
	ds_read_b128 v[192:195], v215 offset:36864
	ds_read_b128 v[196:199], v215 offset:37888
	ds_read_b128 v[200:203], v215 offset:38912
	global_load_lds_dwordx4 v176, s[24:25]
	s_mov_b32 m0, s30
	ds_read_b128 v[204:207], v215 offset:39936
	global_load_lds_dwordx4 v180, s[24:25]
	s_waitcnt vmcnt(8)
	s_waitcnt lgkmcnt(0)
	s_barrier
	s_setprio 1
	s_waitcnt lgkmcnt(0)
	v_mfma_f32_16x16x32_bf16 v[124:127], v[128:131], v[160:163], v[124:127]
	v_mfma_f32_16x16x32_bf16 v[120:123], v[136:139], v[160:163], v[120:123]
	v_mfma_f32_16x16x32_bf16 v[108:111], v[128:131], v[168:171], v[108:111]
	v_mfma_f32_16x16x32_bf16 v[104:107], v[136:139], v[168:171], v[104:107]
	v_mfma_f32_16x16x32_bf16 v[92:95], v[128:131], v[192:195], v[92:95]
	v_mfma_f32_16x16x32_bf16 v[88:91], v[136:139], v[192:195], v[88:91]
	v_mfma_f32_16x16x32_bf16 v[76:79], v[128:131], v[200:203], v[76:79]
	v_mfma_f32_16x16x32_bf16 v[72:75], v[136:139], v[200:203], v[72:75]
	v_mfma_f32_16x16x32_bf16 v[124:127], v[132:135], v[164:167], v[124:127]
	v_mfma_f32_16x16x32_bf16 v[120:123], v[140:143], v[164:167], v[120:123]
	v_mfma_f32_16x16x32_bf16 v[108:111], v[132:135], v[172:175], v[108:111]
	v_mfma_f32_16x16x32_bf16 v[104:107], v[140:143], v[172:175], v[104:107]
	v_mfma_f32_16x16x32_bf16 v[92:95], v[132:135], v[196:199], v[92:95]
	v_mfma_f32_16x16x32_bf16 v[88:91], v[140:143], v[196:199], v[88:91]
	v_mfma_f32_16x16x32_bf16 v[76:79], v[132:135], v[204:207], v[76:79]
	v_mfma_f32_16x16x32_bf16 v[72:75], v[140:143], v[204:207], v[72:75]
	s_setprio 0
	s_setprio 1
	v_mfma_f32_16x16x32_bf16 v[116:119], v[144:147], v[160:163], v[116:119]
	v_mfma_f32_16x16x32_bf16 v[112:115], v[152:155], v[160:163], v[112:115]
	v_mfma_f32_16x16x32_bf16 v[100:103], v[144:147], v[168:171], v[100:103]
	v_mfma_f32_16x16x32_bf16 v[96:99], v[152:155], v[168:171], v[96:99]
	v_mfma_f32_16x16x32_bf16 v[84:87], v[144:147], v[192:195], v[84:87]
	v_mfma_f32_16x16x32_bf16 v[80:83], v[152:155], v[192:195], v[80:83]
	v_mfma_f32_16x16x32_bf16 v[68:71], v[144:147], v[200:203], v[68:71]
	v_mfma_f32_16x16x32_bf16 v[64:67], v[152:155], v[200:203], v[64:67]
	v_mfma_f32_16x16x32_bf16 v[116:119], v[148:151], v[164:167], v[116:119]
	v_mfma_f32_16x16x32_bf16 v[112:115], v[156:159], v[164:167], v[112:115]
	v_mfma_f32_16x16x32_bf16 v[100:103], v[148:151], v[172:175], v[100:103]
	v_mfma_f32_16x16x32_bf16 v[96:99], v[156:159], v[172:175], v[96:99]
	v_mfma_f32_16x16x32_bf16 v[84:87], v[148:151], v[196:199], v[84:87]
	v_mfma_f32_16x16x32_bf16 v[80:83], v[156:159], v[196:199], v[80:83]
	v_mfma_f32_16x16x32_bf16 v[68:71], v[148:151], v[204:207], v[68:71]
	v_mfma_f32_16x16x32_bf16 v[64:67], v[156:159], v[204:207], v[64:67]
	s_setprio 0
	s_barrier
	s_add_i32 s24, s47, s26
	s_mov_b32 m0, s24
	ds_read_b128 v[160:163], v215 offset:49152
	ds_read_b128 v[164:167], v215 offset:50176
	ds_read_b128 v[168:171], v215 offset:51200
	ds_read_b128 v[172:175], v215 offset:52224
	global_load_lds_dwordx4 v178, vcc
	s_add_i32 m0, s24, 0x2000
	s_add_u32 s22, s22, 0x160080
	s_addc_u32 s23, s23, 0
	s_add_i32 s24, s48, s26
	global_load_lds_dwordx4 v182, vcc
	s_mov_b32 m0, s24
	ds_read_b128 v[204:207], v215 offset:56320
	global_load_lds_dwordx4 v178, s[22:23]
	s_add_i32 m0, s24, 0x2000
	ds_read_b128 v[200:203], v215 offset:55296
	global_load_lds_dwordx4 v182, s[22:23]
	s_mov_b32 m0, s33
	ds_read_b128 v[196:199], v215 offset:54272
	global_load_lds_dwordx4 v176, s[98:99]
	s_mov_b32 m0, s34
	ds_read_b128 v[192:195], v215 offset:53248
	global_load_lds_dwordx4 v180, s[98:99]
	s_waitcnt vmcnt(8)
	s_waitcnt lgkmcnt(0)
	s_barrier
	s_setprio 1
	s_waitcnt lgkmcnt(0)
	v_mfma_f32_16x16x32_bf16 v[60:63], v[128:131], v[160:163], v[60:63]
	v_mfma_f32_16x16x32_bf16 v[56:59], v[136:139], v[160:163], v[56:59]
	v_mfma_f32_16x16x32_bf16 v[44:47], v[128:131], v[168:171], v[44:47]
	v_mfma_f32_16x16x32_bf16 v[40:43], v[136:139], v[168:171], v[40:43]
	v_mfma_f32_16x16x32_bf16 v[28:31], v[128:131], v[192:195], v[28:31]
	v_mfma_f32_16x16x32_bf16 v[24:27], v[136:139], v[192:195], v[24:27]
	v_mfma_f32_16x16x32_bf16 v[12:15], v[128:131], v[200:203], v[12:15]
	v_mfma_f32_16x16x32_bf16 v[8:11], v[136:139], v[200:203], v[8:11]
	v_mfma_f32_16x16x32_bf16 v[60:63], v[132:135], v[164:167], v[60:63]
	v_mfma_f32_16x16x32_bf16 v[56:59], v[140:143], v[164:167], v[56:59]
	v_mfma_f32_16x16x32_bf16 v[44:47], v[132:135], v[172:175], v[44:47]
	v_mfma_f32_16x16x32_bf16 v[40:43], v[140:143], v[172:175], v[40:43]
	v_mfma_f32_16x16x32_bf16 v[28:31], v[132:135], v[196:199], v[28:31]
	v_mfma_f32_16x16x32_bf16 v[24:27], v[140:143], v[196:199], v[24:27]
	v_mfma_f32_16x16x32_bf16 v[12:15], v[132:135], v[204:207], v[12:15]
	v_mfma_f32_16x16x32_bf16 v[8:11], v[140:143], v[204:207], v[8:11]
	s_setprio 0
	s_setprio 1
	v_mfma_f32_16x16x32_bf16 v[52:55], v[144:147], v[160:163], v[52:55]
	v_mfma_f32_16x16x32_bf16 v[48:51], v[152:155], v[160:163], v[48:51]
	v_mfma_f32_16x16x32_bf16 v[36:39], v[144:147], v[168:171], v[36:39]
	v_mfma_f32_16x16x32_bf16 v[32:35], v[152:155], v[168:171], v[32:35]
	v_mfma_f32_16x16x32_bf16 v[20:23], v[144:147], v[192:195], v[20:23]
	v_mfma_f32_16x16x32_bf16 v[16:19], v[152:155], v[192:195], v[16:19]
	v_mfma_f32_16x16x32_bf16 v[4:7], v[144:147], v[200:203], v[4:7]
	v_mfma_f32_16x16x32_bf16 v[0:3], v[152:155], v[200:203], v[0:3]
	v_mfma_f32_16x16x32_bf16 v[52:55], v[148:151], v[164:167], v[52:55]
	v_mfma_f32_16x16x32_bf16 v[48:51], v[156:159], v[164:167], v[48:51]
	v_mfma_f32_16x16x32_bf16 v[36:39], v[148:151], v[172:175], v[36:39]
	v_mfma_f32_16x16x32_bf16 v[32:35], v[156:159], v[172:175], v[32:35]
	v_mfma_f32_16x16x32_bf16 v[20:23], v[148:151], v[196:199], v[20:23]
	v_mfma_f32_16x16x32_bf16 v[16:19], v[156:159], v[196:199], v[16:19]
	v_mfma_f32_16x16x32_bf16 v[4:7], v[148:151], v[204:207], v[4:7]
	v_mfma_f32_16x16x32_bf16 v[0:3], v[156:159], v[204:207], v[0:3]
	s_setprio 0
	s_barrier
	s_add_i32 s46, s46, 2
	s_add_u32 s20, s20, 0x100
	s_addc_u32 s21, s21, 0
	s_add_u32 s44, s44, 0x100
	s_addc_u32 s45, s45, 0
	s_cmpk_gt_u32 s46, 0x55
	s_cbranch_scc0 .LBB0_1204
	s_and_b64 vcc, exec, s[16:17]
	s_cbranch_vccz .LBB0_1207
	s_barrier

; #define PG8_STAGE(bufoff, gbase, voff) do { _Pragma("unroll") for (int _i = 0; _i < 2; ++_i) \
;         __builtin_amdgcn_global_load_lds((const unsigned*)((const char*)(gbase) + (voff)[_i]), (PG8_LAS unsigned*)(lds + (bufoff) + ldsw + _i * 8192), 16, 0, 0); } while (0)
; #define PG8_LDA(dst, b, h) do { _Pragma("unroll") for (int m = 0; m < 4; ++m) _Pragma("unroll") for (int k = 0; k < 2; ++k) dst[m][k] = *(const PG8_LAS bf16x8*)(lds + PG8_SA(b, h) + aoff + m * 2048 + k * 1024); } while (0)
; #define PG8_LDB(dst, b, h) do { _Pragma("unroll") for (int n = 0; n < 2; ++n) _Pragma("unroll") for (int k = 0; k < 2; ++k) dst[n][k] = *(const PG8_LAS bf16x8*)(lds + PG8_SB(b, h) + boff + n * 2048 + k * 1024); } while (0)
; #define PG8_MMA(ai, bj, At, Bt) do { __builtin_amdgcn_s_setprio(1); _Pragma("unroll") for (int m = 0; m < 4; ++m) _Pragma("unroll") for (int n = 0; n < 2; ++n) _Pragma("unroll") for (int k = 0; k < 2; ++k) \
;         acc[ai][bj][m][n] = __builtin_amdgcn_mfma_f32_16x16x32_bf16(Bt[n][k], At[m][k], acc[ai][bj][m][n], 0, 0, 0); __builtin_amdgcn_s_setprio(0); } while (0)
; #define PG8_WAIT_V(n) asm volatile("s_waitcnt vmcnt(" #n ")" ::: "memory")
; #define PG8_WAIT_L(n) asm volatile("s_waitcnt lgkmcnt(" #n ")" ::: "memory")
; template <class Epi, class Sched, bool ALIGN_EPI = false, bool SP2 = false>
; __device__ __forceinline__ void gemm_phase(PG8_LAS unsigned char* lds, const Gemm g, const Sched& S, const Epi& E) {
;     ...
;             const bool last = (t == nt - 2);
;             const char* a1 = cA + (size_t)(t + 1) * kstep;
;             const char* a2 = last ? nA : cA + (size_t)(t + 2) * kstep; const char* b2 = last ? nB : cB + (size_t)(t + 2) * kstep;
;             const char* a3 = a2 + kstep; const char* b3 = b2 + kstep;
;             if (last && has_next) S.a_ready(nxt);
;             if constexpr (SP2) {
;             PG8_LDB(B0, 0, 0); PG8_LDB(B1, 0, 1); PG8_SCHED; PG8_LDA(At, 0, 0); PG8_STAGE(PG8_SA(1, 1), a1 + hstep, voffA);
;             PG8_WAIT_V(8); PG8_WAIT_L(0); PG8_BAR; PG8_MMA(0, 0, At, B0); PG8_MMA(0, 1, At, B1); PG8_BAR; PG8_SCHED;
;             PG8_LDA(At, 0, 1); PG8_STAGE(PG8_SB(0, 0), b2, voffB); PG8_STAGE(PG8_SB(0, 1), b2 + hstep, voffB); PG8_STAGE(PG8_SA(0, 0), a2, voffA);
;             PG8_WAIT_V(8); PG8_WAIT_L(0); PG8_BAR; PG8_MMA(1, 0, At, B0); PG8_MMA(1, 1, At, B1); PG8_BAR; PG8_SCHED;
.LBB0_1295:
	ds_read_b128 v[56:59], v203
	ds_read_b128 v[64:67], v203 offset:1024
	ds_read_b128 v[72:75], v203 offset:2048
	ds_read_b128 v[76:79], v203 offset:3072
	ds_read_b128 v[144:147], v204
	ds_read_b128 v[148:151], v204 offset:1024
	ds_read_b128 v[152:155], v204 offset:2048
	ds_read_b128 v[156:159], v204 offset:3072
	s_add_u32 s36, s34, 0xfff80080
	s_addc_u32 s37, s35, -1
	s_cmp_eq_u32 s56, 28
	s_cselect_b32 s39, s27, s37
	s_cselect_b32 s38, s52, s36
	s_cselect_b32 s37, s25, s55
	s_cselect_b32 s36, s53, s54
	s_add_i32 m0, s41, 0xc000
	ds_read_b128 v[160:163], v205
	ds_read_b128 v[164:167], v205 offset:1024
	ds_read_b128 v[168:171], v205 offset:2048
	ds_read_b128 v[188:191], v205 offset:3072
	ds_read_b128 v[192:195], v205 offset:4096
	ds_read_b128 v[196:199], v205 offset:5120
	ds_read_b128 v[208:211], v205 offset:6144
	global_load_lds_dwordx4 v180, s[34:35]
	s_add_i32 m0, s41, 0xe000
	ds_read_b128 v[212:215], v205 offset:7168
	global_load_lds_dwordx4 v182, s[34:35]
	s_waitcnt vmcnt(8)
	s_waitcnt lgkmcnt(0)
	s_barrier
	s_setprio 1
	s_waitcnt lgkmcnt(0)
	v_mfma_f32_16x16x32_bf16 v[140:143], v[56:59], v[160:163], v[140:143]
	v_mfma_f32_16x16x32_bf16 v[136:139], v[72:75], v[160:163], v[136:139]
	v_mfma_f32_16x16x32_bf16 v[124:127], v[56:59], v[168:171], v[124:127]
	v_mfma_f32_16x16x32_bf16 v[120:123], v[72:75], v[168:171], v[120:123]
	v_mfma_f32_16x16x32_bf16 v[108:111], v[56:59], v[192:195], v[108:111]
	v_mfma_f32_16x16x32_bf16 v[104:107], v[72:75], v[192:195], v[104:107]
	v_mfma_f32_16x16x32_bf16 v[92:95], v[56:59], v[208:211], v[92:95]
	v_mfma_f32_16x16x32_bf16 v[88:91], v[72:75], v[208:211], v[88:91]
	v_mfma_f32_16x16x32_bf16 v[140:143], v[64:67], v[164:167], v[140:143]
	v_mfma_f32_16x16x32_bf16 v[136:139], v[76:79], v[164:167], v[136:139]
	v_mfma_f32_16x16x32_bf16 v[124:127], v[64:67], v[188:191], v[124:127]
	v_mfma_f32_16x16x32_bf16 v[120:123], v[76:79], v[188:191], v[120:123]
	v_mfma_f32_16x16x32_bf16 v[108:111], v[64:67], v[196:199], v[108:111]
	v_mfma_f32_16x16x32_bf16 v[104:107], v[76:79], v[196:199], v[104:107]
	v_mfma_f32_16x16x32_bf16 v[92:95], v[64:67], v[212:215], v[92:95]
	v_mfma_f32_16x16x32_bf16 v[88:91], v[76:79], v[212:215], v[88:91]
	s_setprio 0
	s_setprio 1
	v_mfma_f32_16x16x32_bf16 v[132:135], v[144:147], v[160:163], v[132:135]
	v_mfma_f32_16x16x32_bf16 v[128:131], v[152:155], v[160:163], v[128:131]
	v_mfma_f32_16x16x32_bf16 v[116:119], v[144:147], v[168:171], v[116:119]
	v_mfma_f32_16x16x32_bf16 v[112:115], v[152:155], v[168:171], v[112:115]
	v_mfma_f32_16x16x32_bf16 v[100:103], v[144:147], v[192:195], v[100:103]
	v_mfma_f32_16x16x32_bf16 v[96:99], v[152:155], v[192:195], v[96:99]
	v_mfma_f32_16x16x32_bf16 v[84:87], v[144:147], v[208:211], v[84:87]
	v_mfma_f32_16x16x32_bf16 v[80:83], v[152:155], v[208:211], v[80:83]
	v_mfma_f32_16x16x32_bf16 v[132:135], v[148:151], v[164:167], v[132:135]
	v_mfma_f32_16x16x32_bf16 v[128:131], v[156:159], v[164:167], v[128:131]
	v_mfma_f32_16x16x32_bf16 v[116:119], v[148:151], v[188:191], v[116:119]
	v_mfma_f32_16x16x32_bf16 v[112:115], v[156:159], v[188:191], v[112:115]
	v_mfma_f32_16x16x32_bf16 v[100:103], v[148:151], v[196:199], v[100:103]
	v_mfma_f32_16x16x32_bf16 v[96:99], v[156:159], v[196:199], v[96:99]
	v_mfma_f32_16x16x32_bf16 v[84:87], v[148:151], v[212:215], v[84:87]
	v_mfma_f32_16x16x32_bf16 v[80:83], v[156:159], v[212:215], v[80:83]
	s_setprio 0
	s_barrier
	s_add_i32 s57, s49, s40
	s_add_u32 vcc_lo, s36, 0x80
	s_addc_u32 vcc_hi, s37, 0
	s_mov_b32 m0, s57
	ds_read_b128 v[160:163], v205 offset:16384
	ds_read_b128 v[164:167], v205 offset:17408
	ds_read_b128 v[168:171], v205 offset:18432
	ds_read_b128 v[188:191], v205 offset:19456
	global_load_lds_dwordx4 v174, s[36:37]
	s_add_i32 m0, s57, 0x2000
	s_add_u32 s58, s36, 0x80000
	s_addc_u32 s59, s37, 0
	s_add_i32 s57, s50, s40
	global_load_lds_dwordx4 v178, s[36:37]
	s_mov_b32 m0, s57
	ds_read_b128 v[212:215], v205 offset:23552
	global_load_lds_dwordx4 v174, s[58:59]
	s_add_i32 m0, s57, 0x2000
	ds_read_b128 v[208:211], v205 offset:22528
	global_load_lds_dwordx4 v178, s[58:59]
	s_add_u32 s98, s38, 0x80
	s_addc_u32 s99, s39, 0
	s_mov_b32 m0, s41
	ds_read_b128 v[196:199], v205 offset:21504
	global_load_lds_dwordx4 v172, s[38:39]
	s_mov_b32 m0, s42
	ds_read_b128 v[192:195], v205 offset:20480
	global_load_lds_dwordx4 v176, s[38:39]
	s_waitcnt vmcnt(8)
	s_waitcnt lgkmcnt(0)
	s_barrier
	s_setprio 1
	s_waitcnt lgkmcnt(0)
	v_mfma_f32_16x16x32_bf16 v[68:71], v[56:59], v[160:163], v[68:71]
	v_mfma_f32_16x16x32_bf16 v[60:63], v[72:75], v[160:163], v[60:63]
	v_mfma_f32_16x16x32_bf16 v[44:47], v[56:59], v[168:171], v[44:47]
	v_mfma_f32_16x16x32_bf16 v[40:43], v[72:75], v[168:171], v[40:43]
	v_mfma_f32_16x16x32_bf16 v[28:31], v[56:59], v[192:195], v[28:31]
	v_mfma_f32_16x16x32_bf16 v[24:27], v[72:75], v[192:195], v[24:27]
	v_mfma_f32_16x16x32_bf16 v[12:15], v[56:59], v[208:211], v[12:15]
	v_mfma_f32_16x16x32_bf16 v[8:11], v[72:75], v[208:211], v[8:11]
	v_mfma_f32_16x16x32_bf16 v[68:71], v[64:67], v[164:167], v[68:71]
	v_mfma_f32_16x16x32_bf16 v[60:63], v[76:79], v[164:167], v[60:63]
	v_mfma_f32_16x16x32_bf16 v[44:47], v[64:67], v[188:191], v[44:47]
	v_mfma_f32_16x16x32_bf16 v[40:43], v[76:79], v[188:191], v[40:43]
	v_mfma_f32_16x16x32_bf16 v[28:31], v[64:67], v[196:199], v[28:31]
	v_mfma_f32_16x16x32_bf16 v[24:27], v[76:79], v[196:199], v[24:27]
	v_mfma_f32_16x16x32_bf16 v[12:15], v[64:67], v[212:215], v[12:15]
	v_mfma_f32_16x16x32_bf16 v[8:11], v[76:79], v[212:215], v[8:11]
	s_setprio 0
	s_setprio 1
	v_mfma_f32_16x16x32_bf16 v[52:55], v[144:147], v[160:163], v[52:55]
	v_mfma_f32_16x16x32_bf16 v[48:51], v[152:155], v[160:163], v[48:51]
	v_mfma_f32_16x16x32_bf16 v[36:39], v[144:147], v[168:171], v[36:39]
	v_mfma_f32_16x16x32_bf16 v[32:35], v[152:155], v[168:171], v[32:35]
	v_mfma_f32_16x16x32_bf16 v[20:23], v[144:147], v[192:195], v[20:23]
	v_mfma_f32_16x16x32_bf16 v[16:19], v[152:155], v[192:195], v[16:19]
	v_mfma_f32_16x16x32_bf16 v[4:7], v[144:147], v[208:211], v[4:7]
	v_mfma_f32_16x16x32_bf16 v[0:3], v[152:155], v[208:211], v[0:3]
	v_mfma_f32_16x16x32_bf16 v[52:55], v[148:151], v[164:167], v[52:55]
	v_mfma_f32_16x16x32_bf16 v[48:51], v[156:159], v[164:167], v[48:51]
	v_mfma_f32_16x16x32_bf16 v[36:39], v[148:151], v[188:191], v[36:39]
	v_mfma_f32_16x16x32_bf16 v[32:35], v[156:159], v[188:191], v[32:35]
	v_mfma_f32_16x16x32_bf16 v[20:23], v[148:151], v[196:199], v[20:23]
	v_mfma_f32_16x16x32_bf16 v[16:19], v[156:159], v[196:199], v[16:19]
	v_mfma_f32_16x16x32_bf16 v[4:7], v[148:151], v[212:215], v[4:7]
	v_mfma_f32_16x16x32_bf16 v[0:3], v[156:159], v[212:215], v[0:3]
	s_setprio 0
	s_barrier
; #define PG8_STAGE(bufoff, gbase, voff) do { _Pragma("unroll") for (int _i = 0; _i < 2; ++_i) \
;         __builtin_amdgcn_global_load_lds((const unsigned*)((const char*)(gbase) + (voff)[_i]), (PG8_LAS unsigned*)(lds + (bufoff) + ldsw + _i * 8192), 16, 0, 0); } while (0)
; #define PG8_LDA(dst, b, h) do { _Pragma("unroll") for (int m = 0; m < 4; ++m) _Pragma("unroll") for (int k = 0; k < 2; ++k) dst[m][k] = *(const PG8_LAS bf16x8*)(lds + PG8_SA(b, h) + aoff + m * 2048 + k * 1024); } while (0)
; #define PG8_LDB(dst, b, h) do { _Pragma("unroll") for (int n = 0; n < 2; ++n) _Pragma("unroll") for (int k = 0; k < 2; ++k) dst[n][k] = *(const PG8_LAS bf16x8*)(lds + PG8_SB(b, h) + boff + n * 2048 + k * 1024); } while (0)
; #define PG8_MMA(ai, bj, At, Bt) do { __builtin_amdgcn_s_setprio(1); _Pragma("unroll") for (int m = 0; m < 4; ++m) _Pragma("unroll") for (int n = 0; n < 2; ++n) _Pragma("unroll") for (int k = 0; k < 2; ++k) \
;         acc[ai][bj][m][n] = __builtin_amdgcn_mfma_f32_16x16x32_bf16(Bt[n][k], At[m][k], acc[ai][bj][m][n], 0, 0, 0); __builtin_amdgcn_s_setprio(0); } while (0)
; #define PG8_WAIT_V(n) asm volatile("s_waitcnt vmcnt(" #n ")" ::: "memory")
; #define PG8_WAIT_L(n) asm volatile("s_waitcnt lgkmcnt(" #n ")" ::: "memory")
; #define PG8_BAR __builtin_amdgcn_s_barrier()
; #define PG8_SCHED __builtin_amdgcn_sched_barrier(0)
; template <class Epi, class Sched, bool ALIGN_EPI = false, bool SP2 = false>
; __device__ __forceinline__ void gemm_phase(PG8_LAS unsigned char* lds, const Gemm g, const Sched& S, const Epi& E) {
;     ...
;         for (int t = 0; t < nt; t += 2) {
;     ...
;             PG8_LDB(B0, 1, 0); PG8_LDB(B1, 1, 1); PG8_SCHED; PG8_LDA(At, 1, 0); PG8_STAGE(PG8_SA(0, 1), a2 + hstep, voffA);
;             PG8_WAIT_V(8); PG8_WAIT_L(0); PG8_BAR; PG8_MMA(0, 0, At, B0); PG8_MMA(0, 1, At, B1); PG8_BAR; PG8_SCHED;
;             PG8_LDA(At, 1, 1); PG8_STAGE(PG8_SB(1, 0), b3, voffB); PG8_STAGE(PG8_SB(1, 1), b3 + hstep, voffB); PG8_STAGE(PG8_SA(1, 0), a3, voffA);
;             PG8_WAIT_V(8); PG8_WAIT_L(0); PG8_BAR; PG8_MMA(1, 0, At, B0); PG8_MMA(1, 1, At, B1); PG8_BAR; PG8_SCHED;
	s_add_i32 s57, 0, 0x18000
	s_add_i32 s58, 0, 0x1c000
	v_add_u32_e32 v76, s57, v201
	v_add_u32_e32 v156, s58, v201
	ds_read_b128 v[56:59], v76
	ds_read_b128 v[64:67], v76 offset:1024
	ds_read_b128 v[72:75], v76 offset:2048
	ds_read_b128 v[76:79], v76 offset:3072
	ds_read_b128 v[144:147], v156
	ds_read_b128 v[148:151], v156 offset:1024
	ds_read_b128 v[152:155], v156 offset:2048
	ds_read_b128 v[156:159], v156 offset:3072
	s_add_u32 s38, s38, 0x80000
	s_addc_u32 s39, s39, 0
	s_mov_b32 m0, s43
	ds_read_b128 v[160:163], v205 offset:32768
	ds_read_b128 v[164:167], v205 offset:33792
	ds_read_b128 v[168:171], v205 offset:34816
	ds_read_b128 v[188:191], v205 offset:35840
	ds_read_b128 v[192:195], v205 offset:36864
	ds_read_b128 v[196:199], v205 offset:37888
	ds_read_b128 v[208:211], v205 offset:38912
	global_load_lds_dwordx4 v172, s[38:39]
	s_mov_b32 m0, s44
	ds_read_b128 v[212:215], v205 offset:39936
	global_load_lds_dwordx4 v176, s[38:39]
	s_waitcnt vmcnt(8)
	s_waitcnt lgkmcnt(0)
	s_barrier
	s_setprio 1
	s_waitcnt lgkmcnt(0)
	v_mfma_f32_16x16x32_bf16 v[140:143], v[56:59], v[160:163], v[140:143]
	v_mfma_f32_16x16x32_bf16 v[136:139], v[72:75], v[160:163], v[136:139]
	v_mfma_f32_16x16x32_bf16 v[124:127], v[56:59], v[168:171], v[124:127]
	v_mfma_f32_16x16x32_bf16 v[120:123], v[72:75], v[168:171], v[120:123]
	v_mfma_f32_16x16x32_bf16 v[108:111], v[56:59], v[192:195], v[108:111]
	v_mfma_f32_16x16x32_bf16 v[104:107], v[72:75], v[192:195], v[104:107]
	v_mfma_f32_16x16x32_bf16 v[92:95], v[56:59], v[208:211], v[92:95]
	v_mfma_f32_16x16x32_bf16 v[88:91], v[72:75], v[208:211], v[88:91]
	v_mfma_f32_16x16x32_bf16 v[140:143], v[64:67], v[164:167], v[140:143]
	v_mfma_f32_16x16x32_bf16 v[136:139], v[76:79], v[164:167], v[136:139]
	v_mfma_f32_16x16x32_bf16 v[124:127], v[64:67], v[188:191], v[124:127]
	v_mfma_f32_16x16x32_bf16 v[120:123], v[76:79], v[188:191], v[120:123]
	v_mfma_f32_16x16x32_bf16 v[108:111], v[64:67], v[196:199], v[108:111]
	v_mfma_f32_16x16x32_bf16 v[104:107], v[76:79], v[196:199], v[104:107]
	v_mfma_f32_16x16x32_bf16 v[92:95], v[64:67], v[212:215], v[92:95]
	v_mfma_f32_16x16x32_bf16 v[88:91], v[76:79], v[212:215], v[88:91]
	s_setprio 0
	s_setprio 1
	v_mfma_f32_16x16x32_bf16 v[132:135], v[144:147], v[160:163], v[132:135]
	v_mfma_f32_16x16x32_bf16 v[128:131], v[152:155], v[160:163], v[128:131]
	v_mfma_f32_16x16x32_bf16 v[116:119], v[144:147], v[168:171], v[116:119]
	v_mfma_f32_16x16x32_bf16 v[112:115], v[152:155], v[168:171], v[112:115]
	v_mfma_f32_16x16x32_bf16 v[100:103], v[144:147], v[192:195], v[100:103]
	v_mfma_f32_16x16x32_bf16 v[96:99], v[152:155], v[192:195], v[96:99]
	v_mfma_f32_16x16x32_bf16 v[84:87], v[144:147], v[208:211], v[84:87]
	v_mfma_f32_16x16x32_bf16 v[80:83], v[152:155], v[208:211], v[80:83]
	v_mfma_f32_16x16x32_bf16 v[132:135], v[148:151], v[164:167], v[132:135]
	v_mfma_f32_16x16x32_bf16 v[128:131], v[156:159], v[164:167], v[128:131]
	v_mfma_f32_16x16x32_bf16 v[116:119], v[148:151], v[188:191], v[116:119]
	v_mfma_f32_16x16x32_bf16 v[112:115], v[156:159], v[188:191], v[112:115]
	v_mfma_f32_16x16x32_bf16 v[100:103], v[148:151], v[196:199], v[100:103]
	v_mfma_f32_16x16x32_bf16 v[96:99], v[156:159], v[196:199], v[96:99]
	v_mfma_f32_16x16x32_bf16 v[84:87], v[148:151], v[212:215], v[84:87]
	v_mfma_f32_16x16x32_bf16 v[80:83], v[156:159], v[212:215], v[80:83]
	s_setprio 0
	s_barrier
	s_add_i32 s38, s57, s40
	s_mov_b32 m0, s38
	ds_read_b128 v[160:163], v205 offset:49152
	ds_read_b128 v[164:167], v205 offset:50176
	ds_read_b128 v[168:171], v205 offset:51200
	ds_read_b128 v[188:191], v205 offset:52224
	global_load_lds_dwordx4 v174, vcc
	s_add_i32 m0, s38, 0x2000
	s_add_u32 s36, s36, 0x80080
	s_addc_u32 s37, s37, 0
	s_add_i32 s38, s58, s40
	global_load_lds_dwordx4 v178, vcc
	s_mov_b32 m0, s38
	ds_read_b128 v[212:215], v205 offset:56320
	global_load_lds_dwordx4 v174, s[36:37]
	s_add_i32 m0, s38, 0x2000
	ds_read_b128 v[208:211], v205 offset:55296
	global_load_lds_dwordx4 v178, s[36:37]
	s_mov_b32 m0, s46
	ds_read_b128 v[196:199], v205 offset:54272
	global_load_lds_dwordx4 v172, s[98:99]
	s_mov_b32 m0, s47
	ds_read_b128 v[192:195], v205 offset:53248
	global_load_lds_dwordx4 v176, s[98:99]
	s_waitcnt vmcnt(8)
	s_waitcnt lgkmcnt(0)
	s_barrier
	s_setprio 1
	s_waitcnt lgkmcnt(0)
	v_mfma_f32_16x16x32_bf16 v[68:71], v[56:59], v[160:163], v[68:71]
	v_mfma_f32_16x16x32_bf16 v[60:63], v[72:75], v[160:163], v[60:63]
	v_mfma_f32_16x16x32_bf16 v[44:47], v[56:59], v[168:171], v[44:47]
	v_mfma_f32_16x16x32_bf16 v[40:43], v[72:75], v[168:171], v[40:43]
	v_mfma_f32_16x16x32_bf16 v[28:31], v[56:59], v[192:195], v[28:31]
	v_mfma_f32_16x16x32_bf16 v[24:27], v[72:75], v[192:195], v[24:27]
	v_mfma_f32_16x16x32_bf16 v[12:15], v[56:59], v[208:211], v[12:15]
	v_mfma_f32_16x16x32_bf16 v[8:11], v[72:75], v[208:211], v[8:11]
	v_mfma_f32_16x16x32_bf16 v[68:71], v[64:67], v[164:167], v[68:71]
	v_mfma_f32_16x16x32_bf16 v[60:63], v[76:79], v[164:167], v[60:63]
	v_mfma_f32_16x16x32_bf16 v[44:47], v[64:67], v[188:191], v[44:47]
	v_mfma_f32_16x16x32_bf16 v[40:43], v[76:79], v[188:191], v[40:43]
	v_mfma_f32_16x16x32_bf16 v[28:31], v[64:67], v[196:199], v[28:31]
	v_mfma_f32_16x16x32_bf16 v[24:27], v[76:79], v[196:199], v[24:27]
	v_mfma_f32_16x16x32_bf16 v[12:15], v[64:67], v[212:215], v[12:15]
	v_mfma_f32_16x16x32_bf16 v[8:11], v[76:79], v[212:215], v[8:11]
	s_setprio 0
	s_setprio 1
	v_mfma_f32_16x16x32_bf16 v[52:55], v[144:147], v[160:163], v[52:55]
	v_mfma_f32_16x16x32_bf16 v[48:51], v[152:155], v[160:163], v[48:51]
	v_mfma_f32_16x16x32_bf16 v[36:39], v[144:147], v[168:171], v[36:39]
	v_mfma_f32_16x16x32_bf16 v[32:35], v[152:155], v[168:171], v[32:35]
	v_mfma_f32_16x16x32_bf16 v[20:23], v[144:147], v[192:195], v[20:23]
	v_mfma_f32_16x16x32_bf16 v[16:19], v[152:155], v[192:195], v[16:19]
	v_mfma_f32_16x16x32_bf16 v[4:7], v[144:147], v[208:211], v[4:7]
	v_mfma_f32_16x16x32_bf16 v[0:3], v[152:155], v[208:211], v[0:3]
	v_mfma_f32_16x16x32_bf16 v[52:55], v[148:151], v[164:167], v[52:55]
	v_mfma_f32_16x16x32_bf16 v[48:51], v[156:159], v[164:167], v[48:51]
	v_mfma_f32_16x16x32_bf16 v[36:39], v[148:151], v[188:191], v[36:39]
	v_mfma_f32_16x16x32_bf16 v[32:35], v[156:159], v[188:191], v[32:35]
	v_mfma_f32_16x16x32_bf16 v[20:23], v[148:151], v[196:199], v[20:23]
	v_mfma_f32_16x16x32_bf16 v[16:19], v[156:159], v[196:199], v[16:19]
	v_mfma_f32_16x16x32_bf16 v[4:7], v[148:151], v[212:215], v[4:7]
	v_mfma_f32_16x16x32_bf16 v[0:3], v[156:159], v[212:215], v[0:3]
	s_setprio 0
	s_barrier
	s_add_i32 s56, s56, 2
	s_add_u32 s34, s34, 0x100
	s_addc_u32 s35, s35, 0
	s_add_u32 s54, s54, 0x100
	s_addc_u32 s55, s55, 0
	s_cmp_gt_u32 s56, 29
	s_cbranch_scc0 .LBB0_1295
	s_and_b64 vcc, exec, s[16:17]
	s_cbranch_vccz .LBB0_1298
	s_barrier
